# MFMA operand-reuse order: within each 8-MFMA k-pass consecutive MFMAs share one operand (snake order); power/clock hypothesis
# speedup vs baseline: 1.0020x; 1.0020x over previous
; #define PG8_STAGE(bufoff, gbase, voff) do { _Pragma("unroll") for (int _i = 0; _i < 2; ++_i) \
;         __builtin_amdgcn_global_load_lds((const unsigned*)((const char*)(gbase) + (voff)[_i]), (PG8_LAS unsigned*)(lds + (bufoff) + ldsw + _i * 8192), 16, 0, 0); } while (0)
; #define PG8_LDA(dst, b, h) do { _Pragma("unroll") for (int m = 0; m < 4; ++m) _Pragma("unroll") for (int k = 0; k < 2; ++k) dst[m][k] = *(const PG8_LAS bf16x8*)(lds + PG8_SA(b, h) + aoff + m * 2048 + k * 1024); } while (0)
; #define PG8_LDB(dst, b, h) do { _Pragma("unroll") for (int n = 0; n < 2; ++n) _Pragma("unroll") for (int k = 0; k < 2; ++k) dst[n][k] = *(const PG8_LAS bf16x8*)(lds + PG8_SB(b, h) + boff + n * 2048 + k * 1024); } while (0)
; #define PG8_MMA(ai, bj, At, Bt) do { __builtin_amdgcn_s_setprio(1); _Pragma("unroll") for (int m = 0; m < 4; ++m) _Pragma("unroll") for (int n = 0; n < 2; ++n) _Pragma("unroll") for (int k = 0; k < 2; ++k) \
;         acc[ai][bj][m][n] = __builtin_amdgcn_mfma_f32_16x16x32_bf16(Bt[n][k], At[m][k], acc[ai][bj][m][n], 0, 0, 0); __builtin_amdgcn_s_setprio(0); } while (0)
; #define PG8_WAIT_V(n) asm volatile("s_waitcnt vmcnt(" #n ")" ::: "memory")
; #define PG8_WAIT_L(n) asm volatile("s_waitcnt lgkmcnt(" #n ")" ::: "memory")
; #define PG8_BAR __builtin_amdgcn_s_barrier()
; #define PG8_SCHED __builtin_amdgcn_sched_barrier(0)
; template <class Epi, class Sched, bool ALIGN_EPI = false, bool SP2 = false>
; __device__ __forceinline__ void gemm_phase(PG8_LAS unsigned char* lds, const Gemm g, const Sched& S, const Epi& E) {
;     ...
;             PG8_LDB(B0, 0, 0); PG8_LDB(B1, 0, 1); PG8_SCHED; PG8_LDA(At, 0, 0); PG8_STAGE(PG8_SA(1, 1), a1 + hstep, voffA);
;             PG8_WAIT_V(8); PG8_WAIT_L(0); PG8_BAR; PG8_MMA(0, 0, At, B0); PG8_MMA(0, 1, At, B1); PG8_BAR; PG8_SCHED;
;             PG8_LDA(At, 0, 1); PG8_STAGE(PG8_SB(0, 0), b2, voffB); PG8_STAGE(PG8_SB(0, 1), b2 + hstep, voffB); PG8_STAGE(PG8_SA(0, 0), a2, voffA);
.LBB0_168:
	s_add_i32 s18, s6, 2
	s_add_u32 s19, s0, 0x80
	s_addc_u32 s7, s1, 0
	s_add_i32 s28, 0, 0x10000
	s_cmp_eq_u32 s79, s6
	s_cselect_b32 s7, s67, s7
	s_cselect_b32 s6, s66, s19
	s_cselect_b32 s25, s27, s9
	s_cselect_b32 s24, s26, s8
	s_add_i32 s19, 0, 0x14000
	v_add_u32_e32 v154, s28, v197
	v_add_u32_e32 v170, s19, v197
	ds_read_b128 v[142:145], v154
	ds_read_b128 v[146:149], v154 offset:1024
	ds_read_b128 v[150:153], v154 offset:2048
	ds_read_b128 v[154:157], v154 offset:3072
	ds_read_b128 v[158:161], v170
	ds_read_b128 v[162:165], v170 offset:1024
	ds_read_b128 v[166:169], v170 offset:2048
	ds_read_b128 v[170:173], v170 offset:3072
	v_lshl_add_u64 v[174:175], s[0:1], 0, v[136:137]
	s_add_i32 m0, s42, 0xc000
	ds_read_b128 v[186:189], v198
	ds_read_b128 v[190:193], v198 offset:1024
	ds_read_b128 v[200:203], v198 offset:2048
	ds_read_b128 v[204:207], v198 offset:3072
	ds_read_b128 v[208:211], v198 offset:4096
	ds_read_b128 v[212:215], v198 offset:5120
	ds_read_b128 v[216:219], v198 offset:6144
	ds_read_b128 v[220:223], v198 offset:7168
	global_load_lds_dwordx4 v[174:175], off
	v_lshl_add_u64 v[174:175], s[0:1], 0, v[138:139]
	s_add_i32 m0, s42, 0xe000
	s_nop 0
	global_load_lds_dwordx4 v[174:175], off
	s_waitcnt vmcnt(8)
	s_waitcnt lgkmcnt(0)
	s_barrier
	s_setprio 1
	s_waitcnt lgkmcnt(0)
	v_mfma_f32_16x16x32_bf16 v[120:123], v[142:145], v[186:189], v[120:123]
	v_mfma_f32_16x16x32_bf16 v[124:127], v[150:153], v[186:189], v[124:127]
	v_mfma_f32_16x16x32_bf16 v[116:119], v[150:153], v[200:203], v[116:119]
	v_mfma_f32_16x16x32_bf16 v[112:115], v[142:145], v[200:203], v[112:115]
	v_mfma_f32_16x16x32_bf16 v[104:107], v[142:145], v[208:211], v[104:107]
	v_mfma_f32_16x16x32_bf16 v[108:111], v[150:153], v[208:211], v[108:111]
	v_mfma_f32_16x16x32_bf16 v[100:103], v[150:153], v[216:219], v[100:103]
	v_mfma_f32_16x16x32_bf16 v[96:99], v[142:145], v[216:219], v[96:99]
	v_mfma_f32_16x16x32_bf16 v[120:123], v[146:149], v[190:193], v[120:123]
	v_mfma_f32_16x16x32_bf16 v[124:127], v[154:157], v[190:193], v[124:127]
	v_mfma_f32_16x16x32_bf16 v[116:119], v[154:157], v[204:207], v[116:119]
	v_mfma_f32_16x16x32_bf16 v[112:115], v[146:149], v[204:207], v[112:115]
	v_mfma_f32_16x16x32_bf16 v[104:107], v[146:149], v[212:215], v[104:107]
	v_mfma_f32_16x16x32_bf16 v[108:111], v[154:157], v[212:215], v[108:111]
	v_mfma_f32_16x16x32_bf16 v[100:103], v[154:157], v[220:223], v[100:103]
	v_mfma_f32_16x16x32_bf16 v[96:99], v[146:149], v[220:223], v[96:99]
	s_setprio 0
	s_setprio 1
	v_mfma_f32_16x16x32_bf16 v[60:63], v[158:161], v[186:189], v[60:63]
	v_mfma_f32_16x16x32_bf16 v[56:59], v[166:169], v[186:189], v[56:59]
	v_mfma_f32_16x16x32_bf16 v[48:51], v[166:169], v[200:203], v[48:51]
	v_mfma_f32_16x16x32_bf16 v[52:55], v[158:161], v[200:203], v[52:55]
	v_mfma_f32_16x16x32_bf16 v[44:47], v[158:161], v[208:211], v[44:47]
	v_mfma_f32_16x16x32_bf16 v[40:43], v[166:169], v[208:211], v[40:43]
	v_mfma_f32_16x16x32_bf16 v[32:35], v[166:169], v[216:219], v[32:35]
	v_mfma_f32_16x16x32_bf16 v[36:39], v[158:161], v[216:219], v[36:39]
	v_mfma_f32_16x16x32_bf16 v[60:63], v[162:165], v[190:193], v[60:63]
	v_mfma_f32_16x16x32_bf16 v[56:59], v[170:173], v[190:193], v[56:59]
	v_mfma_f32_16x16x32_bf16 v[48:51], v[170:173], v[204:207], v[48:51]
	v_mfma_f32_16x16x32_bf16 v[52:55], v[162:165], v[204:207], v[52:55]
	v_mfma_f32_16x16x32_bf16 v[44:47], v[162:165], v[212:215], v[44:47]
	v_mfma_f32_16x16x32_bf16 v[40:43], v[170:173], v[212:215], v[40:43]
	v_mfma_f32_16x16x32_bf16 v[32:35], v[170:173], v[220:223], v[32:35]
	v_mfma_f32_16x16x32_bf16 v[36:39], v[162:165], v[220:223], v[36:39]
	s_setprio 0
	s_barrier
	s_add_i32 s28, s28, s31
	v_lshl_add_u64 v[174:175], s[24:25], 0, v[130:131]
	s_mov_b32 m0, s28
	ds_read_b128 v[186:189], v198 offset:16384
	ds_read_b128 v[190:193], v198 offset:17408
	ds_read_b128 v[200:203], v198 offset:18432
	ds_read_b128 v[204:207], v198 offset:19456
	ds_read_b128 v[208:211], v198 offset:20480
	ds_read_b128 v[212:215], v198 offset:21504
	ds_read_b128 v[216:219], v198 offset:22528
	ds_read_b128 v[220:223], v198 offset:23552
	global_load_lds_dwordx4 v[174:175], off
	s_add_i32 m0, s28, 0x2000
	v_lshl_add_u64 v[182:183], s[24:25], 0, v[134:135]
	s_add_u32 s24, s24, s14
	s_addc_u32 s25, s25, s15
	s_add_i32 s19, s19, s31
	global_load_lds_dwordx4 v[182:183], off
	v_lshl_add_u64 v[184:185], s[24:25], 0, v[130:131]
	s_mov_b32 m0, s19
	v_lshl_add_u64 v[194:195], s[24:25], 0, v[134:135]
	global_load_lds_dwordx4 v[184:185], off
	s_add_i32 m0, s19, 0x2000
	v_lshl_add_u64 v[224:225], s[6:7], 0, v[128:129]
	global_load_lds_dwordx4 v[194:195], off
	s_mov_b32 m0, s42
	v_lshl_add_u64 v[226:227], s[6:7], 0, v[132:133]
	global_load_lds_dwordx4 v[224:225], off
	s_mov_b32 m0, s43
	s_nop 0
	global_load_lds_dwordx4 v[226:227], off
	s_waitcnt vmcnt(8)
	s_waitcnt lgkmcnt(0)
	s_barrier
; #define PG8_STAGE(bufoff, gbase, voff) do { _Pragma("unroll") for (int _i = 0; _i < 2; ++_i) \
;         __builtin_amdgcn_global_load_lds((const unsigned*)((const char*)(gbase) + (voff)[_i]), (PG8_LAS unsigned*)(lds + (bufoff) + ldsw + _i * 8192), 16, 0, 0); } while (0)
; #define PG8_LDA(dst, b, h) do { _Pragma("unroll") for (int m = 0; m < 4; ++m) _Pragma("unroll") for (int k = 0; k < 2; ++k) dst[m][k] = *(const PG8_LAS bf16x8*)(lds + PG8_SA(b, h) + aoff + m * 2048 + k * 1024); } while (0)
; #define PG8_LDB(dst, b, h) do { _Pragma("unroll") for (int n = 0; n < 2; ++n) _Pragma("unroll") for (int k = 0; k < 2; ++k) dst[n][k] = *(const PG8_LAS bf16x8*)(lds + PG8_SB(b, h) + boff + n * 2048 + k * 1024); } while (0)
; #define PG8_MMA(ai, bj, At, Bt) do { __builtin_amdgcn_s_setprio(1); _Pragma("unroll") for (int m = 0; m < 4; ++m) _Pragma("unroll") for (int n = 0; n < 2; ++n) _Pragma("unroll") for (int k = 0; k < 2; ++k) \
;         acc[ai][bj][m][n] = __builtin_amdgcn_mfma_f32_16x16x32_bf16(Bt[n][k], At[m][k], acc[ai][bj][m][n], 0, 0, 0); __builtin_amdgcn_s_setprio(0); } while (0)
; #define PG8_WAIT_V(n) asm volatile("s_waitcnt vmcnt(" #n ")" ::: "memory")
; #define PG8_WAIT_L(n) asm volatile("s_waitcnt lgkmcnt(" #n ")" ::: "memory")
; #define PG8_BAR __builtin_amdgcn_s_barrier()
; #define PG8_SCHED __builtin_amdgcn_sched_barrier(0)
; template <class Epi, class Sched, bool ALIGN_EPI = false, bool SP2 = false>
; __device__ __forceinline__ void gemm_phase(PG8_LAS unsigned char* lds, const Gemm g, const Sched& S, const Epi& E) {
;     ...
;             PG8_WAIT_V(8); PG8_WAIT_L(0); PG8_BAR; PG8_MMA(1, 0, At, B0); PG8_MMA(1, 1, At, B1); PG8_BAR; PG8_SCHED;
;             PG8_LDB(B0, 1, 0); PG8_LDB(B1, 1, 1); PG8_SCHED; PG8_LDA(At, 1, 0); PG8_STAGE(PG8_SA(0, 1), a2 + hstep, voffA);
;             PG8_WAIT_V(8); PG8_WAIT_L(0); PG8_BAR; PG8_MMA(0, 0, At, B0); PG8_MMA(0, 1, At, B1); PG8_BAR; PG8_SCHED;
	s_setprio 1
	s_waitcnt lgkmcnt(0)
	v_mfma_f32_16x16x32_bf16 v[88:91], v[142:145], v[186:189], v[88:91]
	v_mfma_f32_16x16x32_bf16 v[92:95], v[150:153], v[186:189], v[92:95]
	v_mfma_f32_16x16x32_bf16 v[84:87], v[150:153], v[200:203], v[84:87]
	v_mfma_f32_16x16x32_bf16 v[80:83], v[142:145], v[200:203], v[80:83]
	v_mfma_f32_16x16x32_bf16 v[72:75], v[142:145], v[208:211], v[72:75]
	v_mfma_f32_16x16x32_bf16 v[76:79], v[150:153], v[208:211], v[76:79]
	v_mfma_f32_16x16x32_bf16 v[68:71], v[150:153], v[216:219], v[68:71]
	v_mfma_f32_16x16x32_bf16 v[64:67], v[142:145], v[216:219], v[64:67]
	v_mfma_f32_16x16x32_bf16 v[88:91], v[146:149], v[190:193], v[88:91]
	v_mfma_f32_16x16x32_bf16 v[92:95], v[154:157], v[190:193], v[92:95]
	v_mfma_f32_16x16x32_bf16 v[84:87], v[154:157], v[204:207], v[84:87]
	v_mfma_f32_16x16x32_bf16 v[80:83], v[146:149], v[204:207], v[80:83]
	v_mfma_f32_16x16x32_bf16 v[72:75], v[146:149], v[212:215], v[72:75]
	v_mfma_f32_16x16x32_bf16 v[76:79], v[154:157], v[212:215], v[76:79]
	v_mfma_f32_16x16x32_bf16 v[68:71], v[154:157], v[220:223], v[68:71]
	v_mfma_f32_16x16x32_bf16 v[64:67], v[146:149], v[220:223], v[64:67]
	s_setprio 0
	s_setprio 1
	v_mfma_f32_16x16x32_bf16 v[28:31], v[158:161], v[186:189], v[28:31]
	v_mfma_f32_16x16x32_bf16 v[24:27], v[166:169], v[186:189], v[24:27]
	v_mfma_f32_16x16x32_bf16 v[16:19], v[166:169], v[200:203], v[16:19]
	v_mfma_f32_16x16x32_bf16 v[20:23], v[158:161], v[200:203], v[20:23]
	v_mfma_f32_16x16x32_bf16 v[12:15], v[158:161], v[208:211], v[12:15]
	v_mfma_f32_16x16x32_bf16 v[8:11], v[166:169], v[208:211], v[8:11]
	v_mfma_f32_16x16x32_bf16 v[0:3], v[166:169], v[216:219], v[0:3]
	v_mfma_f32_16x16x32_bf16 v[4:7], v[158:161], v[216:219], v[4:7]
	v_mfma_f32_16x16x32_bf16 v[28:31], v[162:165], v[190:193], v[28:31]
	v_mfma_f32_16x16x32_bf16 v[24:27], v[170:173], v[190:193], v[24:27]
	v_mfma_f32_16x16x32_bf16 v[16:19], v[170:173], v[204:207], v[16:19]
	v_mfma_f32_16x16x32_bf16 v[20:23], v[162:165], v[204:207], v[20:23]
	v_mfma_f32_16x16x32_bf16 v[12:15], v[162:165], v[212:215], v[12:15]
	v_mfma_f32_16x16x32_bf16 v[8:11], v[170:173], v[212:215], v[8:11]
	v_mfma_f32_16x16x32_bf16 v[0:3], v[170:173], v[220:223], v[0:3]
	v_mfma_f32_16x16x32_bf16 v[4:7], v[162:165], v[220:223], v[4:7]
	s_setprio 0
	s_barrier
	s_add_i32 s19, 0, 0x18000
	s_add_i32 s24, 0, 0x1c000
	v_add_u32_e32 v154, s19, v197
	v_add_u32_e32 v170, s24, v197
	ds_read_b128 v[142:145], v154
	ds_read_b128 v[146:149], v154 offset:1024
	ds_read_b128 v[150:153], v154 offset:2048
	ds_read_b128 v[154:157], v154 offset:3072
	ds_read_b128 v[158:161], v170
	ds_read_b128 v[162:165], v170 offset:1024
	ds_read_b128 v[166:169], v170 offset:2048
	ds_read_b128 v[170:173], v170 offset:3072
	s_add_u32 s6, s6, s14
	s_addc_u32 s7, s7, s15
	s_mov_b32 m0, s72
	v_lshl_add_u64 v[236:237], s[6:7], 0, v[128:129]
	ds_read_b128 v[186:189], v198 offset:32768
	ds_read_b128 v[190:193], v198 offset:33792
	ds_read_b128 v[200:203], v198 offset:34816
	ds_read_b128 v[204:207], v198 offset:35840
	ds_read_b128 v[208:211], v198 offset:36864
	ds_read_b128 v[212:215], v198 offset:37888
	ds_read_b128 v[216:219], v198 offset:38912
	ds_read_b128 v[220:223], v198 offset:39936
	global_load_lds_dwordx4 v[236:237], off
	v_lshl_add_u64 v[236:237], s[6:7], 0, v[132:133]
	s_mov_b32 m0, s73
	s_nop 0
	global_load_lds_dwordx4 v[236:237], off
	s_waitcnt vmcnt(8)
	s_waitcnt lgkmcnt(0)
	s_barrier
	s_setprio 1
	s_waitcnt lgkmcnt(0)
	v_mfma_f32_16x16x32_bf16 v[120:123], v[142:145], v[186:189], v[120:123]
	v_mfma_f32_16x16x32_bf16 v[124:127], v[150:153], v[186:189], v[124:127]
	v_mfma_f32_16x16x32_bf16 v[116:119], v[150:153], v[200:203], v[116:119]
	v_mfma_f32_16x16x32_bf16 v[112:115], v[142:145], v[200:203], v[112:115]
	v_mfma_f32_16x16x32_bf16 v[104:107], v[142:145], v[208:211], v[104:107]
	v_mfma_f32_16x16x32_bf16 v[108:111], v[150:153], v[208:211], v[108:111]
	v_mfma_f32_16x16x32_bf16 v[100:103], v[150:153], v[216:219], v[100:103]
	v_mfma_f32_16x16x32_bf16 v[96:99], v[142:145], v[216:219], v[96:99]
	v_mfma_f32_16x16x32_bf16 v[120:123], v[146:149], v[190:193], v[120:123]
	v_mfma_f32_16x16x32_bf16 v[124:127], v[154:157], v[190:193], v[124:127]
	v_mfma_f32_16x16x32_bf16 v[116:119], v[154:157], v[204:207], v[116:119]
	v_mfma_f32_16x16x32_bf16 v[112:115], v[146:149], v[204:207], v[112:115]
	v_mfma_f32_16x16x32_bf16 v[104:107], v[146:149], v[212:215], v[104:107]
	v_mfma_f32_16x16x32_bf16 v[108:111], v[154:157], v[212:215], v[108:111]
	v_mfma_f32_16x16x32_bf16 v[100:103], v[154:157], v[220:223], v[100:103]
	v_mfma_f32_16x16x32_bf16 v[96:99], v[146:149], v[220:223], v[96:99]
	s_setprio 0
	s_setprio 1
	v_mfma_f32_16x16x32_bf16 v[60:63], v[158:161], v[186:189], v[60:63]
	v_mfma_f32_16x16x32_bf16 v[56:59], v[166:169], v[186:189], v[56:59]
	v_mfma_f32_16x16x32_bf16 v[48:51], v[166:169], v[200:203], v[48:51]
	v_mfma_f32_16x16x32_bf16 v[52:55], v[158:161], v[200:203], v[52:55]
	v_mfma_f32_16x16x32_bf16 v[44:47], v[158:161], v[208:211], v[44:47]
	v_mfma_f32_16x16x32_bf16 v[40:43], v[166:169], v[208:211], v[40:43]
	v_mfma_f32_16x16x32_bf16 v[32:35], v[166:169], v[216:219], v[32:35]
	v_mfma_f32_16x16x32_bf16 v[36:39], v[158:161], v[216:219], v[36:39]
	v_mfma_f32_16x16x32_bf16 v[60:63], v[162:165], v[190:193], v[60:63]
	v_mfma_f32_16x16x32_bf16 v[56:59], v[170:173], v[190:193], v[56:59]
	v_mfma_f32_16x16x32_bf16 v[48:51], v[170:173], v[204:207], v[48:51]
	v_mfma_f32_16x16x32_bf16 v[52:55], v[162:165], v[204:207], v[52:55]
	v_mfma_f32_16x16x32_bf16 v[44:47], v[162:165], v[212:215], v[44:47]
	v_mfma_f32_16x16x32_bf16 v[40:43], v[170:173], v[212:215], v[40:43]
	v_mfma_f32_16x16x32_bf16 v[32:35], v[170:173], v[220:223], v[32:35]
	v_mfma_f32_16x16x32_bf16 v[36:39], v[162:165], v[220:223], v[36:39]
	s_setprio 0
	s_barrier
; #define PG8_STAGE(bufoff, gbase, voff) do { _Pragma("unroll") for (int _i = 0; _i < 2; ++_i) \
;         __builtin_amdgcn_global_load_lds((const unsigned*)((const char*)(gbase) + (voff)[_i]), (PG8_LAS unsigned*)(lds + (bufoff) + ldsw + _i * 8192), 16, 0, 0); } while (0)
; #define PG8_LDA(dst, b, h) do { _Pragma("unroll") for (int m = 0; m < 4; ++m) _Pragma("unroll") for (int k = 0; k < 2; ++k) dst[m][k] = *(const PG8_LAS bf16x8*)(lds + PG8_SA(b, h) + aoff + m * 2048 + k * 1024); } while (0)
; #define PG8_MMA(ai, bj, At, Bt) do { __builtin_amdgcn_s_setprio(1); _Pragma("unroll") for (int m = 0; m < 4; ++m) _Pragma("unroll") for (int n = 0; n < 2; ++n) _Pragma("unroll") for (int k = 0; k < 2; ++k) \
;         acc[ai][bj][m][n] = __builtin_amdgcn_mfma_f32_16x16x32_bf16(Bt[n][k], At[m][k], acc[ai][bj][m][n], 0, 0, 0); __builtin_amdgcn_s_setprio(0); } while (0)
; #define PG8_WAIT_V(n) asm volatile("s_waitcnt vmcnt(" #n ")" ::: "memory")
; #define PG8_WAIT_L(n) asm volatile("s_waitcnt lgkmcnt(" #n ")" ::: "memory")
; #define PG8_BAR __builtin_amdgcn_s_barrier()
; #define PG8_SCHED __builtin_amdgcn_sched_barrier(0)
; template <class Epi, class Sched, bool ALIGN_EPI = false, bool SP2 = false>
; __device__ __forceinline__ void gemm_phase(PG8_LAS unsigned char* lds, const Gemm g, const Sched& S, const Epi& E) {
;     ...
;         for (int t = 0; t < nt; t += 2) {
;             const bool last = (t == nt - 2);
;             const char* a1 = cA + (size_t)(t + 1) * kstep;
;             const char* a2 = last ? nA : cA + (size_t)(t + 2) * kstep; const char* b2 = last ? nB : cB + (size_t)(t + 2) * kstep;
;     ...
;             PG8_LDA(At, 1, 1); PG8_STAGE(PG8_SB(1, 0), b3, voffB); PG8_STAGE(PG8_SB(1, 1), b3 + hstep, voffB); PG8_STAGE(PG8_SA(1, 0), a3, voffA);
;             PG8_WAIT_V(8); PG8_WAIT_L(0); PG8_BAR; PG8_MMA(1, 0, At, B0); PG8_MMA(1, 1, At, B1); PG8_BAR; PG8_SCHED;
	s_add_i32 s6, s19, s31
	v_lshl_add_u64 v[174:175], v[174:175], 0, s[44:45]
	s_mov_b32 m0, s6
	ds_read_b128 v[186:189], v198 offset:49152
	ds_read_b128 v[190:193], v198 offset:50176
	ds_read_b128 v[200:203], v198 offset:51200
	ds_read_b128 v[204:207], v198 offset:52224
	ds_read_b128 v[208:211], v198 offset:53248
	ds_read_b128 v[212:215], v198 offset:54272
	ds_read_b128 v[216:219], v198 offset:55296
	ds_read_b128 v[220:223], v198 offset:56320
	global_load_lds_dwordx4 v[174:175], off
	v_lshl_add_u64 v[174:175], v[182:183], 0, s[44:45]
	s_add_i32 m0, s6, 0x2000
	s_add_i32 s6, s24, s31
	global_load_lds_dwordx4 v[174:175], off
	v_lshl_add_u64 v[174:175], v[184:185], 0, s[44:45]
	s_mov_b32 m0, s6
	s_nop 0
	global_load_lds_dwordx4 v[174:175], off
	v_lshl_add_u64 v[174:175], v[194:195], 0, s[44:45]
	s_add_i32 m0, s6, 0x2000
	s_nop 0
	global_load_lds_dwordx4 v[174:175], off
	v_lshl_add_u64 v[174:175], v[224:225], 0, s[44:45]
	s_mov_b32 m0, s74
	s_nop 0
	global_load_lds_dwordx4 v[174:175], off
	v_lshl_add_u64 v[174:175], v[226:227], 0, s[44:45]
	s_mov_b32 m0, s75
	s_nop 0
	global_load_lds_dwordx4 v[174:175], off
	s_waitcnt vmcnt(8)
	s_waitcnt lgkmcnt(0)
	s_barrier
	s_setprio 1
	s_waitcnt lgkmcnt(0)
	v_mfma_f32_16x16x32_bf16 v[88:91], v[142:145], v[186:189], v[88:91]
	v_mfma_f32_16x16x32_bf16 v[92:95], v[150:153], v[186:189], v[92:95]
	v_mfma_f32_16x16x32_bf16 v[84:87], v[150:153], v[200:203], v[84:87]
	v_mfma_f32_16x16x32_bf16 v[80:83], v[142:145], v[200:203], v[80:83]
	v_mfma_f32_16x16x32_bf16 v[72:75], v[142:145], v[208:211], v[72:75]
	v_mfma_f32_16x16x32_bf16 v[76:79], v[150:153], v[208:211], v[76:79]
	v_mfma_f32_16x16x32_bf16 v[68:71], v[150:153], v[216:219], v[68:71]
	v_mfma_f32_16x16x32_bf16 v[64:67], v[142:145], v[216:219], v[64:67]
	v_mfma_f32_16x16x32_bf16 v[88:91], v[146:149], v[190:193], v[88:91]
	v_mfma_f32_16x16x32_bf16 v[92:95], v[154:157], v[190:193], v[92:95]
	v_mfma_f32_16x16x32_bf16 v[84:87], v[154:157], v[204:207], v[84:87]
	v_mfma_f32_16x16x32_bf16 v[80:83], v[146:149], v[204:207], v[80:83]
	v_mfma_f32_16x16x32_bf16 v[72:75], v[146:149], v[212:215], v[72:75]
	v_mfma_f32_16x16x32_bf16 v[76:79], v[154:157], v[212:215], v[76:79]
	v_mfma_f32_16x16x32_bf16 v[68:71], v[154:157], v[220:223], v[68:71]
	v_mfma_f32_16x16x32_bf16 v[64:67], v[146:149], v[220:223], v[64:67]
	s_setprio 0
	s_setprio 1
	v_mfma_f32_16x16x32_bf16 v[28:31], v[158:161], v[186:189], v[28:31]
	v_mfma_f32_16x16x32_bf16 v[24:27], v[166:169], v[186:189], v[24:27]
	v_mfma_f32_16x16x32_bf16 v[20:23], v[158:161], v[200:203], v[20:23]
	v_mfma_f32_16x16x32_bf16 v[16:19], v[166:169], v[200:203], v[16:19]
	v_mfma_f32_16x16x32_bf16 v[12:15], v[158:161], v[208:211], v[12:15]
	v_mfma_f32_16x16x32_bf16 v[8:11], v[166:169], v[208:211], v[8:11]
	v_mfma_f32_16x16x32_bf16 v[4:7], v[158:161], v[216:219], v[4:7]
	v_mfma_f32_16x16x32_bf16 v[0:3], v[166:169], v[216:219], v[0:3]
	v_mfma_f32_16x16x32_bf16 v[28:31], v[162:165], v[190:193], v[28:31]
	v_mfma_f32_16x16x32_bf16 v[24:27], v[170:173], v[190:193], v[24:27]
	s_add_u32 s0, s0, 0x100
	v_mfma_f32_16x16x32_bf16 v[20:23], v[162:165], v[204:207], v[20:23]
	s_addc_u32 s1, s1, 0
	v_mfma_f32_16x16x32_bf16 v[16:19], v[170:173], v[204:207], v[16:19]
	s_add_u32 s8, s8, 0x100
	v_mfma_f32_16x16x32_bf16 v[12:15], v[162:165], v[212:215], v[12:15]
	s_addc_u32 s9, s9, 0
	v_mfma_f32_16x16x32_bf16 v[8:11], v[170:173], v[212:215], v[8:11]
	s_cmp_ge_i32 s18, s76
	v_mfma_f32_16x16x32_bf16 v[4:7], v[162:165], v[220:223], v[4:7]
	s_mov_b32 s6, s18
	v_mfma_f32_16x16x32_bf16 v[0:3], v[170:173], v[220:223], v[0:3]
	s_setprio 0
	s_barrier
	s_cbranch_scc0 .LBB0_168

; #define PG8_STAGE(bufoff, gbase, voff) do { _Pragma("unroll") for (int _i = 0; _i < 2; ++_i) \
;         __builtin_amdgcn_global_load_lds((const unsigned*)((const char*)(gbase) + (voff)[_i]), (PG8_LAS unsigned*)(lds + (bufoff) + ldsw + _i * 8192), 16, 0, 0); } while (0)
; #define PG8_LDA(dst, b, h) do { _Pragma("unroll") for (int m = 0; m < 4; ++m) _Pragma("unroll") for (int k = 0; k < 2; ++k) dst[m][k] = *(const PG8_LAS bf16x8*)(lds + PG8_SA(b, h) + aoff + m * 2048 + k * 1024); } while (0)
; #define PG8_LDB(dst, b, h) do { _Pragma("unroll") for (int n = 0; n < 2; ++n) _Pragma("unroll") for (int k = 0; k < 2; ++k) dst[n][k] = *(const PG8_LAS bf16x8*)(lds + PG8_SB(b, h) + boff + n * 2048 + k * 1024); } while (0)
; #define PG8_MMA(ai, bj, At, Bt) do { __builtin_amdgcn_s_setprio(1); _Pragma("unroll") for (int m = 0; m < 4; ++m) _Pragma("unroll") for (int n = 0; n < 2; ++n) _Pragma("unroll") for (int k = 0; k < 2; ++k) \
;         acc[ai][bj][m][n] = __builtin_amdgcn_mfma_f32_16x16x32_bf16(Bt[n][k], At[m][k], acc[ai][bj][m][n], 0, 0, 0); __builtin_amdgcn_s_setprio(0); } while (0)
; #define PG8_WAIT_V(n) asm volatile("s_waitcnt vmcnt(" #n ")" ::: "memory")
; #define PG8_WAIT_L(n) asm volatile("s_waitcnt lgkmcnt(" #n ")" ::: "memory")
; #define PG8_BAR __builtin_amdgcn_s_barrier()
; #define PG8_SCHED __builtin_amdgcn_sched_barrier(0)
; template <class Epi, class Sched, bool ALIGN_EPI = false, bool SP2 = false>
; __device__ __forceinline__ void gemm_phase(PG8_LAS unsigned char* lds, const Gemm g, const Sched& S, const Epi& E) {
;     ...
;             PG8_LDB(B0, 0, 0); PG8_LDB(B1, 0, 1); PG8_SCHED; PG8_LDA(At, 0, 0); PG8_STAGE(PG8_SA(1, 1), a1 + hstep, voffA);
;             PG8_WAIT_V(8); PG8_WAIT_L(0); PG8_BAR; PG8_MMA(0, 0, At, B0); PG8_MMA(0, 1, At, B1); PG8_BAR; PG8_SCHED;
;             PG8_LDA(At, 0, 1); PG8_STAGE(PG8_SB(0, 0), b2, voffB); PG8_STAGE(PG8_SB(0, 1), b2 + hstep, voffB); PG8_STAGE(PG8_SA(0, 0), a2, voffA);
.LBB0_375:
	s_add_i32 s80, s64, 2
	s_add_u32 s28, s40, 0x80
	s_addc_u32 s38, s41, 0
	s_add_i32 s48, 0, 0x10000
	s_cmp_eq_u32 s74, s64
	s_cselect_b32 s65, s5, s38
	s_cselect_b32 s64, s4, s28
	s_cselect_b32 s39, s37, s79
	s_cselect_b32 s38, s36, s78
	s_add_i32 s28, 0, 0x14000
	v_add_u32_e32 v154, s48, v140
	v_add_u32_e32 v170, s28, v140
	ds_read_b128 v[142:145], v154
	ds_read_b128 v[146:149], v154 offset:1024
	ds_read_b128 v[150:153], v154 offset:2048
	ds_read_b128 v[154:157], v154 offset:3072
	ds_read_b128 v[158:161], v170
	ds_read_b128 v[162:165], v170 offset:1024
	ds_read_b128 v[166:169], v170 offset:2048
	ds_read_b128 v[170:173], v170 offset:3072
	v_lshl_add_u64 v[174:175], s[40:41], 0, v[134:135]
	s_add_i32 m0, s43, 0xc000
	ds_read_b128 v[182:185], v141
	ds_read_b128 v[186:189], v141 offset:1024
	ds_read_b128 v[190:193], v141 offset:2048
	ds_read_b128 v[194:197], v141 offset:3072
	ds_read_b128 v[198:201], v141 offset:4096
	ds_read_b128 v[202:205], v141 offset:5120
	ds_read_b128 v[206:209], v141 offset:6144
	ds_read_b128 v[210:213], v141 offset:7168
	global_load_lds_dwordx4 v[174:175], off
	v_lshl_add_u64 v[174:175], s[40:41], 0, v[136:137]
	s_add_i32 m0, s43, 0xe000
	s_nop 0
	global_load_lds_dwordx4 v[174:175], off
	s_waitcnt vmcnt(8)
	s_waitcnt lgkmcnt(0)
	s_barrier
	s_setprio 1
	s_waitcnt lgkmcnt(0)
	v_mfma_f32_16x16x32_bf16 v[120:123], v[142:145], v[182:185], v[120:123]
	v_mfma_f32_16x16x32_bf16 v[124:127], v[150:153], v[182:185], v[124:127]
	v_mfma_f32_16x16x32_bf16 v[104:107], v[150:153], v[190:193], v[104:107]
	v_mfma_f32_16x16x32_bf16 v[108:111], v[142:145], v[190:193], v[108:111]
	v_mfma_f32_16x16x32_bf16 v[92:95], v[142:145], v[198:201], v[92:95]
	v_mfma_f32_16x16x32_bf16 v[88:91], v[150:153], v[198:201], v[88:91]
	v_mfma_f32_16x16x32_bf16 v[72:75], v[150:153], v[206:209], v[72:75]
	v_mfma_f32_16x16x32_bf16 v[76:79], v[142:145], v[206:209], v[76:79]
	v_mfma_f32_16x16x32_bf16 v[120:123], v[146:149], v[186:189], v[120:123]
	v_mfma_f32_16x16x32_bf16 v[124:127], v[154:157], v[186:189], v[124:127]
	v_mfma_f32_16x16x32_bf16 v[104:107], v[154:157], v[194:197], v[104:107]
	v_mfma_f32_16x16x32_bf16 v[108:111], v[146:149], v[194:197], v[108:111]
	v_mfma_f32_16x16x32_bf16 v[92:95], v[146:149], v[202:205], v[92:95]
	v_mfma_f32_16x16x32_bf16 v[88:91], v[154:157], v[202:205], v[88:91]
	v_mfma_f32_16x16x32_bf16 v[72:75], v[154:157], v[210:213], v[72:75]
	v_mfma_f32_16x16x32_bf16 v[76:79], v[146:149], v[210:213], v[76:79]
	s_setprio 0
	s_setprio 1
	v_mfma_f32_16x16x32_bf16 v[116:119], v[158:161], v[182:185], v[116:119]
	v_mfma_f32_16x16x32_bf16 v[112:115], v[166:169], v[182:185], v[112:115]
	v_mfma_f32_16x16x32_bf16 v[96:99], v[166:169], v[190:193], v[96:99]
	v_mfma_f32_16x16x32_bf16 v[100:103], v[158:161], v[190:193], v[100:103]
	v_mfma_f32_16x16x32_bf16 v[84:87], v[158:161], v[198:201], v[84:87]
	v_mfma_f32_16x16x32_bf16 v[80:83], v[166:169], v[198:201], v[80:83]
	v_mfma_f32_16x16x32_bf16 v[64:67], v[166:169], v[206:209], v[64:67]
	v_mfma_f32_16x16x32_bf16 v[68:71], v[158:161], v[206:209], v[68:71]
	v_mfma_f32_16x16x32_bf16 v[116:119], v[162:165], v[186:189], v[116:119]
	v_mfma_f32_16x16x32_bf16 v[112:115], v[170:173], v[186:189], v[112:115]
	v_mfma_f32_16x16x32_bf16 v[96:99], v[170:173], v[194:197], v[96:99]
	v_mfma_f32_16x16x32_bf16 v[100:103], v[162:165], v[194:197], v[100:103]
	v_mfma_f32_16x16x32_bf16 v[84:87], v[162:165], v[202:205], v[84:87]
	v_mfma_f32_16x16x32_bf16 v[80:83], v[170:173], v[202:205], v[80:83]
	v_mfma_f32_16x16x32_bf16 v[64:67], v[170:173], v[210:213], v[64:67]
	v_mfma_f32_16x16x32_bf16 v[68:71], v[162:165], v[210:213], v[68:71]
	s_setprio 0
	s_barrier
	s_add_i32 s48, s48, s24
	v_lshl_add_u64 v[174:175], s[38:39], 0, v[176:177]
	s_mov_b32 m0, s48
	ds_read_b128 v[182:185], v141 offset:16384
	ds_read_b128 v[186:189], v141 offset:17408
	ds_read_b128 v[190:193], v141 offset:18432
	ds_read_b128 v[194:197], v141 offset:19456
	ds_read_b128 v[198:201], v141 offset:20480
	ds_read_b128 v[202:205], v141 offset:21504
	ds_read_b128 v[206:209], v141 offset:22528
	ds_read_b128 v[210:213], v141 offset:23552
	global_load_lds_dwordx4 v[174:175], off
	s_add_i32 m0, s48, 0x2000
	v_lshl_add_u64 v[214:215], s[38:39], 0, v[132:133]
	s_add_u32 s38, s38, s10
	s_addc_u32 s39, s39, s11
	s_add_i32 s28, s28, s24
	global_load_lds_dwordx4 v[214:215], off
	v_lshl_add_u64 v[216:217], s[38:39], 0, v[176:177]
	s_mov_b32 m0, s28
	v_lshl_add_u64 v[218:219], s[38:39], 0, v[132:133]
	global_load_lds_dwordx4 v[216:217], off
	s_add_i32 m0, s28, 0x2000
	v_lshl_add_u64 v[220:221], s[64:65], 0, v[128:129]
	global_load_lds_dwordx4 v[218:219], off
	s_mov_b32 m0, s43
	v_lshl_add_u64 v[222:223], s[64:65], 0, v[130:131]
	global_load_lds_dwordx4 v[220:221], off
	s_mov_b32 m0, s46
	s_nop 0
	global_load_lds_dwordx4 v[222:223], off
	s_waitcnt vmcnt(8)
	s_waitcnt lgkmcnt(0)
	s_barrier
; #define PG8_STAGE(bufoff, gbase, voff) do { _Pragma("unroll") for (int _i = 0; _i < 2; ++_i) \
;         __builtin_amdgcn_global_load_lds((const unsigned*)((const char*)(gbase) + (voff)[_i]), (PG8_LAS unsigned*)(lds + (bufoff) + ldsw + _i * 8192), 16, 0, 0); } while (0)
; #define PG8_LDA(dst, b, h) do { _Pragma("unroll") for (int m = 0; m < 4; ++m) _Pragma("unroll") for (int k = 0; k < 2; ++k) dst[m][k] = *(const PG8_LAS bf16x8*)(lds + PG8_SA(b, h) + aoff + m * 2048 + k * 1024); } while (0)
; #define PG8_LDB(dst, b, h) do { _Pragma("unroll") for (int n = 0; n < 2; ++n) _Pragma("unroll") for (int k = 0; k < 2; ++k) dst[n][k] = *(const PG8_LAS bf16x8*)(lds + PG8_SB(b, h) + boff + n * 2048 + k * 1024); } while (0)
; #define PG8_MMA(ai, bj, At, Bt) do { __builtin_amdgcn_s_setprio(1); _Pragma("unroll") for (int m = 0; m < 4; ++m) _Pragma("unroll") for (int n = 0; n < 2; ++n) _Pragma("unroll") for (int k = 0; k < 2; ++k) \
;         acc[ai][bj][m][n] = __builtin_amdgcn_mfma_f32_16x16x32_bf16(Bt[n][k], At[m][k], acc[ai][bj][m][n], 0, 0, 0); __builtin_amdgcn_s_setprio(0); } while (0)
; #define PG8_WAIT_V(n) asm volatile("s_waitcnt vmcnt(" #n ")" ::: "memory")
; #define PG8_WAIT_L(n) asm volatile("s_waitcnt lgkmcnt(" #n ")" ::: "memory")
; #define PG8_BAR __builtin_amdgcn_s_barrier()
; #define PG8_SCHED __builtin_amdgcn_sched_barrier(0)
; template <class Epi, class Sched, bool ALIGN_EPI = false, bool SP2 = false>
; __device__ __forceinline__ void gemm_phase(PG8_LAS unsigned char* lds, const Gemm g, const Sched& S, const Epi& E) {
;     ...
;             PG8_WAIT_V(8); PG8_WAIT_L(0); PG8_BAR; PG8_MMA(0, 0, At, B0); PG8_MMA(0, 1, At, B1); PG8_BAR; PG8_SCHED;
;             PG8_LDA(At, 0, 1); PG8_STAGE(PG8_SB(0, 0), b2, voffB); PG8_STAGE(PG8_SB(0, 1), b2 + hstep, voffB); PG8_STAGE(PG8_SA(0, 0), a2, voffA);
;             PG8_WAIT_V(8); PG8_WAIT_L(0); PG8_BAR; PG8_MMA(1, 0, At, B0); PG8_MMA(1, 1, At, B1); PG8_BAR; PG8_SCHED;
;             PG8_LDB(B0, 1, 0); PG8_LDB(B1, 1, 1); PG8_SCHED; PG8_LDA(At, 1, 0); PG8_STAGE(PG8_SA(0, 1), a2 + hstep, voffA);
;             PG8_WAIT_V(8); PG8_WAIT_L(0); PG8_BAR; PG8_MMA(0, 0, At, B0); PG8_MMA(0, 1, At, B1); PG8_BAR; PG8_SCHED;
	s_setprio 1
	s_waitcnt lgkmcnt(0)
	v_mfma_f32_16x16x32_bf16 v[60:63], v[142:145], v[182:185], v[60:63]
	v_mfma_f32_16x16x32_bf16 v[56:59], v[150:153], v[182:185], v[56:59]
	v_mfma_f32_16x16x32_bf16 v[40:43], v[150:153], v[190:193], v[40:43]
	v_mfma_f32_16x16x32_bf16 v[44:47], v[142:145], v[190:193], v[44:47]
	v_mfma_f32_16x16x32_bf16 v[28:31], v[142:145], v[198:201], v[28:31]
	v_mfma_f32_16x16x32_bf16 v[24:27], v[150:153], v[198:201], v[24:27]
	v_mfma_f32_16x16x32_bf16 v[8:11], v[150:153], v[206:209], v[8:11]
	v_mfma_f32_16x16x32_bf16 v[12:15], v[142:145], v[206:209], v[12:15]
	v_mfma_f32_16x16x32_bf16 v[60:63], v[146:149], v[186:189], v[60:63]
	v_mfma_f32_16x16x32_bf16 v[56:59], v[154:157], v[186:189], v[56:59]
	v_mfma_f32_16x16x32_bf16 v[40:43], v[154:157], v[194:197], v[40:43]
	v_mfma_f32_16x16x32_bf16 v[44:47], v[146:149], v[194:197], v[44:47]
	v_mfma_f32_16x16x32_bf16 v[28:31], v[146:149], v[202:205], v[28:31]
	v_mfma_f32_16x16x32_bf16 v[24:27], v[154:157], v[202:205], v[24:27]
	v_mfma_f32_16x16x32_bf16 v[8:11], v[154:157], v[210:213], v[8:11]
	v_mfma_f32_16x16x32_bf16 v[12:15], v[146:149], v[210:213], v[12:15]
	s_setprio 0
	s_setprio 1
	v_mfma_f32_16x16x32_bf16 v[52:55], v[158:161], v[182:185], v[52:55]
	v_mfma_f32_16x16x32_bf16 v[48:51], v[166:169], v[182:185], v[48:51]
	v_mfma_f32_16x16x32_bf16 v[32:35], v[166:169], v[190:193], v[32:35]
	v_mfma_f32_16x16x32_bf16 v[36:39], v[158:161], v[190:193], v[36:39]
	v_mfma_f32_16x16x32_bf16 v[20:23], v[158:161], v[198:201], v[20:23]
	v_mfma_f32_16x16x32_bf16 v[16:19], v[166:169], v[198:201], v[16:19]
	v_mfma_f32_16x16x32_bf16 v[0:3], v[166:169], v[206:209], v[0:3]
	v_mfma_f32_16x16x32_bf16 v[4:7], v[158:161], v[206:209], v[4:7]
	v_mfma_f32_16x16x32_bf16 v[52:55], v[162:165], v[186:189], v[52:55]
	v_mfma_f32_16x16x32_bf16 v[48:51], v[170:173], v[186:189], v[48:51]
	v_mfma_f32_16x16x32_bf16 v[32:35], v[170:173], v[194:197], v[32:35]
	v_mfma_f32_16x16x32_bf16 v[36:39], v[162:165], v[194:197], v[36:39]
	v_mfma_f32_16x16x32_bf16 v[20:23], v[162:165], v[202:205], v[20:23]
	v_mfma_f32_16x16x32_bf16 v[16:19], v[170:173], v[202:205], v[16:19]
	v_mfma_f32_16x16x32_bf16 v[0:3], v[170:173], v[210:213], v[0:3]
	v_mfma_f32_16x16x32_bf16 v[4:7], v[162:165], v[210:213], v[4:7]
	s_setprio 0
	s_barrier
	s_add_i32 s28, 0, 0x18000
	s_add_i32 s48, 0, 0x1c000
	v_add_u32_e32 v154, s28, v140
	v_add_u32_e32 v170, s48, v140
	ds_read_b128 v[142:145], v154
	ds_read_b128 v[146:149], v154 offset:1024
	ds_read_b128 v[150:153], v154 offset:2048
	ds_read_b128 v[154:157], v154 offset:3072
	ds_read_b128 v[158:161], v170
	ds_read_b128 v[162:165], v170 offset:1024
	ds_read_b128 v[166:169], v170 offset:2048
	ds_read_b128 v[170:173], v170 offset:3072
	s_add_u32 s38, s64, s10
	s_addc_u32 s39, s65, s11
	s_mov_b32 m0, s63
	v_lshl_add_u64 v[224:225], s[38:39], 0, v[128:129]
	ds_read_b128 v[182:185], v141 offset:32768
	ds_read_b128 v[186:189], v141 offset:33792
	ds_read_b128 v[190:193], v141 offset:34816
	ds_read_b128 v[194:197], v141 offset:35840
	ds_read_b128 v[198:201], v141 offset:36864
	ds_read_b128 v[202:205], v141 offset:37888
	ds_read_b128 v[206:209], v141 offset:38912
	ds_read_b128 v[210:213], v141 offset:39936
	global_load_lds_dwordx4 v[224:225], off
	v_lshl_add_u64 v[224:225], s[38:39], 0, v[130:131]
	s_mov_b32 m0, s66
	s_nop 0
	global_load_lds_dwordx4 v[224:225], off
	s_waitcnt vmcnt(8)
	s_waitcnt lgkmcnt(0)
	s_barrier
	s_setprio 1
	s_waitcnt lgkmcnt(0)
	v_mfma_f32_16x16x32_bf16 v[120:123], v[142:145], v[182:185], v[120:123]
	v_mfma_f32_16x16x32_bf16 v[124:127], v[150:153], v[182:185], v[124:127]
	v_mfma_f32_16x16x32_bf16 v[104:107], v[150:153], v[190:193], v[104:107]
	v_mfma_f32_16x16x32_bf16 v[108:111], v[142:145], v[190:193], v[108:111]
	v_mfma_f32_16x16x32_bf16 v[92:95], v[142:145], v[198:201], v[92:95]
	v_mfma_f32_16x16x32_bf16 v[88:91], v[150:153], v[198:201], v[88:91]
	v_mfma_f32_16x16x32_bf16 v[72:75], v[150:153], v[206:209], v[72:75]
	v_mfma_f32_16x16x32_bf16 v[76:79], v[142:145], v[206:209], v[76:79]
	v_mfma_f32_16x16x32_bf16 v[120:123], v[146:149], v[186:189], v[120:123]
	v_mfma_f32_16x16x32_bf16 v[124:127], v[154:157], v[186:189], v[124:127]
	v_mfma_f32_16x16x32_bf16 v[104:107], v[154:157], v[194:197], v[104:107]
	v_mfma_f32_16x16x32_bf16 v[108:111], v[146:149], v[194:197], v[108:111]
	v_mfma_f32_16x16x32_bf16 v[92:95], v[146:149], v[202:205], v[92:95]
	v_mfma_f32_16x16x32_bf16 v[88:91], v[154:157], v[202:205], v[88:91]
	v_mfma_f32_16x16x32_bf16 v[72:75], v[154:157], v[210:213], v[72:75]
	v_mfma_f32_16x16x32_bf16 v[76:79], v[146:149], v[210:213], v[76:79]
	s_setprio 0
	s_setprio 1
	v_mfma_f32_16x16x32_bf16 v[116:119], v[158:161], v[182:185], v[116:119]
	v_mfma_f32_16x16x32_bf16 v[112:115], v[166:169], v[182:185], v[112:115]
	v_mfma_f32_16x16x32_bf16 v[96:99], v[166:169], v[190:193], v[96:99]
	v_mfma_f32_16x16x32_bf16 v[100:103], v[158:161], v[190:193], v[100:103]
	v_mfma_f32_16x16x32_bf16 v[84:87], v[158:161], v[198:201], v[84:87]
	v_mfma_f32_16x16x32_bf16 v[80:83], v[166:169], v[198:201], v[80:83]
	v_mfma_f32_16x16x32_bf16 v[64:67], v[166:169], v[206:209], v[64:67]
	v_mfma_f32_16x16x32_bf16 v[68:71], v[158:161], v[206:209], v[68:71]
	v_mfma_f32_16x16x32_bf16 v[116:119], v[162:165], v[186:189], v[116:119]
	v_mfma_f32_16x16x32_bf16 v[112:115], v[170:173], v[186:189], v[112:115]
	v_mfma_f32_16x16x32_bf16 v[96:99], v[170:173], v[194:197], v[96:99]
	v_mfma_f32_16x16x32_bf16 v[100:103], v[162:165], v[194:197], v[100:103]
	v_mfma_f32_16x16x32_bf16 v[84:87], v[162:165], v[202:205], v[84:87]
	v_mfma_f32_16x16x32_bf16 v[80:83], v[170:173], v[202:205], v[80:83]
	v_mfma_f32_16x16x32_bf16 v[64:67], v[170:173], v[210:213], v[64:67]
	v_mfma_f32_16x16x32_bf16 v[68:71], v[162:165], v[210:213], v[68:71]
	s_setprio 0
	s_barrier
; #define PG8_STAGE(bufoff, gbase, voff) do { _Pragma("unroll") for (int _i = 0; _i < 2; ++_i) \
;         __builtin_amdgcn_global_load_lds((const unsigned*)((const char*)(gbase) + (voff)[_i]), (PG8_LAS unsigned*)(lds + (bufoff) + ldsw + _i * 8192), 16, 0, 0); } while (0)
; #define PG8_LDA(dst, b, h) do { _Pragma("unroll") for (int m = 0; m < 4; ++m) _Pragma("unroll") for (int k = 0; k < 2; ++k) dst[m][k] = *(const PG8_LAS bf16x8*)(lds + PG8_SA(b, h) + aoff + m * 2048 + k * 1024); } while (0)
; #define PG8_MMA(ai, bj, At, Bt) do { __builtin_amdgcn_s_setprio(1); _Pragma("unroll") for (int m = 0; m < 4; ++m) _Pragma("unroll") for (int n = 0; n < 2; ++n) _Pragma("unroll") for (int k = 0; k < 2; ++k) \
;         acc[ai][bj][m][n] = __builtin_amdgcn_mfma_f32_16x16x32_bf16(Bt[n][k], At[m][k], acc[ai][bj][m][n], 0, 0, 0); __builtin_amdgcn_s_setprio(0); } while (0)
; #define PG8_WAIT_V(n) asm volatile("s_waitcnt vmcnt(" #n ")" ::: "memory")
; #define PG8_WAIT_L(n) asm volatile("s_waitcnt lgkmcnt(" #n ")" ::: "memory")
; #define PG8_BAR __builtin_amdgcn_s_barrier()
; #define PG8_SCHED __builtin_amdgcn_sched_barrier(0)
; template <class Epi, class Sched, bool ALIGN_EPI = false, bool SP2 = false>
; __device__ __forceinline__ void gemm_phase(PG8_LAS unsigned char* lds, const Gemm g, const Sched& S, const Epi& E) {
;     ...
;             PG8_LDA(At, 1, 1); PG8_STAGE(PG8_SB(1, 0), b3, voffB); PG8_STAGE(PG8_SB(1, 1), b3 + hstep, voffB); PG8_STAGE(PG8_SA(1, 0), a3, voffA);
;             PG8_WAIT_V(8); PG8_WAIT_L(0); PG8_BAR; PG8_MMA(1, 0, At, B0); PG8_MMA(1, 1, At, B1); PG8_BAR; PG8_SCHED;
	s_add_i32 s28, s28, s24
	v_lshl_add_u64 v[174:175], v[174:175], 0, s[44:45]
	s_mov_b32 m0, s28
	ds_read_b128 v[182:185], v141 offset:49152
	ds_read_b128 v[186:189], v141 offset:50176
	ds_read_b128 v[190:193], v141 offset:51200
	ds_read_b128 v[194:197], v141 offset:52224
	ds_read_b128 v[198:201], v141 offset:53248
	ds_read_b128 v[202:205], v141 offset:54272
	ds_read_b128 v[206:209], v141 offset:55296
	ds_read_b128 v[210:213], v141 offset:56320
	global_load_lds_dwordx4 v[174:175], off
	v_lshl_add_u64 v[174:175], v[214:215], 0, s[44:45]
	s_add_i32 m0, s28, 0x2000
	s_add_i32 s28, s48, s24
	global_load_lds_dwordx4 v[174:175], off
	v_lshl_add_u64 v[174:175], v[216:217], 0, s[44:45]
	s_mov_b32 m0, s28
	s_nop 0
	global_load_lds_dwordx4 v[174:175], off
	v_lshl_add_u64 v[174:175], v[218:219], 0, s[44:45]
	s_add_i32 m0, s28, 0x2000
	s_nop 0
	global_load_lds_dwordx4 v[174:175], off
	v_lshl_add_u64 v[174:175], v[220:221], 0, s[44:45]
	s_mov_b32 m0, s72
	s_nop 0
	global_load_lds_dwordx4 v[174:175], off
	v_lshl_add_u64 v[174:175], v[222:223], 0, s[44:45]
	s_mov_b32 m0, s73
	s_nop 0
	global_load_lds_dwordx4 v[174:175], off
	s_waitcnt vmcnt(8)
	s_waitcnt lgkmcnt(0)
	s_barrier
	s_setprio 1
	s_waitcnt lgkmcnt(0)
	v_mfma_f32_16x16x32_bf16 v[60:63], v[142:145], v[182:185], v[60:63]
	v_mfma_f32_16x16x32_bf16 v[56:59], v[150:153], v[182:185], v[56:59]
	v_mfma_f32_16x16x32_bf16 v[40:43], v[150:153], v[190:193], v[40:43]
	v_mfma_f32_16x16x32_bf16 v[44:47], v[142:145], v[190:193], v[44:47]
	v_mfma_f32_16x16x32_bf16 v[28:31], v[142:145], v[198:201], v[28:31]
	v_mfma_f32_16x16x32_bf16 v[24:27], v[150:153], v[198:201], v[24:27]
	v_mfma_f32_16x16x32_bf16 v[8:11], v[150:153], v[206:209], v[8:11]
	v_mfma_f32_16x16x32_bf16 v[12:15], v[142:145], v[206:209], v[12:15]
	v_mfma_f32_16x16x32_bf16 v[60:63], v[146:149], v[186:189], v[60:63]
	v_mfma_f32_16x16x32_bf16 v[56:59], v[154:157], v[186:189], v[56:59]
	v_mfma_f32_16x16x32_bf16 v[40:43], v[154:157], v[194:197], v[40:43]
	v_mfma_f32_16x16x32_bf16 v[44:47], v[146:149], v[194:197], v[44:47]
	v_mfma_f32_16x16x32_bf16 v[28:31], v[146:149], v[202:205], v[28:31]
	v_mfma_f32_16x16x32_bf16 v[24:27], v[154:157], v[202:205], v[24:27]
	v_mfma_f32_16x16x32_bf16 v[8:11], v[154:157], v[210:213], v[8:11]
	v_mfma_f32_16x16x32_bf16 v[12:15], v[146:149], v[210:213], v[12:15]
	s_setprio 0
	s_setprio 1
	v_mfma_f32_16x16x32_bf16 v[52:55], v[158:161], v[182:185], v[52:55]
	v_mfma_f32_16x16x32_bf16 v[48:51], v[166:169], v[182:185], v[48:51]
	v_mfma_f32_16x16x32_bf16 v[36:39], v[158:161], v[190:193], v[36:39]
	v_mfma_f32_16x16x32_bf16 v[32:35], v[166:169], v[190:193], v[32:35]
	v_mfma_f32_16x16x32_bf16 v[20:23], v[158:161], v[198:201], v[20:23]
	v_mfma_f32_16x16x32_bf16 v[16:19], v[166:169], v[198:201], v[16:19]
	v_mfma_f32_16x16x32_bf16 v[4:7], v[158:161], v[206:209], v[4:7]
	v_mfma_f32_16x16x32_bf16 v[0:3], v[166:169], v[206:209], v[0:3]
	v_mfma_f32_16x16x32_bf16 v[52:55], v[162:165], v[186:189], v[52:55]
	v_mfma_f32_16x16x32_bf16 v[48:51], v[170:173], v[186:189], v[48:51]
	s_add_u32 s40, s40, 0x100
	v_mfma_f32_16x16x32_bf16 v[36:39], v[162:165], v[194:197], v[36:39]
	s_addc_u32 s41, s41, 0
	v_mfma_f32_16x16x32_bf16 v[32:35], v[170:173], v[194:197], v[32:35]
	s_add_u32 s78, s78, 0x100
	v_mfma_f32_16x16x32_bf16 v[20:23], v[162:165], v[202:205], v[20:23]
	s_addc_u32 s79, s79, 0
	v_mfma_f32_16x16x32_bf16 v[16:19], v[170:173], v[202:205], v[16:19]
	s_cmp_ge_i32 s80, s67
	v_mfma_f32_16x16x32_bf16 v[4:7], v[162:165], v[210:213], v[4:7]
	s_mov_b32 s64, s80
	v_mfma_f32_16x16x32_bf16 v[0:3], v[170:173], v[210:213], v[0:3]
	s_setprio 0
	s_barrier
	s_cbranch_scc0 .LBB0_375
	v_readlane_b32 s80, v254, 45
	v_readlane_b32 s78, v254, 43
	v_readlane_b32 s81, v254, 46
	v_readlane_b32 s82, v254, 47
	v_readlane_b32 s83, v254, 48
	v_readlane_b32 s84, v254, 49
	v_readlane_b32 s85, v254, 50
	v_readlane_b32 s86, v254, 51
	v_readlane_b32 s87, v254, 52
	v_readlane_b32 s88, v254, 53
	v_readlane_b32 s89, v254, 54
	v_readlane_b32 s92, v254, 57
	v_readlane_b32 s93, v254, 58
	v_readlane_b32 s94, v254, 59
	v_readlane_b32 s95, v254, 60
	v_readlane_b32 s79, v254, 44
	v_readlane_b32 s90, v254, 55
	v_readlane_b32 s91, v254, 56

; #define PG8_STAGE(bufoff, gbase, voff) do { _Pragma("unroll") for (int _i = 0; _i < 2; ++_i) \
;         __builtin_amdgcn_global_load_lds((const unsigned*)((const char*)(gbase) + (voff)[_i]), (PG8_LAS unsigned*)(lds + (bufoff) + ldsw + _i * 8192), 16, 0, 0); } while (0)
; #define PG8_LDA(dst, b, h) do { _Pragma("unroll") for (int m = 0; m < 4; ++m) _Pragma("unroll") for (int k = 0; k < 2; ++k) dst[m][k] = *(const PG8_LAS bf16x8*)(lds + PG8_SA(b, h) + aoff + m * 2048 + k * 1024); } while (0)
; #define PG8_LDB(dst, b, h) do { _Pragma("unroll") for (int n = 0; n < 2; ++n) _Pragma("unroll") for (int k = 0; k < 2; ++k) dst[n][k] = *(const PG8_LAS bf16x8*)(lds + PG8_SB(b, h) + boff + n * 2048 + k * 1024); } while (0)
; #define PG8_WAIT_V(n) asm volatile("s_waitcnt vmcnt(" #n ")" ::: "memory")
; #define PG8_WAIT_L(n) asm volatile("s_waitcnt lgkmcnt(" #n ")" ::: "memory")
; #define PG8_BAR __builtin_amdgcn_s_barrier()
; #define PG8_SCHED __builtin_amdgcn_sched_barrier(0)
; template <class Epi, class Sched, bool ALIGN_EPI = false, bool SP2 = false>
; __device__ __forceinline__ void gemm_phase(PG8_LAS unsigned char* lds, const Gemm g, const Sched& S, const Epi& E) {
;     ...
;         const char* nA = has_next ? (const char*)g.A + (size_t)nxt.pm * tstep + nxt.ko : cA; const char* nB = has_next ? (const char*)g.Bt + (size_t)nxt.pn * tstep + nxt.ko : cB;
;         for (int t = 0; t < nt; t += 2) {
;             const bool last = (t == nt - 2);
;             const char* a1 = cA + (size_t)(t + 1) * kstep;
;             const char* a2 = last ? nA : cA + (size_t)(t + 2) * kstep; const char* b2 = last ? nB : cB + (size_t)(t + 2) * kstep;
;             const char* a3 = a2 + kstep; const char* b3 = b2 + kstep;
;             if (last && has_next) S.a_ready(nxt);
;             if constexpr (SP2) {
;             PG8_LDB(B0, 0, 0); PG8_LDB(B1, 0, 1); PG8_SCHED; PG8_LDA(At, 0, 0); PG8_STAGE(PG8_SA(1, 1), a1 + hstep, voffA);
;             PG8_WAIT_V(8); PG8_WAIT_L(0); PG8_BAR; PG8_MMA(0, 0, At, B0); PG8_MMA(0, 1, At, B1); PG8_BAR; PG8_SCHED;
;             PG8_LDA(At, 0, 1); PG8_STAGE(PG8_SB(0, 0), b2, voffB); PG8_STAGE(PG8_SB(0, 1), b2 + hstep, voffB); PG8_STAGE(PG8_SA(0, 0), a2, voffA);
;             PG8_WAIT_V(8); PG8_WAIT_L(0); PG8_BAR; PG8_MMA(1, 0, At, B0); PG8_MMA(1, 1, At, B1); PG8_BAR; PG8_SCHED;
.LBB0_406:
	s_add_i32 s81, s66, 2
	s_add_u32 s28, s64, 0x80
	s_addc_u32 s38, s65, 0
	s_add_i32 s48, 0, 0x10000
	s_cmp_eq_u32 s75, s66
	s_cselect_b32 s67, s7, s38
	s_cselect_b32 s66, s6, s28
	s_cselect_b32 s39, s41, s80
	s_cselect_b32 s38, s40, s79
	s_add_i32 s28, 0, 0x14000
	v_add_u32_e32 v154, s48, v148
	v_add_u32_e32 v170, s28, v148
	ds_read_b128 v[138:141], v154
	ds_read_b128 v[142:145], v154 offset:1024
	ds_read_b128 v[150:153], v154 offset:2048
	ds_read_b128 v[154:157], v154 offset:3072
	ds_read_b128 v[158:161], v170
	ds_read_b128 v[162:165], v170 offset:1024
	ds_read_b128 v[166:169], v170 offset:2048
	ds_read_b128 v[170:173], v170 offset:3072
	v_lshl_add_u64 v[174:175], s[64:65], 0, v[134:135]
	s_add_i32 m0, s43, 0xc000
	ds_read_b128 v[182:185], v149
	ds_read_b128 v[186:189], v149 offset:1024
	ds_read_b128 v[190:193], v149 offset:2048
	ds_read_b128 v[194:197], v149 offset:3072
	ds_read_b128 v[198:201], v149 offset:4096
	ds_read_b128 v[202:205], v149 offset:5120
	ds_read_b128 v[206:209], v149 offset:6144
	ds_read_b128 v[210:213], v149 offset:7168
	global_load_lds_dwordx4 v[174:175], off
	v_lshl_add_u64 v[174:175], s[64:65], 0, v[136:137]
	s_add_i32 m0, s43, 0xe000
	s_nop 0
	global_load_lds_dwordx4 v[174:175], off
	s_waitcnt vmcnt(8)
	s_waitcnt lgkmcnt(0)
	s_barrier
	s_setprio 1
	s_waitcnt lgkmcnt(0)
	v_mfma_f32_16x16x32_bf16 v[124:127], v[138:141], v[182:185], v[124:127]
	v_mfma_f32_16x16x32_bf16 v[120:123], v[150:153], v[182:185], v[120:123]
	v_mfma_f32_16x16x32_bf16 v[112:115], v[150:153], v[190:193], v[112:115]
	v_mfma_f32_16x16x32_bf16 v[116:119], v[138:141], v[190:193], v[116:119]
	v_mfma_f32_16x16x32_bf16 v[104:107], v[138:141], v[198:201], v[104:107]
	v_mfma_f32_16x16x32_bf16 v[96:99], v[150:153], v[198:201], v[96:99]
	v_mfma_f32_16x16x32_bf16 v[80:83], v[150:153], v[206:209], v[80:83]
	v_mfma_f32_16x16x32_bf16 v[88:91], v[138:141], v[206:209], v[88:91]
	v_mfma_f32_16x16x32_bf16 v[124:127], v[142:145], v[186:189], v[124:127]
	v_mfma_f32_16x16x32_bf16 v[120:123], v[154:157], v[186:189], v[120:123]
	v_mfma_f32_16x16x32_bf16 v[112:115], v[154:157], v[194:197], v[112:115]
	v_mfma_f32_16x16x32_bf16 v[116:119], v[142:145], v[194:197], v[116:119]
	v_mfma_f32_16x16x32_bf16 v[104:107], v[142:145], v[202:205], v[104:107]
	v_mfma_f32_16x16x32_bf16 v[96:99], v[154:157], v[202:205], v[96:99]
	v_mfma_f32_16x16x32_bf16 v[80:83], v[154:157], v[210:213], v[80:83]
	v_mfma_f32_16x16x32_bf16 v[88:91], v[142:145], v[210:213], v[88:91]
	s_setprio 0
	s_setprio 1
	v_mfma_f32_16x16x32_bf16 v[108:111], v[158:161], v[182:185], v[108:111]
	v_mfma_f32_16x16x32_bf16 v[100:103], v[166:169], v[182:185], v[100:103]
	v_mfma_f32_16x16x32_bf16 v[84:87], v[166:169], v[190:193], v[84:87]
	v_mfma_f32_16x16x32_bf16 v[92:95], v[158:161], v[190:193], v[92:95]
	v_mfma_f32_16x16x32_bf16 v[76:79], v[158:161], v[198:201], v[76:79]
	v_mfma_f32_16x16x32_bf16 v[72:75], v[166:169], v[198:201], v[72:75]
	v_mfma_f32_16x16x32_bf16 v[64:67], v[166:169], v[206:209], v[64:67]
	v_mfma_f32_16x16x32_bf16 v[68:71], v[158:161], v[206:209], v[68:71]
	v_mfma_f32_16x16x32_bf16 v[108:111], v[162:165], v[186:189], v[108:111]
	v_mfma_f32_16x16x32_bf16 v[100:103], v[170:173], v[186:189], v[100:103]
	v_mfma_f32_16x16x32_bf16 v[84:87], v[170:173], v[194:197], v[84:87]
	v_mfma_f32_16x16x32_bf16 v[92:95], v[162:165], v[194:197], v[92:95]
	v_mfma_f32_16x16x32_bf16 v[76:79], v[162:165], v[202:205], v[76:79]
	v_mfma_f32_16x16x32_bf16 v[72:75], v[170:173], v[202:205], v[72:75]
	v_mfma_f32_16x16x32_bf16 v[64:67], v[170:173], v[210:213], v[64:67]
	v_mfma_f32_16x16x32_bf16 v[68:71], v[162:165], v[210:213], v[68:71]
	s_setprio 0
	s_barrier
	s_add_i32 s48, s48, s24
	v_lshl_add_u64 v[174:175], s[38:39], 0, v[176:177]
	s_mov_b32 m0, s48
	ds_read_b128 v[182:185], v149 offset:16384
	ds_read_b128 v[186:189], v149 offset:17408
	ds_read_b128 v[190:193], v149 offset:18432
	ds_read_b128 v[194:197], v149 offset:19456
	ds_read_b128 v[198:201], v149 offset:20480
	ds_read_b128 v[202:205], v149 offset:21504
	ds_read_b128 v[206:209], v149 offset:22528
	ds_read_b128 v[210:213], v149 offset:23552
	global_load_lds_dwordx4 v[174:175], off
	s_add_i32 m0, s48, 0x2000
	v_lshl_add_u64 v[214:215], s[38:39], 0, v[132:133]
	s_add_u32 s38, s38, s10
	s_addc_u32 s39, s39, s11
	s_add_i32 s28, s28, s24
	global_load_lds_dwordx4 v[214:215], off
	v_lshl_add_u64 v[216:217], s[38:39], 0, v[176:177]
	s_mov_b32 m0, s28
	v_lshl_add_u64 v[218:219], s[38:39], 0, v[132:133]
	global_load_lds_dwordx4 v[216:217], off
	s_add_i32 m0, s28, 0x2000
	v_lshl_add_u64 v[220:221], s[66:67], 0, v[128:129]
	global_load_lds_dwordx4 v[218:219], off
	s_mov_b32 m0, s43
	v_lshl_add_u64 v[222:223], s[66:67], 0, v[130:131]
	global_load_lds_dwordx4 v[220:221], off
	s_mov_b32 m0, s46
	s_nop 0
	global_load_lds_dwordx4 v[222:223], off
	s_waitcnt vmcnt(8)
	s_waitcnt lgkmcnt(0)
	s_barrier
; #define PG8_STAGE(bufoff, gbase, voff) do { _Pragma("unroll") for (int _i = 0; _i < 2; ++_i) \
;         __builtin_amdgcn_global_load_lds((const unsigned*)((const char*)(gbase) + (voff)[_i]), (PG8_LAS unsigned*)(lds + (bufoff) + ldsw + _i * 8192), 16, 0, 0); } while (0)
; #define PG8_LDA(dst, b, h) do { _Pragma("unroll") for (int m = 0; m < 4; ++m) _Pragma("unroll") for (int k = 0; k < 2; ++k) dst[m][k] = *(const PG8_LAS bf16x8*)(lds + PG8_SA(b, h) + aoff + m * 2048 + k * 1024); } while (0)
; #define PG8_LDB(dst, b, h) do { _Pragma("unroll") for (int n = 0; n < 2; ++n) _Pragma("unroll") for (int k = 0; k < 2; ++k) dst[n][k] = *(const PG8_LAS bf16x8*)(lds + PG8_SB(b, h) + boff + n * 2048 + k * 1024); } while (0)
; #define PG8_MMA(ai, bj, At, Bt) do { __builtin_amdgcn_s_setprio(1); _Pragma("unroll") for (int m = 0; m < 4; ++m) _Pragma("unroll") for (int n = 0; n < 2; ++n) _Pragma("unroll") for (int k = 0; k < 2; ++k) \
;         acc[ai][bj][m][n] = __builtin_amdgcn_mfma_f32_16x16x32_bf16(Bt[n][k], At[m][k], acc[ai][bj][m][n], 0, 0, 0); __builtin_amdgcn_s_setprio(0); } while (0)
; #define PG8_WAIT_V(n) asm volatile("s_waitcnt vmcnt(" #n ")" ::: "memory")
; #define PG8_WAIT_L(n) asm volatile("s_waitcnt lgkmcnt(" #n ")" ::: "memory")
; #define PG8_BAR __builtin_amdgcn_s_barrier()
; #define PG8_SCHED __builtin_amdgcn_sched_barrier(0)
; template <class Epi, class Sched, bool ALIGN_EPI = false, bool SP2 = false>
; __device__ __forceinline__ void gemm_phase(PG8_LAS unsigned char* lds, const Gemm g, const Sched& S, const Epi& E) {
;     ...
;             PG8_WAIT_V(8); PG8_WAIT_L(0); PG8_BAR; PG8_MMA(1, 0, At, B0); PG8_MMA(1, 1, At, B1); PG8_BAR; PG8_SCHED;
;             PG8_LDB(B0, 1, 0); PG8_LDB(B1, 1, 1); PG8_SCHED; PG8_LDA(At, 1, 0); PG8_STAGE(PG8_SA(0, 1), a2 + hstep, voffA);
;             PG8_WAIT_V(8); PG8_WAIT_L(0); PG8_BAR; PG8_MMA(0, 0, At, B0); PG8_MMA(0, 1, At, B1); PG8_BAR; PG8_SCHED;
;             PG8_LDA(At, 1, 1); PG8_STAGE(PG8_SB(1, 0), b3, voffB); PG8_STAGE(PG8_SB(1, 1), b3 + hstep, voffB); PG8_STAGE(PG8_SA(1, 0), a3, voffA);
	s_setprio 1
	s_waitcnt lgkmcnt(0)
	v_mfma_f32_16x16x32_bf16 v[60:63], v[138:141], v[182:185], v[60:63]
	v_mfma_f32_16x16x32_bf16 v[56:59], v[150:153], v[182:185], v[56:59]
	v_mfma_f32_16x16x32_bf16 v[48:51], v[150:153], v[190:193], v[48:51]
	v_mfma_f32_16x16x32_bf16 v[52:55], v[138:141], v[190:193], v[52:55]
	v_mfma_f32_16x16x32_bf16 v[40:43], v[138:141], v[198:201], v[40:43]
	v_mfma_f32_16x16x32_bf16 v[32:35], v[150:153], v[198:201], v[32:35]
	v_mfma_f32_16x16x32_bf16 v[16:19], v[150:153], v[206:209], v[16:19]
	v_mfma_f32_16x16x32_bf16 v[24:27], v[138:141], v[206:209], v[24:27]
	v_mfma_f32_16x16x32_bf16 v[60:63], v[142:145], v[186:189], v[60:63]
	v_mfma_f32_16x16x32_bf16 v[56:59], v[154:157], v[186:189], v[56:59]
	v_mfma_f32_16x16x32_bf16 v[48:51], v[154:157], v[194:197], v[48:51]
	v_mfma_f32_16x16x32_bf16 v[52:55], v[142:145], v[194:197], v[52:55]
	v_mfma_f32_16x16x32_bf16 v[40:43], v[142:145], v[202:205], v[40:43]
	v_mfma_f32_16x16x32_bf16 v[32:35], v[154:157], v[202:205], v[32:35]
	v_mfma_f32_16x16x32_bf16 v[16:19], v[154:157], v[210:213], v[16:19]
	v_mfma_f32_16x16x32_bf16 v[24:27], v[142:145], v[210:213], v[24:27]
	s_setprio 0
	s_setprio 1
	v_mfma_f32_16x16x32_bf16 v[44:47], v[158:161], v[182:185], v[44:47]
	v_mfma_f32_16x16x32_bf16 v[36:39], v[166:169], v[182:185], v[36:39]
	v_mfma_f32_16x16x32_bf16 v[20:23], v[166:169], v[190:193], v[20:23]
	v_mfma_f32_16x16x32_bf16 v[28:31], v[158:161], v[190:193], v[28:31]
	v_mfma_f32_16x16x32_bf16 v[12:15], v[158:161], v[198:201], v[12:15]
	v_mfma_f32_16x16x32_bf16 v[8:11], v[166:169], v[198:201], v[8:11]
	v_mfma_f32_16x16x32_bf16 v[0:3], v[166:169], v[206:209], v[0:3]
	v_mfma_f32_16x16x32_bf16 v[4:7], v[158:161], v[206:209], v[4:7]
	v_mfma_f32_16x16x32_bf16 v[44:47], v[162:165], v[186:189], v[44:47]
	v_mfma_f32_16x16x32_bf16 v[36:39], v[170:173], v[186:189], v[36:39]
	v_mfma_f32_16x16x32_bf16 v[20:23], v[170:173], v[194:197], v[20:23]
	v_mfma_f32_16x16x32_bf16 v[28:31], v[162:165], v[194:197], v[28:31]
	v_mfma_f32_16x16x32_bf16 v[12:15], v[162:165], v[202:205], v[12:15]
	v_mfma_f32_16x16x32_bf16 v[8:11], v[170:173], v[202:205], v[8:11]
	v_mfma_f32_16x16x32_bf16 v[0:3], v[170:173], v[210:213], v[0:3]
	v_mfma_f32_16x16x32_bf16 v[4:7], v[162:165], v[210:213], v[4:7]
	s_setprio 0
	s_barrier
	s_add_i32 s28, 0, 0x18000
	s_add_i32 s48, 0, 0x1c000
	v_add_u32_e32 v154, s28, v148
	v_add_u32_e32 v170, s48, v148
	ds_read_b128 v[138:141], v154
	ds_read_b128 v[142:145], v154 offset:1024
	ds_read_b128 v[150:153], v154 offset:2048
	ds_read_b128 v[154:157], v154 offset:3072
	ds_read_b128 v[158:161], v170
	ds_read_b128 v[162:165], v170 offset:1024
	ds_read_b128 v[166:169], v170 offset:2048
	ds_read_b128 v[170:173], v170 offset:3072
	s_add_u32 s38, s66, s10
	s_addc_u32 s39, s67, s11
	s_mov_b32 m0, s63
	v_lshl_add_u64 v[224:225], s[38:39], 0, v[128:129]
	ds_read_b128 v[182:185], v149 offset:32768
	ds_read_b128 v[186:189], v149 offset:33792
	ds_read_b128 v[190:193], v149 offset:34816
	ds_read_b128 v[194:197], v149 offset:35840
	ds_read_b128 v[198:201], v149 offset:36864
	ds_read_b128 v[202:205], v149 offset:37888
	ds_read_b128 v[206:209], v149 offset:38912
	ds_read_b128 v[210:213], v149 offset:39936
	global_load_lds_dwordx4 v[224:225], off
	v_lshl_add_u64 v[224:225], s[38:39], 0, v[130:131]
	s_mov_b32 m0, s68
	s_nop 0
	global_load_lds_dwordx4 v[224:225], off
	s_waitcnt vmcnt(8)
	s_waitcnt lgkmcnt(0)
	s_barrier
	s_setprio 1
	s_waitcnt lgkmcnt(0)
	v_mfma_f32_16x16x32_bf16 v[124:127], v[138:141], v[182:185], v[124:127]
	v_mfma_f32_16x16x32_bf16 v[120:123], v[150:153], v[182:185], v[120:123]
	v_mfma_f32_16x16x32_bf16 v[112:115], v[150:153], v[190:193], v[112:115]
	v_mfma_f32_16x16x32_bf16 v[116:119], v[138:141], v[190:193], v[116:119]
	v_mfma_f32_16x16x32_bf16 v[104:107], v[138:141], v[198:201], v[104:107]
	v_mfma_f32_16x16x32_bf16 v[96:99], v[150:153], v[198:201], v[96:99]
	v_mfma_f32_16x16x32_bf16 v[80:83], v[150:153], v[206:209], v[80:83]
	v_mfma_f32_16x16x32_bf16 v[88:91], v[138:141], v[206:209], v[88:91]
	v_mfma_f32_16x16x32_bf16 v[124:127], v[142:145], v[186:189], v[124:127]
	v_mfma_f32_16x16x32_bf16 v[120:123], v[154:157], v[186:189], v[120:123]
	v_mfma_f32_16x16x32_bf16 v[112:115], v[154:157], v[194:197], v[112:115]
	v_mfma_f32_16x16x32_bf16 v[116:119], v[142:145], v[194:197], v[116:119]
	v_mfma_f32_16x16x32_bf16 v[104:107], v[142:145], v[202:205], v[104:107]
	v_mfma_f32_16x16x32_bf16 v[96:99], v[154:157], v[202:205], v[96:99]
	v_mfma_f32_16x16x32_bf16 v[80:83], v[154:157], v[210:213], v[80:83]
	v_mfma_f32_16x16x32_bf16 v[88:91], v[142:145], v[210:213], v[88:91]
	s_setprio 0
	s_setprio 1
	v_mfma_f32_16x16x32_bf16 v[108:111], v[158:161], v[182:185], v[108:111]
	v_mfma_f32_16x16x32_bf16 v[100:103], v[166:169], v[182:185], v[100:103]
	v_mfma_f32_16x16x32_bf16 v[84:87], v[166:169], v[190:193], v[84:87]
	v_mfma_f32_16x16x32_bf16 v[92:95], v[158:161], v[190:193], v[92:95]
	v_mfma_f32_16x16x32_bf16 v[76:79], v[158:161], v[198:201], v[76:79]
	v_mfma_f32_16x16x32_bf16 v[72:75], v[166:169], v[198:201], v[72:75]
	v_mfma_f32_16x16x32_bf16 v[64:67], v[166:169], v[206:209], v[64:67]
	v_mfma_f32_16x16x32_bf16 v[68:71], v[158:161], v[206:209], v[68:71]
	v_mfma_f32_16x16x32_bf16 v[108:111], v[162:165], v[186:189], v[108:111]
	v_mfma_f32_16x16x32_bf16 v[100:103], v[170:173], v[186:189], v[100:103]
	v_mfma_f32_16x16x32_bf16 v[84:87], v[170:173], v[194:197], v[84:87]
	v_mfma_f32_16x16x32_bf16 v[92:95], v[162:165], v[194:197], v[92:95]
	v_mfma_f32_16x16x32_bf16 v[76:79], v[162:165], v[202:205], v[76:79]
	v_mfma_f32_16x16x32_bf16 v[72:75], v[170:173], v[202:205], v[72:75]
	v_mfma_f32_16x16x32_bf16 v[64:67], v[170:173], v[210:213], v[64:67]
	v_mfma_f32_16x16x32_bf16 v[68:71], v[162:165], v[210:213], v[68:71]
	s_setprio 0
	s_barrier
; #define PG8_STAGE(bufoff, gbase, voff) do { _Pragma("unroll") for (int _i = 0; _i < 2; ++_i) \
;         __builtin_amdgcn_global_load_lds((const unsigned*)((const char*)(gbase) + (voff)[_i]), (PG8_LAS unsigned*)(lds + (bufoff) + ldsw + _i * 8192), 16, 0, 0); } while (0)
; #define PG8_LDA(dst, b, h) do { _Pragma("unroll") for (int m = 0; m < 4; ++m) _Pragma("unroll") for (int k = 0; k < 2; ++k) dst[m][k] = *(const PG8_LAS bf16x8*)(lds + PG8_SA(b, h) + aoff + m * 2048 + k * 1024); } while (0)
; #define PG8_MMA(ai, bj, At, Bt) do { __builtin_amdgcn_s_setprio(1); _Pragma("unroll") for (int m = 0; m < 4; ++m) _Pragma("unroll") for (int n = 0; n < 2; ++n) _Pragma("unroll") for (int k = 0; k < 2; ++k) \
;         acc[ai][bj][m][n] = __builtin_amdgcn_mfma_f32_16x16x32_bf16(Bt[n][k], At[m][k], acc[ai][bj][m][n], 0, 0, 0); __builtin_amdgcn_s_setprio(0); } while (0)
; #define PG8_WAIT_V(n) asm volatile("s_waitcnt vmcnt(" #n ")" ::: "memory")
; #define PG8_WAIT_L(n) asm volatile("s_waitcnt lgkmcnt(" #n ")" ::: "memory")
; #define PG8_BAR __builtin_amdgcn_s_barrier()
; #define PG8_SCHED __builtin_amdgcn_sched_barrier(0)
; template <class Epi, class Sched, bool ALIGN_EPI = false, bool SP2 = false>
; __device__ __forceinline__ void gemm_phase(PG8_LAS unsigned char* lds, const Gemm g, const Sched& S, const Epi& E) {
;     ...
;             PG8_LDA(At, 1, 1); PG8_STAGE(PG8_SB(1, 0), b3, voffB); PG8_STAGE(PG8_SB(1, 1), b3 + hstep, voffB); PG8_STAGE(PG8_SA(1, 0), a3, voffA);
;             PG8_WAIT_V(8); PG8_WAIT_L(0); PG8_BAR; PG8_MMA(1, 0, At, B0); PG8_MMA(1, 1, At, B1); PG8_BAR; PG8_SCHED;
	s_add_i32 s28, s28, s24
	v_lshl_add_u64 v[174:175], v[174:175], 0, s[44:45]
	s_mov_b32 m0, s28
	ds_read_b128 v[182:185], v149 offset:49152
	ds_read_b128 v[186:189], v149 offset:50176
	ds_read_b128 v[190:193], v149 offset:51200
	ds_read_b128 v[194:197], v149 offset:52224
	ds_read_b128 v[198:201], v149 offset:53248
	ds_read_b128 v[202:205], v149 offset:54272
	ds_read_b128 v[206:209], v149 offset:55296
	ds_read_b128 v[210:213], v149 offset:56320
	global_load_lds_dwordx4 v[174:175], off
	v_lshl_add_u64 v[174:175], v[214:215], 0, s[44:45]
	s_add_i32 m0, s28, 0x2000
	s_add_i32 s28, s48, s24
	global_load_lds_dwordx4 v[174:175], off
	v_lshl_add_u64 v[174:175], v[216:217], 0, s[44:45]
	s_mov_b32 m0, s28
	s_nop 0
	global_load_lds_dwordx4 v[174:175], off
	v_lshl_add_u64 v[174:175], v[218:219], 0, s[44:45]
	s_add_i32 m0, s28, 0x2000
	s_nop 0
	global_load_lds_dwordx4 v[174:175], off
	v_lshl_add_u64 v[174:175], v[220:221], 0, s[44:45]
	s_mov_b32 m0, s73
	s_nop 0
	global_load_lds_dwordx4 v[174:175], off
	v_lshl_add_u64 v[174:175], v[222:223], 0, s[44:45]
	s_mov_b32 m0, s74
	s_nop 0
	global_load_lds_dwordx4 v[174:175], off
	s_waitcnt vmcnt(8)
	s_waitcnt lgkmcnt(0)
	s_barrier
	s_setprio 1
	s_waitcnt lgkmcnt(0)
	v_mfma_f32_16x16x32_bf16 v[60:63], v[138:141], v[182:185], v[60:63]
	v_mfma_f32_16x16x32_bf16 v[56:59], v[150:153], v[182:185], v[56:59]
	v_mfma_f32_16x16x32_bf16 v[48:51], v[150:153], v[190:193], v[48:51]
	v_mfma_f32_16x16x32_bf16 v[52:55], v[138:141], v[190:193], v[52:55]
	v_mfma_f32_16x16x32_bf16 v[40:43], v[138:141], v[198:201], v[40:43]
	v_mfma_f32_16x16x32_bf16 v[32:35], v[150:153], v[198:201], v[32:35]
	v_mfma_f32_16x16x32_bf16 v[16:19], v[150:153], v[206:209], v[16:19]
	v_mfma_f32_16x16x32_bf16 v[24:27], v[138:141], v[206:209], v[24:27]
	v_mfma_f32_16x16x32_bf16 v[60:63], v[142:145], v[186:189], v[60:63]
	v_mfma_f32_16x16x32_bf16 v[56:59], v[154:157], v[186:189], v[56:59]
	v_mfma_f32_16x16x32_bf16 v[48:51], v[154:157], v[194:197], v[48:51]
	v_mfma_f32_16x16x32_bf16 v[52:55], v[142:145], v[194:197], v[52:55]
	v_mfma_f32_16x16x32_bf16 v[40:43], v[142:145], v[202:205], v[40:43]
	v_mfma_f32_16x16x32_bf16 v[32:35], v[154:157], v[202:205], v[32:35]
	v_mfma_f32_16x16x32_bf16 v[16:19], v[154:157], v[210:213], v[16:19]
	v_mfma_f32_16x16x32_bf16 v[24:27], v[142:145], v[210:213], v[24:27]
	s_setprio 0
	s_setprio 1
	v_mfma_f32_16x16x32_bf16 v[44:47], v[158:161], v[182:185], v[44:47]
	v_mfma_f32_16x16x32_bf16 v[36:39], v[166:169], v[182:185], v[36:39]
	v_mfma_f32_16x16x32_bf16 v[28:31], v[158:161], v[190:193], v[28:31]
	v_mfma_f32_16x16x32_bf16 v[20:23], v[166:169], v[190:193], v[20:23]
	v_mfma_f32_16x16x32_bf16 v[12:15], v[158:161], v[198:201], v[12:15]
	v_mfma_f32_16x16x32_bf16 v[8:11], v[166:169], v[198:201], v[8:11]
	v_mfma_f32_16x16x32_bf16 v[4:7], v[158:161], v[206:209], v[4:7]
	v_mfma_f32_16x16x32_bf16 v[0:3], v[166:169], v[206:209], v[0:3]
	v_mfma_f32_16x16x32_bf16 v[44:47], v[162:165], v[186:189], v[44:47]
	v_mfma_f32_16x16x32_bf16 v[36:39], v[170:173], v[186:189], v[36:39]
	s_add_u32 s64, s64, 0x100
	v_mfma_f32_16x16x32_bf16 v[28:31], v[162:165], v[194:197], v[28:31]
	s_addc_u32 s65, s65, 0
	v_mfma_f32_16x16x32_bf16 v[20:23], v[170:173], v[194:197], v[20:23]
	s_add_u32 s79, s79, 0x100
	v_mfma_f32_16x16x32_bf16 v[12:15], v[162:165], v[202:205], v[12:15]
	s_addc_u32 s80, s80, 0
	v_mfma_f32_16x16x32_bf16 v[8:11], v[170:173], v[202:205], v[8:11]
	s_cmp_ge_i32 s81, s69
	v_mfma_f32_16x16x32_bf16 v[4:7], v[162:165], v[210:213], v[4:7]
	s_mov_b32 s66, s81
	v_mfma_f32_16x16x32_bf16 v[0:3], v[170:173], v[210:213], v[0:3]
	s_setprio 0
	s_barrier
	s_cbranch_scc0 .LBB0_406
;     __device__ __forceinline__ void operator()(const f32x4 (&acc)[2][2][4][2], const Unit& u, int wr, int wc, int fr, int fq) const {
;     ...
;                 for (int bj = 0; bj < 2; ++bj) { f32x4 v0 = acc[ai][bj][m][0], v1 = acc[ai][bj][m][1];
;                     if (ACT == 1) {
; #pragma unroll
;                         for (int j = 0; j < 4; ++j) { float a = fmaxf(v0[j], 0.f), b = fmaxf(v1[j], 0.f); v0[j] = a * a; v1[j] = b * b; } }
;                     v0 = v0 * scale; v1 = v1 * scale;
	s_brev_b32 s28, 60
	v_readlane_b32 s80, v254, 45
	v_pk_mul_f32 v[126:127], v[126:127], s[28:29] op_sel_hi:[1,0]
	v_pk_mul_f32 v[124:125], v[124:125], s[28:29] op_sel_hi:[1,0]
	v_pk_mul_f32 v[122:123], v[122:123], s[28:29] op_sel_hi:[1,0]
	v_pk_mul_f32 v[120:121], v[120:121], s[28:29] op_sel_hi:[1,0]
	v_pk_mul_f32 v[138:139], v[110:111], s[28:29] op_sel_hi:[1,0]
	v_pk_mul_f32 v[140:141], v[108:109], s[28:29] op_sel_hi:[1,0]
	v_pk_mul_f32 v[142:143], v[102:103], s[28:29] op_sel_hi:[1,0]
	v_pk_mul_f32 v[144:145], v[100:101], s[28:29] op_sel_hi:[1,0]
	v_pk_mul_f32 v[100:101], v[118:119], s[28:29] op_sel_hi:[1,0]
	v_pk_mul_f32 v[102:103], v[116:117], s[28:29] op_sel_hi:[1,0]
	v_pk_mul_f32 v[108:109], v[114:115], s[28:29] op_sel_hi:[1,0]
	v_pk_mul_f32 v[110:111], v[112:113], s[28:29] op_sel_hi:[1,0]
	v_pk_mul_f32 v[112:113], v[94:95], s[28:29] op_sel_hi:[1,0]
	v_pk_mul_f32 v[114:115], v[92:93], s[28:29] op_sel_hi:[1,0]
	v_pk_mul_f32 v[116:117], v[86:87], s[28:29] op_sel_hi:[1,0]
	v_pk_mul_f32 v[118:119], v[84:85], s[28:29] op_sel_hi:[1,0]
	v_pk_mul_f32 v[84:85], v[106:107], s[28:29] op_sel_hi:[1,0]
	v_pk_mul_f32 v[86:87], v[104:105], s[28:29] op_sel_hi:[1,0]
	v_pk_mul_f32 v[92:93], v[98:99], s[28:29] op_sel_hi:[1,0]
	v_pk_mul_f32 v[94:95], v[96:97], s[28:29] op_sel_hi:[1,0]
	v_pk_mul_f32 v[96:97], v[78:79], s[28:29] op_sel_hi:[1,0]
	v_pk_mul_f32 v[98:99], v[76:77], s[28:29] op_sel_hi:[1,0]
	v_pk_mul_f32 v[104:105], v[74:75], s[28:29] op_sel_hi:[1,0]
	v_pk_mul_f32 v[106:107], v[72:73], s[28:29] op_sel_hi:[1,0]
	v_pk_mul_f32 v[72:73], v[90:91], s[28:29] op_sel_hi:[1,0]
	v_pk_mul_f32 v[74:75], v[88:89], s[28:29] op_sel_hi:[1,0]
	v_pk_mul_f32 v[76:77], v[82:83], s[28:29] op_sel_hi:[1,0]
	v_pk_mul_f32 v[78:79], v[80:81], s[28:29] op_sel_hi:[1,0]
	v_pk_mul_f32 v[70:71], v[70:71], s[28:29] op_sel_hi:[1,0]
	v_pk_mul_f32 v[68:69], v[68:69], s[28:29] op_sel_hi:[1,0]
	v_pk_mul_f32 v[66:67], v[66:67], s[28:29] op_sel_hi:[1,0]
	v_pk_mul_f32 v[64:65], v[64:65], s[28:29] op_sel_hi:[1,0]
	v_pk_mul_f32 v[62:63], v[62:63], s[28:29] op_sel_hi:[1,0]
	v_pk_mul_f32 v[60:61], v[60:61], s[28:29] op_sel_hi:[1,0]
	v_pk_mul_f32 v[58:59], v[58:59], s[28:29] op_sel_hi:[1,0]
	v_pk_mul_f32 v[56:57], v[56:57], s[28:29] op_sel_hi:[1,0]
	v_pk_mul_f32 v[80:81], v[46:47], s[28:29] op_sel_hi:[1,0]
	v_pk_mul_f32 v[82:83], v[44:45], s[28:29] op_sel_hi:[1,0]
	v_pk_mul_f32 v[88:89], v[38:39], s[28:29] op_sel_hi:[1,0]
	v_pk_mul_f32 v[90:91], v[36:37], s[28:29] op_sel_hi:[1,0]
	v_pk_mul_f32 v[36:37], v[54:55], s[28:29] op_sel_hi:[1,0]
	v_pk_mul_f32 v[38:39], v[52:53], s[28:29] op_sel_hi:[1,0]
	v_pk_mul_f32 v[44:45], v[50:51], s[28:29] op_sel_hi:[1,0]
	v_pk_mul_f32 v[46:47], v[48:49], s[28:29] op_sel_hi:[1,0]
	v_pk_mul_f32 v[48:49], v[30:31], s[28:29] op_sel_hi:[1,0]
	v_pk_mul_f32 v[50:51], v[28:29], s[28:29] op_sel_hi:[1,0]
	v_pk_mul_f32 v[52:53], v[22:23], s[28:29] op_sel_hi:[1,0]
	v_pk_mul_f32 v[54:55], v[20:21], s[28:29] op_sel_hi:[1,0]
	v_pk_mul_f32 v[20:21], v[42:43], s[28:29] op_sel_hi:[1,0]
	v_pk_mul_f32 v[22:23], v[40:41], s[28:29] op_sel_hi:[1,0]
	v_pk_mul_f32 v[28:29], v[34:35], s[28:29] op_sel_hi:[1,0]
	v_pk_mul_f32 v[30:31], v[32:33], s[28:29] op_sel_hi:[1,0]
	v_pk_mul_f32 v[32:33], v[14:15], s[28:29] op_sel_hi:[1,0]
	v_pk_mul_f32 v[34:35], v[12:13], s[28:29] op_sel_hi:[1,0]
	v_pk_mul_f32 v[40:41], v[10:11], s[28:29] op_sel_hi:[1,0]
	v_pk_mul_f32 v[42:43], v[8:9], s[28:29] op_sel_hi:[1,0]
	v_pk_mul_f32 v[8:9], v[26:27], s[28:29] op_sel_hi:[1,0]
	v_pk_mul_f32 v[10:11], v[24:25], s[28:29] op_sel_hi:[1,0]
	v_pk_mul_f32 v[12:13], v[18:19], s[28:29] op_sel_hi:[1,0]
	v_pk_mul_f32 v[14:15], v[16:17], s[28:29] op_sel_hi:[1,0]
	v_pk_mul_f32 v[6:7], v[6:7], s[28:29] op_sel_hi:[1,0]
	v_pk_mul_f32 v[4:5], v[4:5], s[28:29] op_sel_hi:[1,0]
	v_pk_mul_f32 v[2:3], v[2:3], s[28:29] op_sel_hi:[1,0]
	v_pk_mul_f32 v[0:1], v[0:1], s[28:29] op_sel_hi:[1,0]
	v_readlane_b32 s81, v254, 46
	v_readlane_b32 s82, v254, 47
	v_readlane_b32 s83, v254, 48
	v_readlane_b32 s84, v254, 49
	v_readlane_b32 s85, v254, 50
	v_readlane_b32 s86, v254, 51
	v_readlane_b32 s87, v254, 52
	v_readlane_b32 s88, v254, 53
	v_readlane_b32 s89, v254, 54
	v_readlane_b32 s92, v254, 57
	v_readlane_b32 s93, v254, 58
	v_readlane_b32 s94, v254, 59
	v_readlane_b32 s95, v254, 60
	v_readlane_b32 s90, v254, 55
	v_readlane_b32 s91, v254, 56

; #define PG8_STAGE(bufoff, gbase, voff) do { _Pragma("unroll") for (int _i = 0; _i < 2; ++_i) \
;         __builtin_amdgcn_global_load_lds((const unsigned*)((const char*)(gbase) + (voff)[_i]), (PG8_LAS unsigned*)(lds + (bufoff) + ldsw + _i * 8192), 16, 0, 0); } while (0)
; #define PG8_LDA(dst, b, h) do { _Pragma("unroll") for (int m = 0; m < 4; ++m) _Pragma("unroll") for (int k = 0; k < 2; ++k) dst[m][k] = *(const PG8_LAS bf16x8*)(lds + PG8_SA(b, h) + aoff + m * 2048 + k * 1024); } while (0)
; #define PG8_LDB(dst, b, h) do { _Pragma("unroll") for (int n = 0; n < 2; ++n) _Pragma("unroll") for (int k = 0; k < 2; ++k) dst[n][k] = *(const PG8_LAS bf16x8*)(lds + PG8_SB(b, h) + boff + n * 2048 + k * 1024); } while (0)
; #define PG8_WAIT_V(n) asm volatile("s_waitcnt vmcnt(" #n ")" ::: "memory")
; #define PG8_WAIT_L(n) asm volatile("s_waitcnt lgkmcnt(" #n ")" ::: "memory")
; #define PG8_BAR __builtin_amdgcn_s_barrier()
; #define PG8_SCHED __builtin_amdgcn_sched_barrier(0)
; template <class Epi, class Sched, bool ALIGN_EPI = false, bool SP2 = false>
; __device__ __forceinline__ void gemm_phase(PG8_LAS unsigned char* lds, const Gemm g, const Sched& S, const Epi& E) {
;     ...
;         const char* nA = has_next ? (const char*)g.A + (size_t)nxt.pm * tstep + nxt.ko : cA; const char* nB = has_next ? (const char*)g.Bt + (size_t)nxt.pn * tstep + nxt.ko : cB;
;         for (int t = 0; t < nt; t += 2) {
;             const bool last = (t == nt - 2);
;             const char* a1 = cA + (size_t)(t + 1) * kstep;
;             const char* a2 = last ? nA : cA + (size_t)(t + 2) * kstep; const char* b2 = last ? nB : cB + (size_t)(t + 2) * kstep;
;             const char* a3 = a2 + kstep; const char* b3 = b2 + kstep;
;             if (last && has_next) S.a_ready(nxt);
;             if constexpr (SP2) {
;             PG8_LDB(B0, 0, 0); PG8_LDB(B1, 0, 1); PG8_SCHED; PG8_LDA(At, 0, 0); PG8_STAGE(PG8_SA(1, 1), a1 + hstep, voffA);
;             PG8_WAIT_V(8); PG8_WAIT_L(0); PG8_BAR; PG8_MMA(0, 0, At, B0); PG8_MMA(0, 1, At, B1); PG8_BAR; PG8_SCHED;
;             PG8_LDA(At, 0, 1); PG8_STAGE(PG8_SB(0, 0), b2, voffB); PG8_STAGE(PG8_SB(0, 1), b2 + hstep, voffB); PG8_STAGE(PG8_SA(0, 0), a2, voffA);
;             PG8_WAIT_V(8); PG8_WAIT_L(0); PG8_BAR; PG8_MMA(1, 0, At, B0); PG8_MMA(1, 1, At, B1); PG8_BAR; PG8_SCHED;
.LBB0_570:
	s_add_u32 s4, s40, 0xfffc0080
	s_addc_u32 s5, s41, -1
	s_add_i32 s28, 0, 0x10000
	s_cmp_eq_u32 s72, 12
	s_cselect_b32 s65, s18, s5
	s_cselect_b32 s64, s19, s4
	v_add_u32_e32 v138, s28, v142
	s_cselect_b32 s5, s13, s71
	s_cselect_b32 s4, s27, s70
	s_add_i32 s48, 0, 0x14000
	ds_read_b128 v[144:147], v138
	ds_read_b128 v[148:151], v138 offset:1024
	ds_read_b128 v[152:155], v138 offset:2048
	ds_read_b128 v[156:159], v138 offset:3072
	v_add_u32_e32 v138, s48, v142
	ds_read_b128 v[160:163], v138
	ds_read_b128 v[164:167], v138 offset:1024
	ds_read_b128 v[168:171], v138 offset:2048
	ds_read_b128 v[172:175], v138 offset:3072
	v_lshl_add_u64 v[138:139], s[40:41], 0, v[134:135]
	s_add_i32 m0, s25, 0xc000
	ds_read_b128 v[182:185], v143
	ds_read_b128 v[186:189], v143 offset:1024
	ds_read_b128 v[190:193], v143 offset:2048
	ds_read_b128 v[194:197], v143 offset:3072
	ds_read_b128 v[198:201], v143 offset:4096
	ds_read_b128 v[202:205], v143 offset:5120
	ds_read_b128 v[206:209], v143 offset:6144
	ds_read_b128 v[210:213], v143 offset:7168
	global_load_lds_dwordx4 v[138:139], off
	v_lshl_add_u64 v[138:139], s[40:41], 0, v[136:137]
	s_add_i32 m0, s25, 0xe000
	s_nop 0
	global_load_lds_dwordx4 v[138:139], off
	s_waitcnt vmcnt(8)
	s_waitcnt lgkmcnt(0)
	s_barrier
	s_setprio 1
	s_waitcnt lgkmcnt(0)
	v_mfma_f32_16x16x32_bf16 v[124:127], v[144:147], v[182:185], v[124:127]
	v_mfma_f32_16x16x32_bf16 v[120:123], v[152:155], v[182:185], v[120:123]
	v_mfma_f32_16x16x32_bf16 v[108:111], v[152:155], v[190:193], v[108:111]
	v_mfma_f32_16x16x32_bf16 v[116:119], v[144:147], v[190:193], v[116:119]
	v_mfma_f32_16x16x32_bf16 v[100:103], v[144:147], v[198:201], v[100:103]
	v_mfma_f32_16x16x32_bf16 v[92:95], v[152:155], v[198:201], v[92:95]
	v_mfma_f32_16x16x32_bf16 v[76:79], v[152:155], v[206:209], v[76:79]
	v_mfma_f32_16x16x32_bf16 v[84:87], v[144:147], v[206:209], v[84:87]
	v_mfma_f32_16x16x32_bf16 v[124:127], v[148:151], v[186:189], v[124:127]
	v_mfma_f32_16x16x32_bf16 v[120:123], v[156:159], v[186:189], v[120:123]
	v_mfma_f32_16x16x32_bf16 v[108:111], v[156:159], v[194:197], v[108:111]
	v_mfma_f32_16x16x32_bf16 v[116:119], v[148:151], v[194:197], v[116:119]
	v_mfma_f32_16x16x32_bf16 v[100:103], v[148:151], v[202:205], v[100:103]
	v_mfma_f32_16x16x32_bf16 v[92:95], v[156:159], v[202:205], v[92:95]
	v_mfma_f32_16x16x32_bf16 v[76:79], v[156:159], v[210:213], v[76:79]
	v_mfma_f32_16x16x32_bf16 v[84:87], v[148:151], v[210:213], v[84:87]
	s_setprio 0
	s_setprio 1
	v_mfma_f32_16x16x32_bf16 v[112:115], v[160:163], v[182:185], v[112:115]
	v_mfma_f32_16x16x32_bf16 v[104:107], v[168:171], v[182:185], v[104:107]
	v_mfma_f32_16x16x32_bf16 v[88:91], v[168:171], v[190:193], v[88:91]
	v_mfma_f32_16x16x32_bf16 v[96:99], v[160:163], v[190:193], v[96:99]
	v_mfma_f32_16x16x32_bf16 v[80:83], v[160:163], v[198:201], v[80:83]
	v_mfma_f32_16x16x32_bf16 v[72:75], v[168:171], v[198:201], v[72:75]
	v_mfma_f32_16x16x32_bf16 v[64:67], v[168:171], v[206:209], v[64:67]
	v_mfma_f32_16x16x32_bf16 v[68:71], v[160:163], v[206:209], v[68:71]
	v_mfma_f32_16x16x32_bf16 v[112:115], v[164:167], v[186:189], v[112:115]
	v_mfma_f32_16x16x32_bf16 v[104:107], v[172:175], v[186:189], v[104:107]
	v_mfma_f32_16x16x32_bf16 v[88:91], v[172:175], v[194:197], v[88:91]
	v_mfma_f32_16x16x32_bf16 v[96:99], v[164:167], v[194:197], v[96:99]
	v_mfma_f32_16x16x32_bf16 v[80:83], v[164:167], v[202:205], v[80:83]
	v_mfma_f32_16x16x32_bf16 v[72:75], v[172:175], v[202:205], v[72:75]
	v_mfma_f32_16x16x32_bf16 v[64:67], v[172:175], v[210:213], v[64:67]
	v_mfma_f32_16x16x32_bf16 v[68:71], v[164:167], v[210:213], v[68:71]
	s_setprio 0
	s_barrier
	s_add_i32 s28, s28, s24
	v_lshl_add_u64 v[138:139], s[4:5], 0, v[176:177]
	s_mov_b32 m0, s28
	ds_read_b128 v[182:185], v143 offset:16384
	ds_read_b128 v[186:189], v143 offset:17408
	ds_read_b128 v[190:193], v143 offset:18432
	ds_read_b128 v[194:197], v143 offset:19456
	ds_read_b128 v[198:201], v143 offset:20480
	ds_read_b128 v[202:205], v143 offset:21504
	ds_read_b128 v[206:209], v143 offset:22528
	ds_read_b128 v[210:213], v143 offset:23552
	global_load_lds_dwordx4 v[138:139], off
	s_add_i32 m0, s28, 0x2000
	s_add_u32 s38, s4, 0x40000
	v_lshl_add_u64 v[214:215], s[4:5], 0, v[128:129]
	s_addc_u32 s39, s5, 0
	s_add_i32 s28, s48, s24
	global_load_lds_dwordx4 v[214:215], off
	v_lshl_add_u64 v[216:217], s[38:39], 0, v[176:177]
	s_mov_b32 m0, s28
	v_lshl_add_u64 v[218:219], s[64:65], 0, v[130:131]
	global_load_lds_dwordx4 v[216:217], off
	v_lshl_add_u64 v[216:217], s[38:39], 0, v[128:129]
	s_add_i32 m0, s28, 0x2000
	s_nop 0
	global_load_lds_dwordx4 v[216:217], off
	v_lshl_add_u64 v[216:217], s[64:65], 0, v[132:133]
	s_mov_b32 m0, s25
	s_nop 0
	global_load_lds_dwordx4 v[216:217], off
	s_mov_b32 m0, s30
	s_nop 0
	global_load_lds_dwordx4 v[218:219], off
	s_waitcnt vmcnt(8)
	s_waitcnt lgkmcnt(0)
	s_barrier
; #define PG8_STAGE(bufoff, gbase, voff) do { _Pragma("unroll") for (int _i = 0; _i < 2; ++_i) \
;         __builtin_amdgcn_global_load_lds((const unsigned*)((const char*)(gbase) + (voff)[_i]), (PG8_LAS unsigned*)(lds + (bufoff) + ldsw + _i * 8192), 16, 0, 0); } while (0)
; #define PG8_LDA(dst, b, h) do { _Pragma("unroll") for (int m = 0; m < 4; ++m) _Pragma("unroll") for (int k = 0; k < 2; ++k) dst[m][k] = *(const PG8_LAS bf16x8*)(lds + PG8_SA(b, h) + aoff + m * 2048 + k * 1024); } while (0)
; #define PG8_LDB(dst, b, h) do { _Pragma("unroll") for (int n = 0; n < 2; ++n) _Pragma("unroll") for (int k = 0; k < 2; ++k) dst[n][k] = *(const PG8_LAS bf16x8*)(lds + PG8_SB(b, h) + boff + n * 2048 + k * 1024); } while (0)
; #define PG8_MMA(ai, bj, At, Bt) do { __builtin_amdgcn_s_setprio(1); _Pragma("unroll") for (int m = 0; m < 4; ++m) _Pragma("unroll") for (int n = 0; n < 2; ++n) _Pragma("unroll") for (int k = 0; k < 2; ++k) \
;         acc[ai][bj][m][n] = __builtin_amdgcn_mfma_f32_16x16x32_bf16(Bt[n][k], At[m][k], acc[ai][bj][m][n], 0, 0, 0); __builtin_amdgcn_s_setprio(0); } while (0)
; #define PG8_WAIT_V(n) asm volatile("s_waitcnt vmcnt(" #n ")" ::: "memory")
; #define PG8_WAIT_L(n) asm volatile("s_waitcnt lgkmcnt(" #n ")" ::: "memory")
; #define PG8_BAR __builtin_amdgcn_s_barrier()
; #define PG8_SCHED __builtin_amdgcn_sched_barrier(0)
; template <class Epi, class Sched, bool ALIGN_EPI = false, bool SP2 = false>
; __device__ __forceinline__ void gemm_phase(PG8_LAS unsigned char* lds, const Gemm g, const Sched& S, const Epi& E) {
;     ...
;             PG8_WAIT_V(8); PG8_WAIT_L(0); PG8_BAR; PG8_MMA(1, 0, At, B0); PG8_MMA(1, 1, At, B1); PG8_BAR; PG8_SCHED;
;             PG8_LDB(B0, 1, 0); PG8_LDB(B1, 1, 1); PG8_SCHED; PG8_LDA(At, 1, 0); PG8_STAGE(PG8_SA(0, 1), a2 + hstep, voffA);
;             PG8_WAIT_V(8); PG8_WAIT_L(0); PG8_BAR; PG8_MMA(0, 0, At, B0); PG8_MMA(0, 1, At, B1); PG8_BAR; PG8_SCHED;
;             PG8_LDA(At, 1, 1); PG8_STAGE(PG8_SB(1, 0), b3, voffB); PG8_STAGE(PG8_SB(1, 1), b3 + hstep, voffB); PG8_STAGE(PG8_SA(1, 0), a3, voffA);
	s_setprio 1
	s_waitcnt lgkmcnt(0)
	v_mfma_f32_16x16x32_bf16 v[60:63], v[144:147], v[182:185], v[60:63]
	v_mfma_f32_16x16x32_bf16 v[56:59], v[152:155], v[182:185], v[56:59]
	v_mfma_f32_16x16x32_bf16 v[44:47], v[152:155], v[190:193], v[44:47]
	v_mfma_f32_16x16x32_bf16 v[52:55], v[144:147], v[190:193], v[52:55]
	v_mfma_f32_16x16x32_bf16 v[36:39], v[144:147], v[198:201], v[36:39]
	v_mfma_f32_16x16x32_bf16 v[28:31], v[152:155], v[198:201], v[28:31]
	v_mfma_f32_16x16x32_bf16 v[12:15], v[152:155], v[206:209], v[12:15]
	v_mfma_f32_16x16x32_bf16 v[20:23], v[144:147], v[206:209], v[20:23]
	v_mfma_f32_16x16x32_bf16 v[60:63], v[148:151], v[186:189], v[60:63]
	v_mfma_f32_16x16x32_bf16 v[56:59], v[156:159], v[186:189], v[56:59]
	v_mfma_f32_16x16x32_bf16 v[44:47], v[156:159], v[194:197], v[44:47]
	v_mfma_f32_16x16x32_bf16 v[52:55], v[148:151], v[194:197], v[52:55]
	v_mfma_f32_16x16x32_bf16 v[36:39], v[148:151], v[202:205], v[36:39]
	v_mfma_f32_16x16x32_bf16 v[28:31], v[156:159], v[202:205], v[28:31]
	v_mfma_f32_16x16x32_bf16 v[12:15], v[156:159], v[210:213], v[12:15]
	v_mfma_f32_16x16x32_bf16 v[20:23], v[148:151], v[210:213], v[20:23]
	s_setprio 0
	s_setprio 1
	v_mfma_f32_16x16x32_bf16 v[48:51], v[160:163], v[182:185], v[48:51]
	v_mfma_f32_16x16x32_bf16 v[40:43], v[168:171], v[182:185], v[40:43]
	v_mfma_f32_16x16x32_bf16 v[24:27], v[168:171], v[190:193], v[24:27]
	v_mfma_f32_16x16x32_bf16 v[32:35], v[160:163], v[190:193], v[32:35]
	v_mfma_f32_16x16x32_bf16 v[16:19], v[160:163], v[198:201], v[16:19]
	v_mfma_f32_16x16x32_bf16 v[8:11], v[168:171], v[198:201], v[8:11]
	v_mfma_f32_16x16x32_bf16 v[0:3], v[168:171], v[206:209], v[0:3]
	v_mfma_f32_16x16x32_bf16 v[4:7], v[160:163], v[206:209], v[4:7]
	v_mfma_f32_16x16x32_bf16 v[48:51], v[164:167], v[186:189], v[48:51]
	v_mfma_f32_16x16x32_bf16 v[40:43], v[172:175], v[186:189], v[40:43]
	v_mfma_f32_16x16x32_bf16 v[24:27], v[172:175], v[194:197], v[24:27]
	v_mfma_f32_16x16x32_bf16 v[32:35], v[164:167], v[194:197], v[32:35]
	v_mfma_f32_16x16x32_bf16 v[16:19], v[164:167], v[202:205], v[16:19]
	v_mfma_f32_16x16x32_bf16 v[8:11], v[172:175], v[202:205], v[8:11]
	v_mfma_f32_16x16x32_bf16 v[0:3], v[172:175], v[210:213], v[0:3]
	v_mfma_f32_16x16x32_bf16 v[4:7], v[164:167], v[210:213], v[4:7]
	s_setprio 0
	s_barrier
	s_add_i32 s28, 0, 0x18000
	s_add_i32 s48, 0, 0x1c000
	v_add_u32_e32 v156, s28, v142
	v_add_u32_e32 v172, s48, v142
	ds_read_b128 v[144:147], v156
	ds_read_b128 v[148:151], v156 offset:1024
	ds_read_b128 v[152:155], v156 offset:2048
	ds_read_b128 v[156:159], v156 offset:3072
	ds_read_b128 v[160:163], v172
	ds_read_b128 v[164:167], v172 offset:1024
	ds_read_b128 v[168:171], v172 offset:2048
	ds_read_b128 v[172:175], v172 offset:3072
	s_add_u32 s38, s64, 0x40000
	s_addc_u32 s39, s65, 0
	s_mov_b32 m0, s31
	v_lshl_add_u64 v[220:221], s[38:39], 0, v[132:133]
	ds_read_b128 v[182:185], v143 offset:32768
	ds_read_b128 v[186:189], v143 offset:33792
	ds_read_b128 v[190:193], v143 offset:34816
	ds_read_b128 v[194:197], v143 offset:35840
	ds_read_b128 v[198:201], v143 offset:36864
	ds_read_b128 v[202:205], v143 offset:37888
	ds_read_b128 v[206:209], v143 offset:38912
	ds_read_b128 v[210:213], v143 offset:39936
	global_load_lds_dwordx4 v[220:221], off
	v_lshl_add_u64 v[220:221], s[38:39], 0, v[130:131]
	s_mov_b32 m0, s42
	s_nop 0
	global_load_lds_dwordx4 v[220:221], off
	s_waitcnt vmcnt(8)
	s_waitcnt lgkmcnt(0)
	s_barrier
	s_setprio 1
	s_waitcnt lgkmcnt(0)
	v_mfma_f32_16x16x32_bf16 v[124:127], v[144:147], v[182:185], v[124:127]
	v_mfma_f32_16x16x32_bf16 v[120:123], v[152:155], v[182:185], v[120:123]
	v_mfma_f32_16x16x32_bf16 v[108:111], v[152:155], v[190:193], v[108:111]
	v_mfma_f32_16x16x32_bf16 v[116:119], v[144:147], v[190:193], v[116:119]
	v_mfma_f32_16x16x32_bf16 v[100:103], v[144:147], v[198:201], v[100:103]
	v_mfma_f32_16x16x32_bf16 v[92:95], v[152:155], v[198:201], v[92:95]
	v_mfma_f32_16x16x32_bf16 v[76:79], v[152:155], v[206:209], v[76:79]
	v_mfma_f32_16x16x32_bf16 v[84:87], v[144:147], v[206:209], v[84:87]
	v_mfma_f32_16x16x32_bf16 v[124:127], v[148:151], v[186:189], v[124:127]
	v_mfma_f32_16x16x32_bf16 v[120:123], v[156:159], v[186:189], v[120:123]
	v_mfma_f32_16x16x32_bf16 v[108:111], v[156:159], v[194:197], v[108:111]
	v_mfma_f32_16x16x32_bf16 v[116:119], v[148:151], v[194:197], v[116:119]
	v_mfma_f32_16x16x32_bf16 v[100:103], v[148:151], v[202:205], v[100:103]
	v_mfma_f32_16x16x32_bf16 v[92:95], v[156:159], v[202:205], v[92:95]
	v_mfma_f32_16x16x32_bf16 v[76:79], v[156:159], v[210:213], v[76:79]
	v_mfma_f32_16x16x32_bf16 v[84:87], v[148:151], v[210:213], v[84:87]
	s_setprio 0
	s_setprio 1
	v_mfma_f32_16x16x32_bf16 v[112:115], v[160:163], v[182:185], v[112:115]
	v_mfma_f32_16x16x32_bf16 v[104:107], v[168:171], v[182:185], v[104:107]
	v_mfma_f32_16x16x32_bf16 v[88:91], v[168:171], v[190:193], v[88:91]
	v_mfma_f32_16x16x32_bf16 v[96:99], v[160:163], v[190:193], v[96:99]
	v_mfma_f32_16x16x32_bf16 v[80:83], v[160:163], v[198:201], v[80:83]
	v_mfma_f32_16x16x32_bf16 v[72:75], v[168:171], v[198:201], v[72:75]
	v_mfma_f32_16x16x32_bf16 v[64:67], v[168:171], v[206:209], v[64:67]
	v_mfma_f32_16x16x32_bf16 v[68:71], v[160:163], v[206:209], v[68:71]
	v_mfma_f32_16x16x32_bf16 v[112:115], v[164:167], v[186:189], v[112:115]
	v_mfma_f32_16x16x32_bf16 v[104:107], v[172:175], v[186:189], v[104:107]
	v_mfma_f32_16x16x32_bf16 v[88:91], v[172:175], v[194:197], v[88:91]
	v_mfma_f32_16x16x32_bf16 v[96:99], v[164:167], v[194:197], v[96:99]
	v_mfma_f32_16x16x32_bf16 v[80:83], v[164:167], v[202:205], v[80:83]
	v_mfma_f32_16x16x32_bf16 v[72:75], v[172:175], v[202:205], v[72:75]
	v_mfma_f32_16x16x32_bf16 v[64:67], v[172:175], v[210:213], v[64:67]
	v_mfma_f32_16x16x32_bf16 v[68:71], v[164:167], v[210:213], v[68:71]
	s_setprio 0
	s_barrier
; #define PG8_STAGE(bufoff, gbase, voff) do { _Pragma("unroll") for (int _i = 0; _i < 2; ++_i) \
;         __builtin_amdgcn_global_load_lds((const unsigned*)((const char*)(gbase) + (voff)[_i]), (PG8_LAS unsigned*)(lds + (bufoff) + ldsw + _i * 8192), 16, 0, 0); } while (0)
; #define PG8_LDA(dst, b, h) do { _Pragma("unroll") for (int m = 0; m < 4; ++m) _Pragma("unroll") for (int k = 0; k < 2; ++k) dst[m][k] = *(const PG8_LAS bf16x8*)(lds + PG8_SA(b, h) + aoff + m * 2048 + k * 1024); } while (0)
; #define PG8_MMA(ai, bj, At, Bt) do { __builtin_amdgcn_s_setprio(1); _Pragma("unroll") for (int m = 0; m < 4; ++m) _Pragma("unroll") for (int n = 0; n < 2; ++n) _Pragma("unroll") for (int k = 0; k < 2; ++k) \
;         acc[ai][bj][m][n] = __builtin_amdgcn_mfma_f32_16x16x32_bf16(Bt[n][k], At[m][k], acc[ai][bj][m][n], 0, 0, 0); __builtin_amdgcn_s_setprio(0); } while (0)
; #define PG8_WAIT_V(n) asm volatile("s_waitcnt vmcnt(" #n ")" ::: "memory")
; #define PG8_WAIT_L(n) asm volatile("s_waitcnt lgkmcnt(" #n ")" ::: "memory")
; #define PG8_BAR __builtin_amdgcn_s_barrier()
; #define PG8_SCHED __builtin_amdgcn_sched_barrier(0)
; template <class Epi, class Sched, bool ALIGN_EPI = false, bool SP2 = false>
; __device__ __forceinline__ void gemm_phase(PG8_LAS unsigned char* lds, const Gemm g, const Sched& S, const Epi& E) {
;     ...
;             PG8_LDA(At, 1, 1); PG8_STAGE(PG8_SB(1, 0), b3, voffB); PG8_STAGE(PG8_SB(1, 1), b3 + hstep, voffB); PG8_STAGE(PG8_SA(1, 0), a3, voffA);
;             PG8_WAIT_V(8); PG8_WAIT_L(0); PG8_BAR; PG8_MMA(1, 0, At, B0); PG8_MMA(1, 1, At, B1); PG8_BAR; PG8_SCHED;
	s_add_i32 s28, s28, s24
	v_lshl_add_u64 v[138:139], v[138:139], 0, s[44:45]
	s_mov_b32 m0, s28
	ds_read_b128 v[182:185], v143 offset:49152
	ds_read_b128 v[186:189], v143 offset:50176
	ds_read_b128 v[190:193], v143 offset:51200
	ds_read_b128 v[194:197], v143 offset:52224
	ds_read_b128 v[198:201], v143 offset:53248
	ds_read_b128 v[202:205], v143 offset:54272
	ds_read_b128 v[206:209], v143 offset:55296
	ds_read_b128 v[210:213], v143 offset:56320
	global_load_lds_dwordx4 v[138:139], off
	s_add_i32 m0, s28, 0x2000
	s_add_u32 s4, s4, 0x40080
	v_lshl_add_u64 v[138:139], v[214:215], 0, s[44:45]
	s_addc_u32 s5, s5, 0
	s_add_i32 s28, s48, s24
	global_load_lds_dwordx4 v[138:139], off
	v_lshl_add_u64 v[138:139], s[4:5], 0, v[176:177]
	s_mov_b32 m0, s28
	s_nop 0
	global_load_lds_dwordx4 v[138:139], off
	v_lshl_add_u64 v[138:139], s[4:5], 0, v[128:129]
	s_add_i32 m0, s28, 0x2000
	s_nop 0
	global_load_lds_dwordx4 v[138:139], off
	v_lshl_add_u64 v[138:139], v[216:217], 0, s[44:45]
	s_mov_b32 m0, s63
	s_nop 0
	global_load_lds_dwordx4 v[138:139], off
	v_lshl_add_u64 v[138:139], v[218:219], 0, s[44:45]
	s_mov_b32 m0, s66
	s_nop 0
	global_load_lds_dwordx4 v[138:139], off
	s_waitcnt vmcnt(8)
	s_waitcnt lgkmcnt(0)
	s_barrier
	s_setprio 1
	s_waitcnt lgkmcnt(0)
	v_mfma_f32_16x16x32_bf16 v[60:63], v[144:147], v[182:185], v[60:63]
	v_mfma_f32_16x16x32_bf16 v[56:59], v[152:155], v[182:185], v[56:59]
	v_mfma_f32_16x16x32_bf16 v[44:47], v[152:155], v[190:193], v[44:47]
	v_mfma_f32_16x16x32_bf16 v[52:55], v[144:147], v[190:193], v[52:55]
	v_mfma_f32_16x16x32_bf16 v[36:39], v[144:147], v[198:201], v[36:39]
	v_mfma_f32_16x16x32_bf16 v[28:31], v[152:155], v[198:201], v[28:31]
	v_mfma_f32_16x16x32_bf16 v[12:15], v[152:155], v[206:209], v[12:15]
	v_mfma_f32_16x16x32_bf16 v[20:23], v[144:147], v[206:209], v[20:23]
	v_mfma_f32_16x16x32_bf16 v[60:63], v[148:151], v[186:189], v[60:63]
	v_mfma_f32_16x16x32_bf16 v[56:59], v[156:159], v[186:189], v[56:59]
	v_mfma_f32_16x16x32_bf16 v[44:47], v[156:159], v[194:197], v[44:47]
	v_mfma_f32_16x16x32_bf16 v[52:55], v[148:151], v[194:197], v[52:55]
	v_mfma_f32_16x16x32_bf16 v[36:39], v[148:151], v[202:205], v[36:39]
	v_mfma_f32_16x16x32_bf16 v[28:31], v[156:159], v[202:205], v[28:31]
	v_mfma_f32_16x16x32_bf16 v[12:15], v[156:159], v[210:213], v[12:15]
	v_mfma_f32_16x16x32_bf16 v[20:23], v[148:151], v[210:213], v[20:23]
	s_setprio 0
	s_setprio 1
	v_mfma_f32_16x16x32_bf16 v[48:51], v[160:163], v[182:185], v[48:51]
	v_mfma_f32_16x16x32_bf16 v[40:43], v[168:171], v[182:185], v[40:43]
	v_mfma_f32_16x16x32_bf16 v[32:35], v[160:163], v[190:193], v[32:35]
	v_mfma_f32_16x16x32_bf16 v[24:27], v[168:171], v[190:193], v[24:27]
	v_mfma_f32_16x16x32_bf16 v[16:19], v[160:163], v[198:201], v[16:19]
	v_mfma_f32_16x16x32_bf16 v[8:11], v[168:171], v[198:201], v[8:11]
	v_mfma_f32_16x16x32_bf16 v[4:7], v[160:163], v[206:209], v[4:7]
	v_mfma_f32_16x16x32_bf16 v[0:3], v[168:171], v[206:209], v[0:3]
	v_mfma_f32_16x16x32_bf16 v[48:51], v[164:167], v[186:189], v[48:51]
	v_mfma_f32_16x16x32_bf16 v[40:43], v[172:175], v[186:189], v[40:43]
	s_add_i32 s72, s72, 2
	v_mfma_f32_16x16x32_bf16 v[32:35], v[164:167], v[194:197], v[32:35]
	s_add_u32 s40, s40, 0x100
	v_mfma_f32_16x16x32_bf16 v[24:27], v[172:175], v[194:197], v[24:27]
	s_addc_u32 s41, s41, 0
	v_mfma_f32_16x16x32_bf16 v[16:19], v[164:167], v[202:205], v[16:19]
	s_add_u32 s70, s70, 0x100
	v_mfma_f32_16x16x32_bf16 v[8:11], v[172:175], v[202:205], v[8:11]
	s_addc_u32 s71, s71, 0
	v_mfma_f32_16x16x32_bf16 v[4:7], v[164:167], v[210:213], v[4:7]
	s_cmp_gt_u32 s72, 13
	v_mfma_f32_16x16x32_bf16 v[0:3], v[172:175], v[210:213], v[0:3]
	s_setprio 0
	s_barrier
	s_cbranch_scc0 .LBB0_570

; #define PG8_STAGE(bufoff, gbase, voff) do { _Pragma("unroll") for (int _i = 0; _i < 2; ++_i) \
;         __builtin_amdgcn_global_load_lds((const unsigned*)((const char*)(gbase) + (voff)[_i]), (PG8_LAS unsigned*)(lds + (bufoff) + ldsw + _i * 8192), 16, 0, 0); } while (0)
; #define PG8_LDA(dst, b, h) do { _Pragma("unroll") for (int m = 0; m < 4; ++m) _Pragma("unroll") for (int k = 0; k < 2; ++k) dst[m][k] = *(const PG8_LAS bf16x8*)(lds + PG8_SA(b, h) + aoff + m * 2048 + k * 1024); } while (0)
; #define PG8_LDB(dst, b, h) do { _Pragma("unroll") for (int n = 0; n < 2; ++n) _Pragma("unroll") for (int k = 0; k < 2; ++k) dst[n][k] = *(const PG8_LAS bf16x8*)(lds + PG8_SB(b, h) + boff + n * 2048 + k * 1024); } while (0)
; #define PG8_MMA(ai, bj, At, Bt) do { __builtin_amdgcn_s_setprio(1); _Pragma("unroll") for (int m = 0; m < 4; ++m) _Pragma("unroll") for (int n = 0; n < 2; ++n) _Pragma("unroll") for (int k = 0; k < 2; ++k) \
;         acc[ai][bj][m][n] = __builtin_amdgcn_mfma_f32_16x16x32_bf16(Bt[n][k], At[m][k], acc[ai][bj][m][n], 0, 0, 0); __builtin_amdgcn_s_setprio(0); } while (0)
; #define PG8_WAIT_V(n) asm volatile("s_waitcnt vmcnt(" #n ")" ::: "memory")
; #define PG8_WAIT_L(n) asm volatile("s_waitcnt lgkmcnt(" #n ")" ::: "memory")
; #define PG8_BAR __builtin_amdgcn_s_barrier()
; #define PG8_SCHED __builtin_amdgcn_sched_barrier(0)
; template <class Epi, class Sched, bool ALIGN_EPI = false, bool SP2 = false>
; __device__ __forceinline__ void gemm_phase(PG8_LAS unsigned char* lds, const Gemm g, const Sched& S, const Epi& E) {
;     ...
;             const char* a2 = last ? nA : cA + (size_t)(t + 2) * kstep; const char* b2 = last ? nB : cB + (size_t)(t + 2) * kstep;
;             const char* a3 = a2 + kstep; const char* b3 = b2 + kstep;
;             if (last && has_next) S.a_ready(nxt);
;             if constexpr (SP2) {
;             PG8_LDB(B0, 0, 0); PG8_LDB(B1, 0, 1); PG8_SCHED; PG8_LDA(At, 0, 0); PG8_STAGE(PG8_SA(1, 1), a1 + hstep, voffA);
;             PG8_WAIT_V(8); PG8_WAIT_L(0); PG8_BAR; PG8_MMA(0, 0, At, B0); PG8_MMA(0, 1, At, B1); PG8_BAR; PG8_SCHED;
;             PG8_LDA(At, 0, 1); PG8_STAGE(PG8_SB(0, 0), b2, voffB); PG8_STAGE(PG8_SB(0, 1), b2 + hstep, voffB); PG8_STAGE(PG8_SA(0, 0), a2, voffA);
;             PG8_WAIT_V(8); PG8_WAIT_L(0); PG8_BAR; PG8_MMA(1, 0, At, B0); PG8_MMA(1, 1, At, B1); PG8_BAR; PG8_SCHED;
.Lg2_peel:
	s_add_u32 s4, s40, 0xfffc0080
	s_addc_u32 s5, s41, -1
	s_add_i32 s28, 0, 0x10000
	s_cmp_eq_u32 s72, 12
	s_cselect_b32 s65, s18, s5
	s_cselect_b32 s64, s19, s4
	v_add_u32_e32 v138, s28, v142
	s_cselect_b32 s5, s13, s71
	s_cselect_b32 s4, s27, s70
	s_add_i32 s48, 0, 0x14000
	ds_read_b128 v[144:147], v138
	ds_read_b128 v[148:151], v138 offset:1024
	ds_read_b128 v[152:155], v138 offset:2048
	ds_read_b128 v[156:159], v138 offset:3072
	v_add_u32_e32 v138, s48, v142
	ds_read_b128 v[160:163], v138
	ds_read_b128 v[164:167], v138 offset:1024
	ds_read_b128 v[168:171], v138 offset:2048
	ds_read_b128 v[172:175], v138 offset:3072
	v_lshl_add_u64 v[138:139], s[40:41], 0, v[134:135]
	s_add_i32 m0, s25, 0xc000
	ds_read_b128 v[182:185], v143
	ds_read_b128 v[186:189], v143 offset:1024
	ds_read_b128 v[190:193], v143 offset:2048
	ds_read_b128 v[194:197], v143 offset:3072
	ds_read_b128 v[198:201], v143 offset:4096
	ds_read_b128 v[202:205], v143 offset:5120
	ds_read_b128 v[206:209], v143 offset:6144
	ds_read_b128 v[210:213], v143 offset:7168
	global_load_lds_dwordx4 v[138:139], off
	v_lshl_add_u64 v[138:139], s[40:41], 0, v[136:137]
	s_add_i32 m0, s25, 0xe000
	s_nop 0
	global_load_lds_dwordx4 v[138:139], off
	s_waitcnt vmcnt(24)
	s_waitcnt lgkmcnt(0)
	s_barrier
	s_setprio 1
	s_waitcnt lgkmcnt(0)
	v_mfma_f32_16x16x32_bf16 v[124:127], v[144:147], v[182:185], 0
	v_mfma_f32_16x16x32_bf16 v[120:123], v[152:155], v[182:185], 0
	v_mfma_f32_16x16x32_bf16 v[108:111], v[152:155], v[190:193], 0
	v_mfma_f32_16x16x32_bf16 v[116:119], v[144:147], v[190:193], 0
	v_mfma_f32_16x16x32_bf16 v[100:103], v[144:147], v[198:201], 0
	v_mfma_f32_16x16x32_bf16 v[92:95], v[152:155], v[198:201], 0
	v_mfma_f32_16x16x32_bf16 v[76:79], v[152:155], v[206:209], 0
	v_mfma_f32_16x16x32_bf16 v[84:87], v[144:147], v[206:209], 0
	v_mfma_f32_16x16x32_bf16 v[124:127], v[148:151], v[186:189], v[124:127]
	v_mfma_f32_16x16x32_bf16 v[120:123], v[156:159], v[186:189], v[120:123]
	v_mfma_f32_16x16x32_bf16 v[108:111], v[156:159], v[194:197], v[108:111]
	v_mfma_f32_16x16x32_bf16 v[116:119], v[148:151], v[194:197], v[116:119]
	v_mfma_f32_16x16x32_bf16 v[100:103], v[148:151], v[202:205], v[100:103]
	v_mfma_f32_16x16x32_bf16 v[92:95], v[156:159], v[202:205], v[92:95]
	v_mfma_f32_16x16x32_bf16 v[76:79], v[156:159], v[210:213], v[76:79]
	v_mfma_f32_16x16x32_bf16 v[84:87], v[148:151], v[210:213], v[84:87]
	s_setprio 0
	s_setprio 1
	v_mfma_f32_16x16x32_bf16 v[112:115], v[160:163], v[182:185], 0
	v_mfma_f32_16x16x32_bf16 v[104:107], v[168:171], v[182:185], 0
	v_mfma_f32_16x16x32_bf16 v[88:91], v[168:171], v[190:193], 0
	v_mfma_f32_16x16x32_bf16 v[96:99], v[160:163], v[190:193], 0
	v_mfma_f32_16x16x32_bf16 v[80:83], v[160:163], v[198:201], 0
	v_mfma_f32_16x16x32_bf16 v[72:75], v[168:171], v[198:201], 0
	v_mfma_f32_16x16x32_bf16 v[64:67], v[168:171], v[206:209], 0
	v_mfma_f32_16x16x32_bf16 v[68:71], v[160:163], v[206:209], 0
	v_mfma_f32_16x16x32_bf16 v[112:115], v[164:167], v[186:189], v[112:115]
	v_mfma_f32_16x16x32_bf16 v[104:107], v[172:175], v[186:189], v[104:107]
	v_mfma_f32_16x16x32_bf16 v[88:91], v[172:175], v[194:197], v[88:91]
	v_mfma_f32_16x16x32_bf16 v[96:99], v[164:167], v[194:197], v[96:99]
	v_mfma_f32_16x16x32_bf16 v[80:83], v[164:167], v[202:205], v[80:83]
	v_mfma_f32_16x16x32_bf16 v[72:75], v[172:175], v[202:205], v[72:75]
	v_mfma_f32_16x16x32_bf16 v[64:67], v[172:175], v[210:213], v[64:67]
	v_mfma_f32_16x16x32_bf16 v[68:71], v[164:167], v[210:213], v[68:71]
	s_setprio 0
	s_barrier
	s_add_i32 s28, s28, s24
	v_lshl_add_u64 v[138:139], s[4:5], 0, v[176:177]
	s_mov_b32 m0, s28
	ds_read_b128 v[182:185], v143 offset:16384
	ds_read_b128 v[186:189], v143 offset:17408
	ds_read_b128 v[190:193], v143 offset:18432
	ds_read_b128 v[194:197], v143 offset:19456
	ds_read_b128 v[198:201], v143 offset:20480
	ds_read_b128 v[202:205], v143 offset:21504
	ds_read_b128 v[206:209], v143 offset:22528
	ds_read_b128 v[210:213], v143 offset:23552
	global_load_lds_dwordx4 v[138:139], off
	s_add_i32 m0, s28, 0x2000
	s_add_u32 s38, s4, 0x40000
	v_lshl_add_u64 v[214:215], s[4:5], 0, v[128:129]
	s_addc_u32 s39, s5, 0
	s_add_i32 s28, s48, s24
	global_load_lds_dwordx4 v[214:215], off
	v_lshl_add_u64 v[216:217], s[38:39], 0, v[176:177]
	s_mov_b32 m0, s28
	v_lshl_add_u64 v[218:219], s[64:65], 0, v[130:131]
	global_load_lds_dwordx4 v[216:217], off
	v_lshl_add_u64 v[216:217], s[38:39], 0, v[128:129]
	s_add_i32 m0, s28, 0x2000
	s_nop 0
	global_load_lds_dwordx4 v[216:217], off
	v_lshl_add_u64 v[216:217], s[64:65], 0, v[132:133]
	s_mov_b32 m0, s25
	s_nop 0
	global_load_lds_dwordx4 v[216:217], off
	s_mov_b32 m0, s30
	s_nop 0
	global_load_lds_dwordx4 v[218:219], off
	s_waitcnt vmcnt(24)
	s_waitcnt lgkmcnt(0)
	s_barrier
; #define PG8_STAGE(bufoff, gbase, voff) do { _Pragma("unroll") for (int _i = 0; _i < 2; ++_i) \
;         __builtin_amdgcn_global_load_lds((const unsigned*)((const char*)(gbase) + (voff)[_i]), (PG8_LAS unsigned*)(lds + (bufoff) + ldsw + _i * 8192), 16, 0, 0); } while (0)
; #define PG8_LDA(dst, b, h) do { _Pragma("unroll") for (int m = 0; m < 4; ++m) _Pragma("unroll") for (int k = 0; k < 2; ++k) dst[m][k] = *(const PG8_LAS bf16x8*)(lds + PG8_SA(b, h) + aoff + m * 2048 + k * 1024); } while (0)
; #define PG8_LDB(dst, b, h) do { _Pragma("unroll") for (int n = 0; n < 2; ++n) _Pragma("unroll") for (int k = 0; k < 2; ++k) dst[n][k] = *(const PG8_LAS bf16x8*)(lds + PG8_SB(b, h) + boff + n * 2048 + k * 1024); } while (0)
; #define PG8_MMA(ai, bj, At, Bt) do { __builtin_amdgcn_s_setprio(1); _Pragma("unroll") for (int m = 0; m < 4; ++m) _Pragma("unroll") for (int n = 0; n < 2; ++n) _Pragma("unroll") for (int k = 0; k < 2; ++k) \
;         acc[ai][bj][m][n] = __builtin_amdgcn_mfma_f32_16x16x32_bf16(Bt[n][k], At[m][k], acc[ai][bj][m][n], 0, 0, 0); __builtin_amdgcn_s_setprio(0); } while (0)
; #define PG8_WAIT_V(n) asm volatile("s_waitcnt vmcnt(" #n ")" ::: "memory")
; #define PG8_WAIT_L(n) asm volatile("s_waitcnt lgkmcnt(" #n ")" ::: "memory")
; #define PG8_BAR __builtin_amdgcn_s_barrier()
; #define PG8_SCHED __builtin_amdgcn_sched_barrier(0)
; template <class Epi, class Sched, bool ALIGN_EPI = false, bool SP2 = false>
; __device__ __forceinline__ void gemm_phase(PG8_LAS unsigned char* lds, const Gemm g, const Sched& S, const Epi& E) {
;     ...
;             PG8_WAIT_V(8); PG8_WAIT_L(0); PG8_BAR; PG8_MMA(1, 0, At, B0); PG8_MMA(1, 1, At, B1); PG8_BAR; PG8_SCHED;
;             PG8_LDB(B0, 1, 0); PG8_LDB(B1, 1, 1); PG8_SCHED; PG8_LDA(At, 1, 0); PG8_STAGE(PG8_SA(0, 1), a2 + hstep, voffA);
;             PG8_WAIT_V(8); PG8_WAIT_L(0); PG8_BAR; PG8_MMA(0, 0, At, B0); PG8_MMA(0, 1, At, B1); PG8_BAR; PG8_SCHED;
;             PG8_LDA(At, 1, 1); PG8_STAGE(PG8_SB(1, 0), b3, voffB); PG8_STAGE(PG8_SB(1, 1), b3 + hstep, voffB); PG8_STAGE(PG8_SA(1, 0), a3, voffA);
	s_setprio 1
	s_waitcnt lgkmcnt(0)
	v_mfma_f32_16x16x32_bf16 v[60:63], v[144:147], v[182:185], 0
	v_mfma_f32_16x16x32_bf16 v[56:59], v[152:155], v[182:185], 0
	v_mfma_f32_16x16x32_bf16 v[44:47], v[152:155], v[190:193], 0
	v_mfma_f32_16x16x32_bf16 v[52:55], v[144:147], v[190:193], 0
	v_mfma_f32_16x16x32_bf16 v[36:39], v[144:147], v[198:201], 0
	v_mfma_f32_16x16x32_bf16 v[28:31], v[152:155], v[198:201], 0
	v_mfma_f32_16x16x32_bf16 v[12:15], v[152:155], v[206:209], 0
	v_mfma_f32_16x16x32_bf16 v[20:23], v[144:147], v[206:209], 0
	v_mfma_f32_16x16x32_bf16 v[60:63], v[148:151], v[186:189], v[60:63]
	v_mfma_f32_16x16x32_bf16 v[56:59], v[156:159], v[186:189], v[56:59]
	v_mfma_f32_16x16x32_bf16 v[44:47], v[156:159], v[194:197], v[44:47]
	v_mfma_f32_16x16x32_bf16 v[52:55], v[148:151], v[194:197], v[52:55]
	v_mfma_f32_16x16x32_bf16 v[36:39], v[148:151], v[202:205], v[36:39]
	v_mfma_f32_16x16x32_bf16 v[28:31], v[156:159], v[202:205], v[28:31]
	v_mfma_f32_16x16x32_bf16 v[12:15], v[156:159], v[210:213], v[12:15]
	v_mfma_f32_16x16x32_bf16 v[20:23], v[148:151], v[210:213], v[20:23]
	s_setprio 0
	s_setprio 1
	v_mfma_f32_16x16x32_bf16 v[48:51], v[160:163], v[182:185], 0
	v_mfma_f32_16x16x32_bf16 v[40:43], v[168:171], v[182:185], 0
	v_mfma_f32_16x16x32_bf16 v[24:27], v[168:171], v[190:193], 0
	v_mfma_f32_16x16x32_bf16 v[32:35], v[160:163], v[190:193], 0
	v_mfma_f32_16x16x32_bf16 v[16:19], v[160:163], v[198:201], 0
	v_mfma_f32_16x16x32_bf16 v[8:11], v[168:171], v[198:201], 0
	v_mfma_f32_16x16x32_bf16 v[0:3], v[168:171], v[206:209], 0
	v_mfma_f32_16x16x32_bf16 v[4:7], v[160:163], v[206:209], 0
	v_mfma_f32_16x16x32_bf16 v[48:51], v[164:167], v[186:189], v[48:51]
	v_mfma_f32_16x16x32_bf16 v[40:43], v[172:175], v[186:189], v[40:43]
	v_mfma_f32_16x16x32_bf16 v[24:27], v[172:175], v[194:197], v[24:27]
	v_mfma_f32_16x16x32_bf16 v[32:35], v[164:167], v[194:197], v[32:35]
	v_mfma_f32_16x16x32_bf16 v[16:19], v[164:167], v[202:205], v[16:19]
	v_mfma_f32_16x16x32_bf16 v[8:11], v[172:175], v[202:205], v[8:11]
	v_mfma_f32_16x16x32_bf16 v[0:3], v[172:175], v[210:213], v[0:3]
	v_mfma_f32_16x16x32_bf16 v[4:7], v[164:167], v[210:213], v[4:7]
	s_setprio 0
	s_barrier
	s_add_i32 s28, 0, 0x18000
	s_add_i32 s48, 0, 0x1c000
	v_add_u32_e32 v156, s28, v142
	v_add_u32_e32 v172, s48, v142
	ds_read_b128 v[144:147], v156
	ds_read_b128 v[148:151], v156 offset:1024
	ds_read_b128 v[152:155], v156 offset:2048
	ds_read_b128 v[156:159], v156 offset:3072
	ds_read_b128 v[160:163], v172
	ds_read_b128 v[164:167], v172 offset:1024
	ds_read_b128 v[168:171], v172 offset:2048
	ds_read_b128 v[172:175], v172 offset:3072
	s_add_u32 s38, s64, 0x40000
	s_addc_u32 s39, s65, 0
	s_mov_b32 m0, s31
	v_lshl_add_u64 v[220:221], s[38:39], 0, v[132:133]
	ds_read_b128 v[182:185], v143 offset:32768
	ds_read_b128 v[186:189], v143 offset:33792
	ds_read_b128 v[190:193], v143 offset:34816
	ds_read_b128 v[194:197], v143 offset:35840
	ds_read_b128 v[198:201], v143 offset:36864
	ds_read_b128 v[202:205], v143 offset:37888
	ds_read_b128 v[206:209], v143 offset:38912
	ds_read_b128 v[210:213], v143 offset:39936
	global_load_lds_dwordx4 v[220:221], off
	v_lshl_add_u64 v[220:221], s[38:39], 0, v[130:131]
	s_mov_b32 m0, s42
	s_nop 0
	global_load_lds_dwordx4 v[220:221], off
	s_waitcnt vmcnt(8)
	s_waitcnt lgkmcnt(0)
	s_barrier
	s_setprio 1
	s_waitcnt lgkmcnt(0)
	v_mfma_f32_16x16x32_bf16 v[124:127], v[144:147], v[182:185], v[124:127]
	v_mfma_f32_16x16x32_bf16 v[120:123], v[152:155], v[182:185], v[120:123]
	v_mfma_f32_16x16x32_bf16 v[108:111], v[152:155], v[190:193], v[108:111]
	v_mfma_f32_16x16x32_bf16 v[116:119], v[144:147], v[190:193], v[116:119]
	v_mfma_f32_16x16x32_bf16 v[100:103], v[144:147], v[198:201], v[100:103]
	v_mfma_f32_16x16x32_bf16 v[92:95], v[152:155], v[198:201], v[92:95]
	v_mfma_f32_16x16x32_bf16 v[76:79], v[152:155], v[206:209], v[76:79]
	v_mfma_f32_16x16x32_bf16 v[84:87], v[144:147], v[206:209], v[84:87]
	v_mfma_f32_16x16x32_bf16 v[124:127], v[148:151], v[186:189], v[124:127]
	v_mfma_f32_16x16x32_bf16 v[120:123], v[156:159], v[186:189], v[120:123]
	v_mfma_f32_16x16x32_bf16 v[108:111], v[156:159], v[194:197], v[108:111]
	v_mfma_f32_16x16x32_bf16 v[116:119], v[148:151], v[194:197], v[116:119]
	v_mfma_f32_16x16x32_bf16 v[100:103], v[148:151], v[202:205], v[100:103]
	v_mfma_f32_16x16x32_bf16 v[92:95], v[156:159], v[202:205], v[92:95]
	v_mfma_f32_16x16x32_bf16 v[76:79], v[156:159], v[210:213], v[76:79]
	v_mfma_f32_16x16x32_bf16 v[84:87], v[148:151], v[210:213], v[84:87]
	s_setprio 0
	s_setprio 1
	v_mfma_f32_16x16x32_bf16 v[112:115], v[160:163], v[182:185], v[112:115]
	v_mfma_f32_16x16x32_bf16 v[104:107], v[168:171], v[182:185], v[104:107]
	v_mfma_f32_16x16x32_bf16 v[88:91], v[168:171], v[190:193], v[88:91]
	v_mfma_f32_16x16x32_bf16 v[96:99], v[160:163], v[190:193], v[96:99]
	v_mfma_f32_16x16x32_bf16 v[80:83], v[160:163], v[198:201], v[80:83]
	v_mfma_f32_16x16x32_bf16 v[72:75], v[168:171], v[198:201], v[72:75]
	v_mfma_f32_16x16x32_bf16 v[64:67], v[168:171], v[206:209], v[64:67]
	v_mfma_f32_16x16x32_bf16 v[68:71], v[160:163], v[206:209], v[68:71]
	v_mfma_f32_16x16x32_bf16 v[112:115], v[164:167], v[186:189], v[112:115]
	v_mfma_f32_16x16x32_bf16 v[104:107], v[172:175], v[186:189], v[104:107]
	v_mfma_f32_16x16x32_bf16 v[88:91], v[172:175], v[194:197], v[88:91]
	v_mfma_f32_16x16x32_bf16 v[96:99], v[164:167], v[194:197], v[96:99]
	v_mfma_f32_16x16x32_bf16 v[80:83], v[164:167], v[202:205], v[80:83]
	v_mfma_f32_16x16x32_bf16 v[72:75], v[172:175], v[202:205], v[72:75]
	v_mfma_f32_16x16x32_bf16 v[64:67], v[172:175], v[210:213], v[64:67]
	v_mfma_f32_16x16x32_bf16 v[68:71], v[164:167], v[210:213], v[68:71]
	s_setprio 0
	s_barrier
; #define PG8_STAGE(bufoff, gbase, voff) do { _Pragma("unroll") for (int _i = 0; _i < 2; ++_i) \
;         __builtin_amdgcn_global_load_lds((const unsigned*)((const char*)(gbase) + (voff)[_i]), (PG8_LAS unsigned*)(lds + (bufoff) + ldsw + _i * 8192), 16, 0, 0); } while (0)
; #define PG8_LDA(dst, b, h) do { _Pragma("unroll") for (int m = 0; m < 4; ++m) _Pragma("unroll") for (int k = 0; k < 2; ++k) dst[m][k] = *(const PG8_LAS bf16x8*)(lds + PG8_SA(b, h) + aoff + m * 2048 + k * 1024); } while (0)
; #define PG8_MMA(ai, bj, At, Bt) do { __builtin_amdgcn_s_setprio(1); _Pragma("unroll") for (int m = 0; m < 4; ++m) _Pragma("unroll") for (int n = 0; n < 2; ++n) _Pragma("unroll") for (int k = 0; k < 2; ++k) \
;         acc[ai][bj][m][n] = __builtin_amdgcn_mfma_f32_16x16x32_bf16(Bt[n][k], At[m][k], acc[ai][bj][m][n], 0, 0, 0); __builtin_amdgcn_s_setprio(0); } while (0)
; #define PG8_WAIT_V(n) asm volatile("s_waitcnt vmcnt(" #n ")" ::: "memory")
; #define PG8_WAIT_L(n) asm volatile("s_waitcnt lgkmcnt(" #n ")" ::: "memory")
; #define PG8_BAR __builtin_amdgcn_s_barrier()
; #define PG8_SCHED __builtin_amdgcn_sched_barrier(0)
; template <class Epi, class Sched, bool ALIGN_EPI = false, bool SP2 = false>
; __device__ __forceinline__ void gemm_phase(PG8_LAS unsigned char* lds, const Gemm g, const Sched& S, const Epi& E) {
;     ...
;             PG8_LDA(At, 1, 1); PG8_STAGE(PG8_SB(1, 0), b3, voffB); PG8_STAGE(PG8_SB(1, 1), b3 + hstep, voffB); PG8_STAGE(PG8_SA(1, 0), a3, voffA);
;             PG8_WAIT_V(8); PG8_WAIT_L(0); PG8_BAR; PG8_MMA(1, 0, At, B0); PG8_MMA(1, 1, At, B1); PG8_BAR; PG8_SCHED;
	s_add_i32 s28, s28, s24
	v_lshl_add_u64 v[138:139], v[138:139], 0, s[44:45]
	s_mov_b32 m0, s28
	ds_read_b128 v[182:185], v143 offset:49152
	ds_read_b128 v[186:189], v143 offset:50176
	ds_read_b128 v[190:193], v143 offset:51200
	ds_read_b128 v[194:197], v143 offset:52224
	ds_read_b128 v[198:201], v143 offset:53248
	ds_read_b128 v[202:205], v143 offset:54272
	ds_read_b128 v[206:209], v143 offset:55296
	ds_read_b128 v[210:213], v143 offset:56320
	global_load_lds_dwordx4 v[138:139], off
	s_add_i32 m0, s28, 0x2000
	s_add_u32 s4, s4, 0x40080
	v_lshl_add_u64 v[138:139], v[214:215], 0, s[44:45]
	s_addc_u32 s5, s5, 0
	s_add_i32 s28, s48, s24
	global_load_lds_dwordx4 v[138:139], off
	v_lshl_add_u64 v[138:139], s[4:5], 0, v[176:177]
	s_mov_b32 m0, s28
	s_nop 0
	global_load_lds_dwordx4 v[138:139], off
	v_lshl_add_u64 v[138:139], s[4:5], 0, v[128:129]
	s_add_i32 m0, s28, 0x2000
	s_nop 0
	global_load_lds_dwordx4 v[138:139], off
	v_lshl_add_u64 v[138:139], v[216:217], 0, s[44:45]
	s_mov_b32 m0, s63
	s_nop 0
	global_load_lds_dwordx4 v[138:139], off
	v_lshl_add_u64 v[138:139], v[218:219], 0, s[44:45]
	s_mov_b32 m0, s66
	s_nop 0
	global_load_lds_dwordx4 v[138:139], off
	s_waitcnt vmcnt(8)
	s_waitcnt lgkmcnt(0)
	s_barrier
	s_setprio 1
	s_waitcnt lgkmcnt(0)
	v_mfma_f32_16x16x32_bf16 v[60:63], v[144:147], v[182:185], v[60:63]
	v_mfma_f32_16x16x32_bf16 v[56:59], v[152:155], v[182:185], v[56:59]
	v_mfma_f32_16x16x32_bf16 v[44:47], v[152:155], v[190:193], v[44:47]
	v_mfma_f32_16x16x32_bf16 v[52:55], v[144:147], v[190:193], v[52:55]
	v_mfma_f32_16x16x32_bf16 v[36:39], v[144:147], v[198:201], v[36:39]
	v_mfma_f32_16x16x32_bf16 v[28:31], v[152:155], v[198:201], v[28:31]
	v_mfma_f32_16x16x32_bf16 v[12:15], v[152:155], v[206:209], v[12:15]
	v_mfma_f32_16x16x32_bf16 v[20:23], v[144:147], v[206:209], v[20:23]
	v_mfma_f32_16x16x32_bf16 v[60:63], v[148:151], v[186:189], v[60:63]
	v_mfma_f32_16x16x32_bf16 v[56:59], v[156:159], v[186:189], v[56:59]
	v_mfma_f32_16x16x32_bf16 v[44:47], v[156:159], v[194:197], v[44:47]
	v_mfma_f32_16x16x32_bf16 v[52:55], v[148:151], v[194:197], v[52:55]
	v_mfma_f32_16x16x32_bf16 v[36:39], v[148:151], v[202:205], v[36:39]
	v_mfma_f32_16x16x32_bf16 v[28:31], v[156:159], v[202:205], v[28:31]
	v_mfma_f32_16x16x32_bf16 v[12:15], v[156:159], v[210:213], v[12:15]
	v_mfma_f32_16x16x32_bf16 v[20:23], v[148:151], v[210:213], v[20:23]
	s_setprio 0
	s_setprio 1
	v_mfma_f32_16x16x32_bf16 v[48:51], v[160:163], v[182:185], v[48:51]
	v_mfma_f32_16x16x32_bf16 v[40:43], v[168:171], v[182:185], v[40:43]
	v_mfma_f32_16x16x32_bf16 v[32:35], v[160:163], v[190:193], v[32:35]
	v_mfma_f32_16x16x32_bf16 v[24:27], v[168:171], v[190:193], v[24:27]
	v_mfma_f32_16x16x32_bf16 v[16:19], v[160:163], v[198:201], v[16:19]
	v_mfma_f32_16x16x32_bf16 v[8:11], v[168:171], v[198:201], v[8:11]
	v_mfma_f32_16x16x32_bf16 v[4:7], v[160:163], v[206:209], v[4:7]
	v_mfma_f32_16x16x32_bf16 v[0:3], v[168:171], v[206:209], v[0:3]
	v_mfma_f32_16x16x32_bf16 v[48:51], v[164:167], v[186:189], v[48:51]
	v_mfma_f32_16x16x32_bf16 v[40:43], v[172:175], v[186:189], v[40:43]
	s_add_i32 s72, s72, 2
	v_mfma_f32_16x16x32_bf16 v[32:35], v[164:167], v[194:197], v[32:35]
	s_add_u32 s40, s40, 0x100
	v_mfma_f32_16x16x32_bf16 v[24:27], v[172:175], v[194:197], v[24:27]
	s_addc_u32 s41, s41, 0
	v_mfma_f32_16x16x32_bf16 v[16:19], v[164:167], v[202:205], v[16:19]
	s_add_u32 s70, s70, 0x100
	v_mfma_f32_16x16x32_bf16 v[8:11], v[172:175], v[202:205], v[8:11]
	s_addc_u32 s71, s71, 0
	v_mfma_f32_16x16x32_bf16 v[4:7], v[164:167], v[210:213], v[4:7]
	s_cmp_gt_u32 s72, 13
	v_mfma_f32_16x16x32_bf16 v[0:3], v[172:175], v[210:213], v[0:3]
	s_setprio 0
	s_barrier
	s_cbranch_scc0 .LBB0_570
	s_branch .Lg2_post

; #define PG8_STAGE(bufoff, gbase, voff) do { _Pragma("unroll") for (int _i = 0; _i < 2; ++_i) \
;         __builtin_amdgcn_global_load_lds((const unsigned*)((const char*)(gbase) + (voff)[_i]), (PG8_LAS unsigned*)(lds + (bufoff) + ldsw + _i * 8192), 16, 0, 0); } while (0)
; #define PG8_LDA(dst, b, h) do { _Pragma("unroll") for (int m = 0; m < 4; ++m) _Pragma("unroll") for (int k = 0; k < 2; ++k) dst[m][k] = *(const PG8_LAS bf16x8*)(lds + PG8_SA(b, h) + aoff + m * 2048 + k * 1024); } while (0)
; #define PG8_LDB(dst, b, h) do { _Pragma("unroll") for (int n = 0; n < 2; ++n) _Pragma("unroll") for (int k = 0; k < 2; ++k) dst[n][k] = *(const PG8_LAS bf16x8*)(lds + PG8_SB(b, h) + boff + n * 2048 + k * 1024); } while (0)
; #define PG8_WAIT_V(n) asm volatile("s_waitcnt vmcnt(" #n ")" ::: "memory")
; #define PG8_WAIT_L(n) asm volatile("s_waitcnt lgkmcnt(" #n ")" ::: "memory")
; #define PG8_BAR __builtin_amdgcn_s_barrier()
; #define PG8_SCHED __builtin_amdgcn_sched_barrier(0)
; template <class Epi, class Sched, bool ALIGN_EPI = false, bool SP2 = false>
; __device__ __forceinline__ void gemm_phase(PG8_LAS unsigned char* lds, const Gemm g, const Sched& S, const Epi& E) {
;     ...
;         const char* nA = has_next ? (const char*)g.A + (size_t)nxt.pm * tstep + nxt.ko : cA; const char* nB = has_next ? (const char*)g.Bt + (size_t)nxt.pn * tstep + nxt.ko : cB;
;         for (int t = 0; t < nt; t += 2) {
;             const bool last = (t == nt - 2);
;             const char* a1 = cA + (size_t)(t + 1) * kstep;
;             const char* a2 = last ? nA : cA + (size_t)(t + 2) * kstep; const char* b2 = last ? nB : cB + (size_t)(t + 2) * kstep;
;             const char* a3 = a2 + kstep; const char* b3 = b2 + kstep;
;             if (last && has_next) S.a_ready(nxt);
;             if constexpr (SP2) {
;             PG8_LDB(B0, 0, 0); PG8_LDB(B1, 0, 1); PG8_SCHED; PG8_LDA(At, 0, 0); PG8_STAGE(PG8_SA(1, 1), a1 + hstep, voffA);
;             PG8_WAIT_V(8); PG8_WAIT_L(0); PG8_BAR; PG8_MMA(0, 0, At, B0); PG8_MMA(0, 1, At, B1); PG8_BAR; PG8_SCHED;
;             PG8_LDA(At, 0, 1); PG8_STAGE(PG8_SB(0, 0), b2, voffB); PG8_STAGE(PG8_SB(0, 1), b2 + hstep, voffB); PG8_STAGE(PG8_SA(0, 0), a2, voffA);
;             PG8_WAIT_V(8); PG8_WAIT_L(0); PG8_BAR; PG8_MMA(1, 0, At, B0); PG8_MMA(1, 1, At, B1); PG8_BAR; PG8_SCHED;
.LBB0_592:
	s_add_i32 s81, s4, 2
	s_add_u32 s28, s66, 0x80
	s_addc_u32 s5, s67, 0
	s_add_i32 s48, 0, 0x10000
	s_cmp_eq_u32 s70, s4
	s_cselect_b32 s5, s41, s5
	s_cselect_b32 s4, s40, s28
	s_cselect_b32 s39, s65, s69
	s_cselect_b32 s38, s64, s68
	s_add_i32 s28, 0, 0x14000
	v_add_u32_e32 v154, s48, v140
	v_add_u32_e32 v170, s28, v140
	ds_read_b128 v[142:145], v154
	ds_read_b128 v[146:149], v154 offset:1024
	ds_read_b128 v[150:153], v154 offset:2048
	ds_read_b128 v[154:157], v154 offset:3072
	ds_read_b128 v[158:161], v170
	ds_read_b128 v[162:165], v170 offset:1024
	ds_read_b128 v[166:169], v170 offset:2048
	ds_read_b128 v[170:173], v170 offset:3072
	v_lshl_add_u64 v[174:175], s[66:67], 0, v[134:135]
	s_add_i32 m0, s19, 0xc000
	ds_read_b128 v[182:185], v141
	ds_read_b128 v[186:189], v141 offset:1024
	ds_read_b128 v[190:193], v141 offset:2048
	ds_read_b128 v[194:197], v141 offset:3072
	ds_read_b128 v[198:201], v141 offset:4096
	ds_read_b128 v[202:205], v141 offset:5120
	ds_read_b128 v[206:209], v141 offset:6144
	ds_read_b128 v[210:213], v141 offset:7168
	global_load_lds_dwordx4 v[174:175], off
	v_lshl_add_u64 v[174:175], s[66:67], 0, v[136:137]
	s_add_i32 m0, s19, 0xe000
	s_nop 0
	global_load_lds_dwordx4 v[174:175], off
	s_waitcnt vmcnt(8)
	s_waitcnt lgkmcnt(0)
	s_barrier
	s_setprio 1
	s_waitcnt lgkmcnt(0)
	v_mfma_f32_16x16x32_bf16 v[124:127], v[142:145], v[182:185], v[124:127]
	v_mfma_f32_16x16x32_bf16 v[120:123], v[150:153], v[182:185], v[120:123]
	v_mfma_f32_16x16x32_bf16 v[104:107], v[150:153], v[190:193], v[104:107]
	v_mfma_f32_16x16x32_bf16 v[108:111], v[142:145], v[190:193], v[108:111]
	v_mfma_f32_16x16x32_bf16 v[92:95], v[142:145], v[198:201], v[92:95]
	v_mfma_f32_16x16x32_bf16 v[88:91], v[150:153], v[198:201], v[88:91]
	v_mfma_f32_16x16x32_bf16 v[72:75], v[150:153], v[206:209], v[72:75]
	v_mfma_f32_16x16x32_bf16 v[76:79], v[142:145], v[206:209], v[76:79]
	v_mfma_f32_16x16x32_bf16 v[124:127], v[146:149], v[186:189], v[124:127]
	v_mfma_f32_16x16x32_bf16 v[120:123], v[154:157], v[186:189], v[120:123]
	v_mfma_f32_16x16x32_bf16 v[104:107], v[154:157], v[194:197], v[104:107]
	v_mfma_f32_16x16x32_bf16 v[108:111], v[146:149], v[194:197], v[108:111]
	v_mfma_f32_16x16x32_bf16 v[92:95], v[146:149], v[202:205], v[92:95]
	v_mfma_f32_16x16x32_bf16 v[88:91], v[154:157], v[202:205], v[88:91]
	v_mfma_f32_16x16x32_bf16 v[72:75], v[154:157], v[210:213], v[72:75]
	v_mfma_f32_16x16x32_bf16 v[76:79], v[146:149], v[210:213], v[76:79]
	s_setprio 0
	s_setprio 1
	v_mfma_f32_16x16x32_bf16 v[116:119], v[158:161], v[182:185], v[116:119]
	v_mfma_f32_16x16x32_bf16 v[112:115], v[166:169], v[182:185], v[112:115]
	v_mfma_f32_16x16x32_bf16 v[96:99], v[166:169], v[190:193], v[96:99]
	v_mfma_f32_16x16x32_bf16 v[100:103], v[158:161], v[190:193], v[100:103]
	v_mfma_f32_16x16x32_bf16 v[84:87], v[158:161], v[198:201], v[84:87]
	v_mfma_f32_16x16x32_bf16 v[80:83], v[166:169], v[198:201], v[80:83]
	v_mfma_f32_16x16x32_bf16 v[64:67], v[166:169], v[206:209], v[64:67]
	v_mfma_f32_16x16x32_bf16 v[68:71], v[158:161], v[206:209], v[68:71]
	v_mfma_f32_16x16x32_bf16 v[116:119], v[162:165], v[186:189], v[116:119]
	v_mfma_f32_16x16x32_bf16 v[112:115], v[170:173], v[186:189], v[112:115]
	v_mfma_f32_16x16x32_bf16 v[96:99], v[170:173], v[194:197], v[96:99]
	v_mfma_f32_16x16x32_bf16 v[100:103], v[162:165], v[194:197], v[100:103]
	v_mfma_f32_16x16x32_bf16 v[84:87], v[162:165], v[202:205], v[84:87]
	v_mfma_f32_16x16x32_bf16 v[80:83], v[170:173], v[202:205], v[80:83]
	v_mfma_f32_16x16x32_bf16 v[64:67], v[170:173], v[210:213], v[64:67]
	v_mfma_f32_16x16x32_bf16 v[68:71], v[162:165], v[210:213], v[68:71]
	s_setprio 0
	s_barrier
	s_add_i32 s48, s48, s18
	v_lshl_add_u64 v[174:175], s[38:39], 0, v[176:177]
	s_mov_b32 m0, s48
	ds_read_b128 v[182:185], v141 offset:16384
	ds_read_b128 v[186:189], v141 offset:17408
	ds_read_b128 v[190:193], v141 offset:18432
	ds_read_b128 v[194:197], v141 offset:19456
	ds_read_b128 v[198:201], v141 offset:20480
	ds_read_b128 v[202:205], v141 offset:21504
	ds_read_b128 v[206:209], v141 offset:22528
	ds_read_b128 v[210:213], v141 offset:23552
	global_load_lds_dwordx4 v[174:175], off
	s_add_i32 m0, s48, 0x2000
	v_lshl_add_u64 v[214:215], s[38:39], 0, v[128:129]
	s_add_u32 s38, s38, s0
	s_addc_u32 s39, s39, s1
	s_add_i32 s28, s28, s18
	global_load_lds_dwordx4 v[214:215], off
	v_lshl_add_u64 v[216:217], s[38:39], 0, v[176:177]
	s_mov_b32 m0, s28
	v_lshl_add_u64 v[218:219], s[38:39], 0, v[128:129]
	global_load_lds_dwordx4 v[216:217], off
	s_add_i32 m0, s28, 0x2000
	v_lshl_add_u64 v[220:221], s[4:5], 0, v[132:133]
	global_load_lds_dwordx4 v[218:219], off
	s_mov_b32 m0, s19
	v_lshl_add_u64 v[222:223], s[4:5], 0, v[130:131]
	global_load_lds_dwordx4 v[220:221], off
	s_mov_b32 m0, s24
	s_nop 0
	global_load_lds_dwordx4 v[222:223], off
	s_waitcnt vmcnt(8)
	s_waitcnt lgkmcnt(0)
	s_barrier
; #define PG8_STAGE(bufoff, gbase, voff) do { _Pragma("unroll") for (int _i = 0; _i < 2; ++_i) \
;         __builtin_amdgcn_global_load_lds((const unsigned*)((const char*)(gbase) + (voff)[_i]), (PG8_LAS unsigned*)(lds + (bufoff) + ldsw + _i * 8192), 16, 0, 0); } while (0)
; #define PG8_LDA(dst, b, h) do { _Pragma("unroll") for (int m = 0; m < 4; ++m) _Pragma("unroll") for (int k = 0; k < 2; ++k) dst[m][k] = *(const PG8_LAS bf16x8*)(lds + PG8_SA(b, h) + aoff + m * 2048 + k * 1024); } while (0)
; #define PG8_LDB(dst, b, h) do { _Pragma("unroll") for (int n = 0; n < 2; ++n) _Pragma("unroll") for (int k = 0; k < 2; ++k) dst[n][k] = *(const PG8_LAS bf16x8*)(lds + PG8_SB(b, h) + boff + n * 2048 + k * 1024); } while (0)
; #define PG8_MMA(ai, bj, At, Bt) do { __builtin_amdgcn_s_setprio(1); _Pragma("unroll") for (int m = 0; m < 4; ++m) _Pragma("unroll") for (int n = 0; n < 2; ++n) _Pragma("unroll") for (int k = 0; k < 2; ++k) \
;         acc[ai][bj][m][n] = __builtin_amdgcn_mfma_f32_16x16x32_bf16(Bt[n][k], At[m][k], acc[ai][bj][m][n], 0, 0, 0); __builtin_amdgcn_s_setprio(0); } while (0)
; #define PG8_WAIT_V(n) asm volatile("s_waitcnt vmcnt(" #n ")" ::: "memory")
; #define PG8_WAIT_L(n) asm volatile("s_waitcnt lgkmcnt(" #n ")" ::: "memory")
; #define PG8_BAR __builtin_amdgcn_s_barrier()
; #define PG8_SCHED __builtin_amdgcn_sched_barrier(0)
; template <class Epi, class Sched, bool ALIGN_EPI = false, bool SP2 = false>
; __device__ __forceinline__ void gemm_phase(PG8_LAS unsigned char* lds, const Gemm g, const Sched& S, const Epi& E) {
;     ...
;             PG8_WAIT_V(8); PG8_WAIT_L(0); PG8_BAR; PG8_MMA(1, 0, At, B0); PG8_MMA(1, 1, At, B1); PG8_BAR; PG8_SCHED;
;             PG8_LDB(B0, 1, 0); PG8_LDB(B1, 1, 1); PG8_SCHED; PG8_LDA(At, 1, 0); PG8_STAGE(PG8_SA(0, 1), a2 + hstep, voffA);
;             PG8_WAIT_V(8); PG8_WAIT_L(0); PG8_BAR; PG8_MMA(0, 0, At, B0); PG8_MMA(0, 1, At, B1); PG8_BAR; PG8_SCHED;
;             PG8_LDA(At, 1, 1); PG8_STAGE(PG8_SB(1, 0), b3, voffB); PG8_STAGE(PG8_SB(1, 1), b3 + hstep, voffB); PG8_STAGE(PG8_SA(1, 0), a3, voffA);
	s_setprio 1
	s_waitcnt lgkmcnt(0)
	v_mfma_f32_16x16x32_bf16 v[60:63], v[142:145], v[182:185], v[60:63]
	v_mfma_f32_16x16x32_bf16 v[56:59], v[150:153], v[182:185], v[56:59]
	v_mfma_f32_16x16x32_bf16 v[40:43], v[150:153], v[190:193], v[40:43]
	v_mfma_f32_16x16x32_bf16 v[44:47], v[142:145], v[190:193], v[44:47]
	v_mfma_f32_16x16x32_bf16 v[28:31], v[142:145], v[198:201], v[28:31]
	v_mfma_f32_16x16x32_bf16 v[24:27], v[150:153], v[198:201], v[24:27]
	v_mfma_f32_16x16x32_bf16 v[8:11], v[150:153], v[206:209], v[8:11]
	v_mfma_f32_16x16x32_bf16 v[12:15], v[142:145], v[206:209], v[12:15]
	v_mfma_f32_16x16x32_bf16 v[60:63], v[146:149], v[186:189], v[60:63]
	v_mfma_f32_16x16x32_bf16 v[56:59], v[154:157], v[186:189], v[56:59]
	v_mfma_f32_16x16x32_bf16 v[40:43], v[154:157], v[194:197], v[40:43]
	v_mfma_f32_16x16x32_bf16 v[44:47], v[146:149], v[194:197], v[44:47]
	v_mfma_f32_16x16x32_bf16 v[28:31], v[146:149], v[202:205], v[28:31]
	v_mfma_f32_16x16x32_bf16 v[24:27], v[154:157], v[202:205], v[24:27]
	v_mfma_f32_16x16x32_bf16 v[8:11], v[154:157], v[210:213], v[8:11]
	v_mfma_f32_16x16x32_bf16 v[12:15], v[146:149], v[210:213], v[12:15]
	s_setprio 0
	s_setprio 1
	v_mfma_f32_16x16x32_bf16 v[52:55], v[158:161], v[182:185], v[52:55]
	v_mfma_f32_16x16x32_bf16 v[48:51], v[166:169], v[182:185], v[48:51]
	v_mfma_f32_16x16x32_bf16 v[32:35], v[166:169], v[190:193], v[32:35]
	v_mfma_f32_16x16x32_bf16 v[36:39], v[158:161], v[190:193], v[36:39]
	v_mfma_f32_16x16x32_bf16 v[20:23], v[158:161], v[198:201], v[20:23]
	v_mfma_f32_16x16x32_bf16 v[16:19], v[166:169], v[198:201], v[16:19]
	v_mfma_f32_16x16x32_bf16 v[0:3], v[166:169], v[206:209], v[0:3]
	v_mfma_f32_16x16x32_bf16 v[4:7], v[158:161], v[206:209], v[4:7]
	v_mfma_f32_16x16x32_bf16 v[52:55], v[162:165], v[186:189], v[52:55]
	v_mfma_f32_16x16x32_bf16 v[48:51], v[170:173], v[186:189], v[48:51]
	v_mfma_f32_16x16x32_bf16 v[32:35], v[170:173], v[194:197], v[32:35]
	v_mfma_f32_16x16x32_bf16 v[36:39], v[162:165], v[194:197], v[36:39]
	v_mfma_f32_16x16x32_bf16 v[20:23], v[162:165], v[202:205], v[20:23]
	v_mfma_f32_16x16x32_bf16 v[16:19], v[170:173], v[202:205], v[16:19]
	v_mfma_f32_16x16x32_bf16 v[0:3], v[170:173], v[210:213], v[0:3]
	v_mfma_f32_16x16x32_bf16 v[4:7], v[162:165], v[210:213], v[4:7]
	s_setprio 0
	s_barrier
	s_add_i32 s28, 0, 0x18000
	s_add_i32 s38, 0, 0x1c000
	v_add_u32_e32 v154, s28, v140
	v_add_u32_e32 v170, s38, v140
	ds_read_b128 v[142:145], v154
	ds_read_b128 v[146:149], v154 offset:1024
	ds_read_b128 v[150:153], v154 offset:2048
	ds_read_b128 v[154:157], v154 offset:3072
	ds_read_b128 v[158:161], v170
	ds_read_b128 v[162:165], v170 offset:1024
	ds_read_b128 v[166:169], v170 offset:2048
	ds_read_b128 v[170:173], v170 offset:3072
	s_add_u32 s4, s4, s0
	s_addc_u32 s5, s5, s1
	s_mov_b32 m0, s25
	v_lshl_add_u64 v[224:225], s[4:5], 0, v[132:133]
	ds_read_b128 v[182:185], v141 offset:32768
	ds_read_b128 v[186:189], v141 offset:33792
	ds_read_b128 v[190:193], v141 offset:34816
	ds_read_b128 v[194:197], v141 offset:35840
	ds_read_b128 v[198:201], v141 offset:36864
	ds_read_b128 v[202:205], v141 offset:37888
	ds_read_b128 v[206:209], v141 offset:38912
	ds_read_b128 v[210:213], v141 offset:39936
	global_load_lds_dwordx4 v[224:225], off
	v_lshl_add_u64 v[224:225], s[4:5], 0, v[130:131]
	s_mov_b32 m0, s30
	s_nop 0
	global_load_lds_dwordx4 v[224:225], off
	s_waitcnt vmcnt(8)
	s_waitcnt lgkmcnt(0)
	s_barrier
	s_setprio 1
	s_waitcnt lgkmcnt(0)
	v_mfma_f32_16x16x32_bf16 v[124:127], v[142:145], v[182:185], v[124:127]
	v_mfma_f32_16x16x32_bf16 v[120:123], v[150:153], v[182:185], v[120:123]
	v_mfma_f32_16x16x32_bf16 v[104:107], v[150:153], v[190:193], v[104:107]
	v_mfma_f32_16x16x32_bf16 v[108:111], v[142:145], v[190:193], v[108:111]
	v_mfma_f32_16x16x32_bf16 v[92:95], v[142:145], v[198:201], v[92:95]
	v_mfma_f32_16x16x32_bf16 v[88:91], v[150:153], v[198:201], v[88:91]
	v_mfma_f32_16x16x32_bf16 v[72:75], v[150:153], v[206:209], v[72:75]
	v_mfma_f32_16x16x32_bf16 v[76:79], v[142:145], v[206:209], v[76:79]
	v_mfma_f32_16x16x32_bf16 v[124:127], v[146:149], v[186:189], v[124:127]
	v_mfma_f32_16x16x32_bf16 v[120:123], v[154:157], v[186:189], v[120:123]
	v_mfma_f32_16x16x32_bf16 v[104:107], v[154:157], v[194:197], v[104:107]
	v_mfma_f32_16x16x32_bf16 v[108:111], v[146:149], v[194:197], v[108:111]
	v_mfma_f32_16x16x32_bf16 v[92:95], v[146:149], v[202:205], v[92:95]
	v_mfma_f32_16x16x32_bf16 v[88:91], v[154:157], v[202:205], v[88:91]
	v_mfma_f32_16x16x32_bf16 v[72:75], v[154:157], v[210:213], v[72:75]
	v_mfma_f32_16x16x32_bf16 v[76:79], v[146:149], v[210:213], v[76:79]
	s_setprio 0
	s_setprio 1
	v_mfma_f32_16x16x32_bf16 v[116:119], v[158:161], v[182:185], v[116:119]
	v_mfma_f32_16x16x32_bf16 v[112:115], v[166:169], v[182:185], v[112:115]
	v_mfma_f32_16x16x32_bf16 v[96:99], v[166:169], v[190:193], v[96:99]
	v_mfma_f32_16x16x32_bf16 v[100:103], v[158:161], v[190:193], v[100:103]
	v_mfma_f32_16x16x32_bf16 v[84:87], v[158:161], v[198:201], v[84:87]
	v_mfma_f32_16x16x32_bf16 v[80:83], v[166:169], v[198:201], v[80:83]
	v_mfma_f32_16x16x32_bf16 v[64:67], v[166:169], v[206:209], v[64:67]
	v_mfma_f32_16x16x32_bf16 v[68:71], v[158:161], v[206:209], v[68:71]
	v_mfma_f32_16x16x32_bf16 v[116:119], v[162:165], v[186:189], v[116:119]
	v_mfma_f32_16x16x32_bf16 v[112:115], v[170:173], v[186:189], v[112:115]
	v_mfma_f32_16x16x32_bf16 v[96:99], v[170:173], v[194:197], v[96:99]
	v_mfma_f32_16x16x32_bf16 v[100:103], v[162:165], v[194:197], v[100:103]
	v_mfma_f32_16x16x32_bf16 v[84:87], v[162:165], v[202:205], v[84:87]
	v_mfma_f32_16x16x32_bf16 v[80:83], v[170:173], v[202:205], v[80:83]
	v_mfma_f32_16x16x32_bf16 v[64:67], v[170:173], v[210:213], v[64:67]
	v_mfma_f32_16x16x32_bf16 v[68:71], v[162:165], v[210:213], v[68:71]
	s_setprio 0
	s_barrier
; #define PG8_STAGE(bufoff, gbase, voff) do { _Pragma("unroll") for (int _i = 0; _i < 2; ++_i) \
;         __builtin_amdgcn_global_load_lds((const unsigned*)((const char*)(gbase) + (voff)[_i]), (PG8_LAS unsigned*)(lds + (bufoff) + ldsw + _i * 8192), 16, 0, 0); } while (0)
; #define PG8_LDA(dst, b, h) do { _Pragma("unroll") for (int m = 0; m < 4; ++m) _Pragma("unroll") for (int k = 0; k < 2; ++k) dst[m][k] = *(const PG8_LAS bf16x8*)(lds + PG8_SA(b, h) + aoff + m * 2048 + k * 1024); } while (0)
; #define PG8_MMA(ai, bj, At, Bt) do { __builtin_amdgcn_s_setprio(1); _Pragma("unroll") for (int m = 0; m < 4; ++m) _Pragma("unroll") for (int n = 0; n < 2; ++n) _Pragma("unroll") for (int k = 0; k < 2; ++k) \
;         acc[ai][bj][m][n] = __builtin_amdgcn_mfma_f32_16x16x32_bf16(Bt[n][k], At[m][k], acc[ai][bj][m][n], 0, 0, 0); __builtin_amdgcn_s_setprio(0); } while (0)
; #define PG8_WAIT_V(n) asm volatile("s_waitcnt vmcnt(" #n ")" ::: "memory")
; #define PG8_WAIT_L(n) asm volatile("s_waitcnt lgkmcnt(" #n ")" ::: "memory")
; #define PG8_BAR __builtin_amdgcn_s_barrier()
; #define PG8_SCHED __builtin_amdgcn_sched_barrier(0)
; template <class Epi, class Sched, bool ALIGN_EPI = false, bool SP2 = false>
; __device__ __forceinline__ void gemm_phase(PG8_LAS unsigned char* lds, const Gemm g, const Sched& S, const Epi& E) {
;     ...
;             PG8_LDA(At, 1, 1); PG8_STAGE(PG8_SB(1, 0), b3, voffB); PG8_STAGE(PG8_SB(1, 1), b3 + hstep, voffB); PG8_STAGE(PG8_SA(1, 0), a3, voffA);
;             PG8_WAIT_V(8); PG8_WAIT_L(0); PG8_BAR; PG8_MMA(1, 0, At, B0); PG8_MMA(1, 1, At, B1); PG8_BAR; PG8_SCHED;
	s_add_i32 s4, s28, s18
	v_lshl_add_u64 v[174:175], v[174:175], 0, s[44:45]
	s_mov_b32 m0, s4
	ds_read_b128 v[182:185], v141 offset:49152
	ds_read_b128 v[186:189], v141 offset:50176
	ds_read_b128 v[190:193], v141 offset:51200
	ds_read_b128 v[194:197], v141 offset:52224
	ds_read_b128 v[198:201], v141 offset:53248
	ds_read_b128 v[202:205], v141 offset:54272
	ds_read_b128 v[206:209], v141 offset:55296
	ds_read_b128 v[210:213], v141 offset:56320
	global_load_lds_dwordx4 v[174:175], off
	v_lshl_add_u64 v[174:175], v[214:215], 0, s[44:45]
	s_add_i32 m0, s4, 0x2000
	s_add_i32 s4, s38, s18
	global_load_lds_dwordx4 v[174:175], off
	v_lshl_add_u64 v[174:175], v[216:217], 0, s[44:45]
	s_mov_b32 m0, s4
	s_nop 0
	global_load_lds_dwordx4 v[174:175], off
	v_lshl_add_u64 v[174:175], v[218:219], 0, s[44:45]
	s_add_i32 m0, s4, 0x2000
	s_nop 0
	global_load_lds_dwordx4 v[174:175], off
	v_lshl_add_u64 v[174:175], v[220:221], 0, s[44:45]
	s_mov_b32 m0, s43
	s_nop 0
	global_load_lds_dwordx4 v[174:175], off
	v_lshl_add_u64 v[174:175], v[222:223], 0, s[44:45]
	s_mov_b32 m0, s46
	s_nop 0
	global_load_lds_dwordx4 v[174:175], off
	s_waitcnt vmcnt(8)
	s_waitcnt lgkmcnt(0)
	s_barrier
	s_setprio 1
	s_waitcnt lgkmcnt(0)
	v_mfma_f32_16x16x32_bf16 v[60:63], v[142:145], v[182:185], v[60:63]
	v_mfma_f32_16x16x32_bf16 v[56:59], v[150:153], v[182:185], v[56:59]
	v_mfma_f32_16x16x32_bf16 v[40:43], v[150:153], v[190:193], v[40:43]
	v_mfma_f32_16x16x32_bf16 v[44:47], v[142:145], v[190:193], v[44:47]
	v_mfma_f32_16x16x32_bf16 v[28:31], v[142:145], v[198:201], v[28:31]
	v_mfma_f32_16x16x32_bf16 v[24:27], v[150:153], v[198:201], v[24:27]
	v_mfma_f32_16x16x32_bf16 v[8:11], v[150:153], v[206:209], v[8:11]
	v_mfma_f32_16x16x32_bf16 v[12:15], v[142:145], v[206:209], v[12:15]
	v_mfma_f32_16x16x32_bf16 v[60:63], v[146:149], v[186:189], v[60:63]
	v_mfma_f32_16x16x32_bf16 v[56:59], v[154:157], v[186:189], v[56:59]
	v_mfma_f32_16x16x32_bf16 v[40:43], v[154:157], v[194:197], v[40:43]
	v_mfma_f32_16x16x32_bf16 v[44:47], v[146:149], v[194:197], v[44:47]
	v_mfma_f32_16x16x32_bf16 v[28:31], v[146:149], v[202:205], v[28:31]
	v_mfma_f32_16x16x32_bf16 v[24:27], v[154:157], v[202:205], v[24:27]
	v_mfma_f32_16x16x32_bf16 v[8:11], v[154:157], v[210:213], v[8:11]
	v_mfma_f32_16x16x32_bf16 v[12:15], v[146:149], v[210:213], v[12:15]
	s_setprio 0
	s_setprio 1
	v_mfma_f32_16x16x32_bf16 v[52:55], v[158:161], v[182:185], v[52:55]
	v_mfma_f32_16x16x32_bf16 v[48:51], v[166:169], v[182:185], v[48:51]
	v_mfma_f32_16x16x32_bf16 v[36:39], v[158:161], v[190:193], v[36:39]
	v_mfma_f32_16x16x32_bf16 v[32:35], v[166:169], v[190:193], v[32:35]
	v_mfma_f32_16x16x32_bf16 v[20:23], v[158:161], v[198:201], v[20:23]
	v_mfma_f32_16x16x32_bf16 v[16:19], v[166:169], v[198:201], v[16:19]
	v_mfma_f32_16x16x32_bf16 v[4:7], v[158:161], v[206:209], v[4:7]
	v_mfma_f32_16x16x32_bf16 v[0:3], v[166:169], v[206:209], v[0:3]
	v_mfma_f32_16x16x32_bf16 v[52:55], v[162:165], v[186:189], v[52:55]
	v_mfma_f32_16x16x32_bf16 v[48:51], v[170:173], v[186:189], v[48:51]
	s_add_u32 s66, s66, 0x100
	v_mfma_f32_16x16x32_bf16 v[36:39], v[162:165], v[194:197], v[36:39]
	s_addc_u32 s67, s67, 0
	v_mfma_f32_16x16x32_bf16 v[32:35], v[170:173], v[194:197], v[32:35]
	s_add_u32 s68, s68, 0x100
	v_mfma_f32_16x16x32_bf16 v[20:23], v[162:165], v[202:205], v[20:23]
	s_addc_u32 s69, s69, 0
	v_mfma_f32_16x16x32_bf16 v[16:19], v[170:173], v[202:205], v[16:19]
	s_cmp_ge_i32 s81, s31
	v_mfma_f32_16x16x32_bf16 v[4:7], v[162:165], v[210:213], v[4:7]
	s_mov_b32 s4, s81
	v_mfma_f32_16x16x32_bf16 v[0:3], v[170:173], v[210:213], v[0:3]
	s_setprio 0
	s_barrier
	s_cbranch_scc0 .LBB0_592

; #define PG8_STAGE(bufoff, gbase, voff) do { _Pragma("unroll") for (int _i = 0; _i < 2; ++_i) \
;         __builtin_amdgcn_global_load_lds((const unsigned*)((const char*)(gbase) + (voff)[_i]), (PG8_LAS unsigned*)(lds + (bufoff) + ldsw + _i * 8192), 16, 0, 0); } while (0)
; #define PG8_LDA(dst, b, h) do { _Pragma("unroll") for (int m = 0; m < 4; ++m) _Pragma("unroll") for (int k = 0; k < 2; ++k) dst[m][k] = *(const PG8_LAS bf16x8*)(lds + PG8_SA(b, h) + aoff + m * 2048 + k * 1024); } while (0)
; #define PG8_LDB(dst, b, h) do { _Pragma("unroll") for (int n = 0; n < 2; ++n) _Pragma("unroll") for (int k = 0; k < 2; ++k) dst[n][k] = *(const PG8_LAS bf16x8*)(lds + PG8_SB(b, h) + boff + n * 2048 + k * 1024); } while (0)
; #define PG8_WAIT_V(n) asm volatile("s_waitcnt vmcnt(" #n ")" ::: "memory")
; #define PG8_WAIT_L(n) asm volatile("s_waitcnt lgkmcnt(" #n ")" ::: "memory")
; #define PG8_BAR __builtin_amdgcn_s_barrier()
; #define PG8_SCHED __builtin_amdgcn_sched_barrier(0)
; template <class Epi, class Sched, bool ALIGN_EPI = false, bool SP2 = false>
; __device__ __forceinline__ void gemm_phase(PG8_LAS unsigned char* lds, const Gemm g, const Sched& S, const Epi& E) {
;     ...
;         const char* nA = has_next ? (const char*)g.A + (size_t)nxt.pm * tstep + nxt.ko : cA; const char* nB = has_next ? (const char*)g.Bt + (size_t)nxt.pn * tstep + nxt.ko : cB;
;         for (int t = 0; t < nt; t += 2) {
;             const bool last = (t == nt - 2);
;             const char* a1 = cA + (size_t)(t + 1) * kstep;
;             const char* a2 = last ? nA : cA + (size_t)(t + 2) * kstep; const char* b2 = last ? nB : cB + (size_t)(t + 2) * kstep;
;             const char* a3 = a2 + kstep; const char* b3 = b2 + kstep;
;             if (last && has_next) S.a_ready(nxt);
;             if constexpr (SP2) {
;             PG8_LDB(B0, 0, 0); PG8_LDB(B1, 0, 1); PG8_SCHED; PG8_LDA(At, 0, 0); PG8_STAGE(PG8_SA(1, 1), a1 + hstep, voffA);
;             PG8_WAIT_V(8); PG8_WAIT_L(0); PG8_BAR; PG8_MMA(0, 0, At, B0); PG8_MMA(0, 1, At, B1); PG8_BAR; PG8_SCHED;
;             PG8_LDA(At, 0, 1); PG8_STAGE(PG8_SB(0, 0), b2, voffB); PG8_STAGE(PG8_SB(0, 1), b2 + hstep, voffB); PG8_STAGE(PG8_SA(0, 0), a2, voffA);
;             PG8_WAIT_V(8); PG8_WAIT_L(0); PG8_BAR; PG8_MMA(1, 0, At, B0); PG8_MMA(1, 1, At, B1); PG8_BAR; PG8_SCHED;
.LBB0_718:
	s_add_u32 s28, vcc_lo, 0xfffc0080
	s_addc_u32 s38, vcc_hi, -1
	s_add_i32 s39, 0, 0x10000
	s_cmp_eq_u32 s80, 12
	s_cselect_b32 s67, s41, s38
	s_cselect_b32 s66, s76, s28
	v_add_u32_e32 v138, s39, v142
	s_cselect_b32 s65, s37, s79
	s_cselect_b32 s64, s77, s78
	s_add_i32 s28, 0, 0x14000
	ds_read_b128 v[144:147], v138
	ds_read_b128 v[148:151], v138 offset:1024
	ds_read_b128 v[152:155], v138 offset:2048
	ds_read_b128 v[156:159], v138 offset:3072
	v_add_u32_e32 v138, s28, v142
	ds_read_b128 v[160:163], v138
	ds_read_b128 v[164:167], v138 offset:1024
	ds_read_b128 v[168:171], v138 offset:2048
	ds_read_b128 v[172:175], v138 offset:3072
	v_lshl_add_u64 v[138:139], vcc, 0, v[134:135]
	s_add_i32 m0, s30, 0xc000
	ds_read_b128 v[182:185], v143
	ds_read_b128 v[186:189], v143 offset:1024
	ds_read_b128 v[190:193], v143 offset:2048
	ds_read_b128 v[194:197], v143 offset:3072
	ds_read_b128 v[198:201], v143 offset:4096
	ds_read_b128 v[202:205], v143 offset:5120
	ds_read_b128 v[206:209], v143 offset:6144
	ds_read_b128 v[210:213], v143 offset:7168
	global_load_lds_dwordx4 v[138:139], off
	v_lshl_add_u64 v[138:139], vcc, 0, v[136:137]
	s_add_i32 m0, s30, 0xe000
	s_nop 0
	global_load_lds_dwordx4 v[138:139], off
	s_waitcnt vmcnt(8)
	s_waitcnt lgkmcnt(0)
	s_barrier
	s_setprio 1
	s_waitcnt lgkmcnt(0)
	v_mfma_f32_16x16x32_bf16 v[124:127], v[144:147], v[182:185], v[124:127]
	v_mfma_f32_16x16x32_bf16 v[120:123], v[152:155], v[182:185], v[120:123]
	v_mfma_f32_16x16x32_bf16 v[104:107], v[152:155], v[190:193], v[104:107]
	v_mfma_f32_16x16x32_bf16 v[108:111], v[144:147], v[190:193], v[108:111]
	v_mfma_f32_16x16x32_bf16 v[92:95], v[144:147], v[198:201], v[92:95]
	v_mfma_f32_16x16x32_bf16 v[88:91], v[152:155], v[198:201], v[88:91]
	v_mfma_f32_16x16x32_bf16 v[72:75], v[152:155], v[206:209], v[72:75]
	v_mfma_f32_16x16x32_bf16 v[76:79], v[144:147], v[206:209], v[76:79]
	v_mfma_f32_16x16x32_bf16 v[124:127], v[148:151], v[186:189], v[124:127]
	v_mfma_f32_16x16x32_bf16 v[120:123], v[156:159], v[186:189], v[120:123]
	v_mfma_f32_16x16x32_bf16 v[104:107], v[156:159], v[194:197], v[104:107]
	v_mfma_f32_16x16x32_bf16 v[108:111], v[148:151], v[194:197], v[108:111]
	v_mfma_f32_16x16x32_bf16 v[92:95], v[148:151], v[202:205], v[92:95]
	v_mfma_f32_16x16x32_bf16 v[88:91], v[156:159], v[202:205], v[88:91]
	v_mfma_f32_16x16x32_bf16 v[72:75], v[156:159], v[210:213], v[72:75]
	v_mfma_f32_16x16x32_bf16 v[76:79], v[148:151], v[210:213], v[76:79]
	s_setprio 0
	s_setprio 1
	v_mfma_f32_16x16x32_bf16 v[116:119], v[160:163], v[182:185], v[116:119]
	v_mfma_f32_16x16x32_bf16 v[112:115], v[168:171], v[182:185], v[112:115]
	v_mfma_f32_16x16x32_bf16 v[96:99], v[168:171], v[190:193], v[96:99]
	v_mfma_f32_16x16x32_bf16 v[100:103], v[160:163], v[190:193], v[100:103]
	v_mfma_f32_16x16x32_bf16 v[84:87], v[160:163], v[198:201], v[84:87]
	v_mfma_f32_16x16x32_bf16 v[80:83], v[168:171], v[198:201], v[80:83]
	v_mfma_f32_16x16x32_bf16 v[64:67], v[168:171], v[206:209], v[64:67]
	v_mfma_f32_16x16x32_bf16 v[68:71], v[160:163], v[206:209], v[68:71]
	v_mfma_f32_16x16x32_bf16 v[116:119], v[164:167], v[186:189], v[116:119]
	v_mfma_f32_16x16x32_bf16 v[112:115], v[172:175], v[186:189], v[112:115]
	v_mfma_f32_16x16x32_bf16 v[96:99], v[172:175], v[194:197], v[96:99]
	v_mfma_f32_16x16x32_bf16 v[100:103], v[164:167], v[194:197], v[100:103]
	v_mfma_f32_16x16x32_bf16 v[84:87], v[164:167], v[202:205], v[84:87]
	v_mfma_f32_16x16x32_bf16 v[80:83], v[172:175], v[202:205], v[80:83]
	v_mfma_f32_16x16x32_bf16 v[64:67], v[172:175], v[210:213], v[64:67]
	v_mfma_f32_16x16x32_bf16 v[68:71], v[164:167], v[210:213], v[68:71]
	s_setprio 0
	s_barrier
	s_add_i32 s38, s39, s23
	v_lshl_add_u64 v[138:139], s[64:65], 0, v[176:177]
	s_mov_b32 m0, s38
	ds_read_b128 v[182:185], v143 offset:16384
	ds_read_b128 v[186:189], v143 offset:17408
	ds_read_b128 v[190:193], v143 offset:18432
	ds_read_b128 v[194:197], v143 offset:19456
	ds_read_b128 v[198:201], v143 offset:20480
	ds_read_b128 v[202:205], v143 offset:21504
	ds_read_b128 v[206:209], v143 offset:22528
	ds_read_b128 v[210:213], v143 offset:23552
	global_load_lds_dwordx4 v[138:139], off
	s_add_i32 m0, s38, 0x2000
	s_add_u32 s38, s64, 0x40000
	v_lshl_add_u64 v[214:215], s[64:65], 0, v[128:129]
	s_addc_u32 s39, s65, 0
	s_add_i32 s28, s28, s23
	global_load_lds_dwordx4 v[214:215], off
	v_lshl_add_u64 v[216:217], s[38:39], 0, v[176:177]
	s_mov_b32 m0, s28
	v_lshl_add_u64 v[218:219], s[66:67], 0, v[130:131]
	global_load_lds_dwordx4 v[216:217], off
	v_lshl_add_u64 v[216:217], s[38:39], 0, v[128:129]
	s_add_i32 m0, s28, 0x2000
	s_nop 0
	global_load_lds_dwordx4 v[216:217], off
	v_lshl_add_u64 v[216:217], s[66:67], 0, v[132:133]
	s_mov_b32 m0, s30
	s_nop 0
	global_load_lds_dwordx4 v[216:217], off
	s_mov_b32 m0, s31
	s_nop 0
	global_load_lds_dwordx4 v[218:219], off
	s_waitcnt vmcnt(8)
	s_waitcnt lgkmcnt(0)
	s_barrier
; #define PG8_STAGE(bufoff, gbase, voff) do { _Pragma("unroll") for (int _i = 0; _i < 2; ++_i) \
;         __builtin_amdgcn_global_load_lds((const unsigned*)((const char*)(gbase) + (voff)[_i]), (PG8_LAS unsigned*)(lds + (bufoff) + ldsw + _i * 8192), 16, 0, 0); } while (0)
; #define PG8_LDA(dst, b, h) do { _Pragma("unroll") for (int m = 0; m < 4; ++m) _Pragma("unroll") for (int k = 0; k < 2; ++k) dst[m][k] = *(const PG8_LAS bf16x8*)(lds + PG8_SA(b, h) + aoff + m * 2048 + k * 1024); } while (0)
; #define PG8_LDB(dst, b, h) do { _Pragma("unroll") for (int n = 0; n < 2; ++n) _Pragma("unroll") for (int k = 0; k < 2; ++k) dst[n][k] = *(const PG8_LAS bf16x8*)(lds + PG8_SB(b, h) + boff + n * 2048 + k * 1024); } while (0)
; #define PG8_MMA(ai, bj, At, Bt) do { __builtin_amdgcn_s_setprio(1); _Pragma("unroll") for (int m = 0; m < 4; ++m) _Pragma("unroll") for (int n = 0; n < 2; ++n) _Pragma("unroll") for (int k = 0; k < 2; ++k) \
;         acc[ai][bj][m][n] = __builtin_amdgcn_mfma_f32_16x16x32_bf16(Bt[n][k], At[m][k], acc[ai][bj][m][n], 0, 0, 0); __builtin_amdgcn_s_setprio(0); } while (0)
; #define PG8_WAIT_V(n) asm volatile("s_waitcnt vmcnt(" #n ")" ::: "memory")
; #define PG8_WAIT_L(n) asm volatile("s_waitcnt lgkmcnt(" #n ")" ::: "memory")
; #define PG8_BAR __builtin_amdgcn_s_barrier()
; #define PG8_SCHED __builtin_amdgcn_sched_barrier(0)
; template <class Epi, class Sched, bool ALIGN_EPI = false, bool SP2 = false>
; __device__ __forceinline__ void gemm_phase(PG8_LAS unsigned char* lds, const Gemm g, const Sched& S, const Epi& E) {
;     ...
;             PG8_WAIT_V(8); PG8_WAIT_L(0); PG8_BAR; PG8_MMA(1, 0, At, B0); PG8_MMA(1, 1, At, B1); PG8_BAR; PG8_SCHED;
;             PG8_LDB(B0, 1, 0); PG8_LDB(B1, 1, 1); PG8_SCHED; PG8_LDA(At, 1, 0); PG8_STAGE(PG8_SA(0, 1), a2 + hstep, voffA);
;             PG8_WAIT_V(8); PG8_WAIT_L(0); PG8_BAR; PG8_MMA(0, 0, At, B0); PG8_MMA(0, 1, At, B1); PG8_BAR; PG8_SCHED;
;             PG8_LDA(At, 1, 1); PG8_STAGE(PG8_SB(1, 0), b3, voffB); PG8_STAGE(PG8_SB(1, 1), b3 + hstep, voffB); PG8_STAGE(PG8_SA(1, 0), a3, voffA);
	s_setprio 1
	s_waitcnt lgkmcnt(0)
	v_mfma_f32_16x16x32_bf16 v[60:63], v[144:147], v[182:185], v[60:63]
	v_mfma_f32_16x16x32_bf16 v[56:59], v[152:155], v[182:185], v[56:59]
	v_mfma_f32_16x16x32_bf16 v[40:43], v[152:155], v[190:193], v[40:43]
	v_mfma_f32_16x16x32_bf16 v[44:47], v[144:147], v[190:193], v[44:47]
	v_mfma_f32_16x16x32_bf16 v[28:31], v[144:147], v[198:201], v[28:31]
	v_mfma_f32_16x16x32_bf16 v[24:27], v[152:155], v[198:201], v[24:27]
	v_mfma_f32_16x16x32_bf16 v[8:11], v[152:155], v[206:209], v[8:11]
	v_mfma_f32_16x16x32_bf16 v[12:15], v[144:147], v[206:209], v[12:15]
	v_mfma_f32_16x16x32_bf16 v[60:63], v[148:151], v[186:189], v[60:63]
	v_mfma_f32_16x16x32_bf16 v[56:59], v[156:159], v[186:189], v[56:59]
	v_mfma_f32_16x16x32_bf16 v[40:43], v[156:159], v[194:197], v[40:43]
	v_mfma_f32_16x16x32_bf16 v[44:47], v[148:151], v[194:197], v[44:47]
	v_mfma_f32_16x16x32_bf16 v[28:31], v[148:151], v[202:205], v[28:31]
	v_mfma_f32_16x16x32_bf16 v[24:27], v[156:159], v[202:205], v[24:27]
	v_mfma_f32_16x16x32_bf16 v[8:11], v[156:159], v[210:213], v[8:11]
	v_mfma_f32_16x16x32_bf16 v[12:15], v[148:151], v[210:213], v[12:15]
	s_setprio 0
	s_setprio 1
	v_mfma_f32_16x16x32_bf16 v[52:55], v[160:163], v[182:185], v[52:55]
	v_mfma_f32_16x16x32_bf16 v[48:51], v[168:171], v[182:185], v[48:51]
	v_mfma_f32_16x16x32_bf16 v[32:35], v[168:171], v[190:193], v[32:35]
	v_mfma_f32_16x16x32_bf16 v[36:39], v[160:163], v[190:193], v[36:39]
	v_mfma_f32_16x16x32_bf16 v[20:23], v[160:163], v[198:201], v[20:23]
	v_mfma_f32_16x16x32_bf16 v[16:19], v[168:171], v[198:201], v[16:19]
	v_mfma_f32_16x16x32_bf16 v[0:3], v[168:171], v[206:209], v[0:3]
	v_mfma_f32_16x16x32_bf16 v[4:7], v[160:163], v[206:209], v[4:7]
	v_mfma_f32_16x16x32_bf16 v[52:55], v[164:167], v[186:189], v[52:55]
	v_mfma_f32_16x16x32_bf16 v[48:51], v[172:175], v[186:189], v[48:51]
	v_mfma_f32_16x16x32_bf16 v[32:35], v[172:175], v[194:197], v[32:35]
	v_mfma_f32_16x16x32_bf16 v[36:39], v[164:167], v[194:197], v[36:39]
	v_mfma_f32_16x16x32_bf16 v[20:23], v[164:167], v[202:205], v[20:23]
	v_mfma_f32_16x16x32_bf16 v[16:19], v[172:175], v[202:205], v[16:19]
	v_mfma_f32_16x16x32_bf16 v[0:3], v[172:175], v[210:213], v[0:3]
	v_mfma_f32_16x16x32_bf16 v[4:7], v[164:167], v[210:213], v[4:7]
	s_setprio 0
	s_barrier
	s_add_i32 s28, 0, 0x18000
	s_add_i32 s48, 0, 0x1c000
	v_add_u32_e32 v156, s28, v142
	v_add_u32_e32 v172, s48, v142
	ds_read_b128 v[144:147], v156
	ds_read_b128 v[148:151], v156 offset:1024
	ds_read_b128 v[152:155], v156 offset:2048
	ds_read_b128 v[156:159], v156 offset:3072
	ds_read_b128 v[160:163], v172
	ds_read_b128 v[164:167], v172 offset:1024
	ds_read_b128 v[168:171], v172 offset:2048
	ds_read_b128 v[172:175], v172 offset:3072
	s_add_u32 s38, s66, 0x40000
	s_addc_u32 s39, s67, 0
	s_mov_b32 m0, s63
	v_lshl_add_u64 v[220:221], s[38:39], 0, v[132:133]
	ds_read_b128 v[182:185], v143 offset:32768
	ds_read_b128 v[186:189], v143 offset:33792
	ds_read_b128 v[190:193], v143 offset:34816
	ds_read_b128 v[194:197], v143 offset:35840
	ds_read_b128 v[198:201], v143 offset:36864
	ds_read_b128 v[202:205], v143 offset:37888
	ds_read_b128 v[206:209], v143 offset:38912
	ds_read_b128 v[210:213], v143 offset:39936
	global_load_lds_dwordx4 v[220:221], off
	v_lshl_add_u64 v[220:221], s[38:39], 0, v[130:131]
	s_mov_b32 m0, s69
	s_nop 0
	global_load_lds_dwordx4 v[220:221], off
	s_waitcnt vmcnt(8)
	s_waitcnt lgkmcnt(0)
	s_barrier
	s_setprio 1
	s_waitcnt lgkmcnt(0)
	v_mfma_f32_16x16x32_bf16 v[124:127], v[144:147], v[182:185], v[124:127]
	v_mfma_f32_16x16x32_bf16 v[120:123], v[152:155], v[182:185], v[120:123]
	v_mfma_f32_16x16x32_bf16 v[104:107], v[152:155], v[190:193], v[104:107]
	v_mfma_f32_16x16x32_bf16 v[108:111], v[144:147], v[190:193], v[108:111]
	v_mfma_f32_16x16x32_bf16 v[92:95], v[144:147], v[198:201], v[92:95]
	v_mfma_f32_16x16x32_bf16 v[88:91], v[152:155], v[198:201], v[88:91]
	v_mfma_f32_16x16x32_bf16 v[72:75], v[152:155], v[206:209], v[72:75]
	v_mfma_f32_16x16x32_bf16 v[76:79], v[144:147], v[206:209], v[76:79]
	v_mfma_f32_16x16x32_bf16 v[124:127], v[148:151], v[186:189], v[124:127]
	v_mfma_f32_16x16x32_bf16 v[120:123], v[156:159], v[186:189], v[120:123]
	v_mfma_f32_16x16x32_bf16 v[104:107], v[156:159], v[194:197], v[104:107]
	v_mfma_f32_16x16x32_bf16 v[108:111], v[148:151], v[194:197], v[108:111]
	v_mfma_f32_16x16x32_bf16 v[92:95], v[148:151], v[202:205], v[92:95]
	v_mfma_f32_16x16x32_bf16 v[88:91], v[156:159], v[202:205], v[88:91]
	v_mfma_f32_16x16x32_bf16 v[72:75], v[156:159], v[210:213], v[72:75]
	v_mfma_f32_16x16x32_bf16 v[76:79], v[148:151], v[210:213], v[76:79]
	s_setprio 0
	s_setprio 1
	v_mfma_f32_16x16x32_bf16 v[116:119], v[160:163], v[182:185], v[116:119]
	v_mfma_f32_16x16x32_bf16 v[112:115], v[168:171], v[182:185], v[112:115]
	v_mfma_f32_16x16x32_bf16 v[96:99], v[168:171], v[190:193], v[96:99]
	v_mfma_f32_16x16x32_bf16 v[100:103], v[160:163], v[190:193], v[100:103]
	v_mfma_f32_16x16x32_bf16 v[84:87], v[160:163], v[198:201], v[84:87]
	v_mfma_f32_16x16x32_bf16 v[80:83], v[168:171], v[198:201], v[80:83]
	v_mfma_f32_16x16x32_bf16 v[64:67], v[168:171], v[206:209], v[64:67]
	v_mfma_f32_16x16x32_bf16 v[68:71], v[160:163], v[206:209], v[68:71]
	v_mfma_f32_16x16x32_bf16 v[116:119], v[164:167], v[186:189], v[116:119]
	v_mfma_f32_16x16x32_bf16 v[112:115], v[172:175], v[186:189], v[112:115]
	v_mfma_f32_16x16x32_bf16 v[96:99], v[172:175], v[194:197], v[96:99]
	v_mfma_f32_16x16x32_bf16 v[100:103], v[164:167], v[194:197], v[100:103]
	v_mfma_f32_16x16x32_bf16 v[84:87], v[164:167], v[202:205], v[84:87]
	v_mfma_f32_16x16x32_bf16 v[80:83], v[172:175], v[202:205], v[80:83]
	v_mfma_f32_16x16x32_bf16 v[64:67], v[172:175], v[210:213], v[64:67]
	v_mfma_f32_16x16x32_bf16 v[68:71], v[164:167], v[210:213], v[68:71]
	s_setprio 0
	s_barrier
; #define PG8_STAGE(bufoff, gbase, voff) do { _Pragma("unroll") for (int _i = 0; _i < 2; ++_i) \
;         __builtin_amdgcn_global_load_lds((const unsigned*)((const char*)(gbase) + (voff)[_i]), (PG8_LAS unsigned*)(lds + (bufoff) + ldsw + _i * 8192), 16, 0, 0); } while (0)
; #define PG8_LDA(dst, b, h) do { _Pragma("unroll") for (int m = 0; m < 4; ++m) _Pragma("unroll") for (int k = 0; k < 2; ++k) dst[m][k] = *(const PG8_LAS bf16x8*)(lds + PG8_SA(b, h) + aoff + m * 2048 + k * 1024); } while (0)
; #define PG8_MMA(ai, bj, At, Bt) do { __builtin_amdgcn_s_setprio(1); _Pragma("unroll") for (int m = 0; m < 4; ++m) _Pragma("unroll") for (int n = 0; n < 2; ++n) _Pragma("unroll") for (int k = 0; k < 2; ++k) \
;         acc[ai][bj][m][n] = __builtin_amdgcn_mfma_f32_16x16x32_bf16(Bt[n][k], At[m][k], acc[ai][bj][m][n], 0, 0, 0); __builtin_amdgcn_s_setprio(0); } while (0)
; #define PG8_WAIT_V(n) asm volatile("s_waitcnt vmcnt(" #n ")" ::: "memory")
; #define PG8_WAIT_L(n) asm volatile("s_waitcnt lgkmcnt(" #n ")" ::: "memory")
; #define PG8_BAR __builtin_amdgcn_s_barrier()
; #define PG8_SCHED __builtin_amdgcn_sched_barrier(0)
; template <class Epi, class Sched, bool ALIGN_EPI = false, bool SP2 = false>
; __device__ __forceinline__ void gemm_phase(PG8_LAS unsigned char* lds, const Gemm g, const Sched& S, const Epi& E) {
;     ...
;             PG8_LDA(At, 1, 1); PG8_STAGE(PG8_SB(1, 0), b3, voffB); PG8_STAGE(PG8_SB(1, 1), b3 + hstep, voffB); PG8_STAGE(PG8_SA(1, 0), a3, voffA);
;             PG8_WAIT_V(8); PG8_WAIT_L(0); PG8_BAR; PG8_MMA(1, 0, At, B0); PG8_MMA(1, 1, At, B1); PG8_BAR; PG8_SCHED;
	s_add_i32 s28, s28, s23
	v_lshl_add_u64 v[138:139], v[138:139], 0, s[44:45]
	s_mov_b32 m0, s28
	ds_read_b128 v[182:185], v143 offset:49152
	ds_read_b128 v[186:189], v143 offset:50176
	ds_read_b128 v[190:193], v143 offset:51200
	ds_read_b128 v[194:197], v143 offset:52224
	ds_read_b128 v[198:201], v143 offset:53248
	ds_read_b128 v[202:205], v143 offset:54272
	ds_read_b128 v[206:209], v143 offset:55296
	ds_read_b128 v[210:213], v143 offset:56320
	global_load_lds_dwordx4 v[138:139], off
	s_add_i32 m0, s28, 0x2000
	s_add_u32 s38, s64, 0x40080
	v_lshl_add_u64 v[138:139], v[214:215], 0, s[44:45]
	s_addc_u32 s39, s65, 0
	s_add_i32 s28, s48, s23
	global_load_lds_dwordx4 v[138:139], off
	v_lshl_add_u64 v[138:139], s[38:39], 0, v[176:177]
	s_mov_b32 m0, s28
	s_nop 0
	global_load_lds_dwordx4 v[138:139], off
	v_lshl_add_u64 v[138:139], s[38:39], 0, v[128:129]
	s_add_i32 m0, s28, 0x2000
	s_nop 0
	global_load_lds_dwordx4 v[138:139], off
	v_lshl_add_u64 v[138:139], v[216:217], 0, s[44:45]
	s_mov_b32 m0, s73
	s_nop 0
	global_load_lds_dwordx4 v[138:139], off
	v_lshl_add_u64 v[138:139], v[218:219], 0, s[44:45]
	s_mov_b32 m0, s74
	s_nop 0
	global_load_lds_dwordx4 v[138:139], off
	s_waitcnt vmcnt(8)
	s_waitcnt lgkmcnt(0)
	s_barrier
	s_setprio 1
	s_waitcnt lgkmcnt(0)
	v_mfma_f32_16x16x32_bf16 v[60:63], v[144:147], v[182:185], v[60:63]
	v_mfma_f32_16x16x32_bf16 v[56:59], v[152:155], v[182:185], v[56:59]
	v_mfma_f32_16x16x32_bf16 v[40:43], v[152:155], v[190:193], v[40:43]
	v_mfma_f32_16x16x32_bf16 v[44:47], v[144:147], v[190:193], v[44:47]
	v_mfma_f32_16x16x32_bf16 v[28:31], v[144:147], v[198:201], v[28:31]
	v_mfma_f32_16x16x32_bf16 v[24:27], v[152:155], v[198:201], v[24:27]
	v_mfma_f32_16x16x32_bf16 v[8:11], v[152:155], v[206:209], v[8:11]
	v_mfma_f32_16x16x32_bf16 v[12:15], v[144:147], v[206:209], v[12:15]
	v_mfma_f32_16x16x32_bf16 v[60:63], v[148:151], v[186:189], v[60:63]
	v_mfma_f32_16x16x32_bf16 v[56:59], v[156:159], v[186:189], v[56:59]
	v_mfma_f32_16x16x32_bf16 v[40:43], v[156:159], v[194:197], v[40:43]
	v_mfma_f32_16x16x32_bf16 v[44:47], v[148:151], v[194:197], v[44:47]
	v_mfma_f32_16x16x32_bf16 v[28:31], v[148:151], v[202:205], v[28:31]
	v_mfma_f32_16x16x32_bf16 v[24:27], v[156:159], v[202:205], v[24:27]
	v_mfma_f32_16x16x32_bf16 v[8:11], v[156:159], v[210:213], v[8:11]
	v_mfma_f32_16x16x32_bf16 v[12:15], v[148:151], v[210:213], v[12:15]
	s_setprio 0
	s_setprio 1
	v_mfma_f32_16x16x32_bf16 v[52:55], v[160:163], v[182:185], v[52:55]
	v_mfma_f32_16x16x32_bf16 v[48:51], v[168:171], v[182:185], v[48:51]
	v_mfma_f32_16x16x32_bf16 v[36:39], v[160:163], v[190:193], v[36:39]
	v_mfma_f32_16x16x32_bf16 v[32:35], v[168:171], v[190:193], v[32:35]
	v_mfma_f32_16x16x32_bf16 v[20:23], v[160:163], v[198:201], v[20:23]
	v_mfma_f32_16x16x32_bf16 v[16:19], v[168:171], v[198:201], v[16:19]
	v_mfma_f32_16x16x32_bf16 v[4:7], v[160:163], v[206:209], v[4:7]
	v_mfma_f32_16x16x32_bf16 v[0:3], v[168:171], v[206:209], v[0:3]
	v_mfma_f32_16x16x32_bf16 v[52:55], v[164:167], v[186:189], v[52:55]
	v_mfma_f32_16x16x32_bf16 v[48:51], v[172:175], v[186:189], v[48:51]
	s_add_i32 s80, s80, 2
	v_mfma_f32_16x16x32_bf16 v[36:39], v[164:167], v[194:197], v[36:39]
	s_add_u32 vcc_lo, vcc_lo, 0x100
	v_mfma_f32_16x16x32_bf16 v[32:35], v[172:175], v[194:197], v[32:35]
	s_addc_u32 vcc_hi, vcc_hi, 0
	v_mfma_f32_16x16x32_bf16 v[20:23], v[164:167], v[202:205], v[20:23]
	s_add_u32 s78, s78, 0x100
	v_mfma_f32_16x16x32_bf16 v[16:19], v[172:175], v[202:205], v[16:19]
	s_addc_u32 s79, s79, 0
	v_mfma_f32_16x16x32_bf16 v[4:7], v[164:167], v[210:213], v[4:7]
	s_cmp_gt_u32 s80, 13
	v_mfma_f32_16x16x32_bf16 v[0:3], v[172:175], v[210:213], v[0:3]
	s_setprio 0
	s_barrier
	s_cbranch_scc0 .LBB0_718

; #define PG8_STAGE(bufoff, gbase, voff) do { _Pragma("unroll") for (int _i = 0; _i < 2; ++_i) \
;         __builtin_amdgcn_global_load_lds((const unsigned*)((const char*)(gbase) + (voff)[_i]), (PG8_LAS unsigned*)(lds + (bufoff) + ldsw + _i * 8192), 16, 0, 0); } while (0)
; #define PG8_LDA(dst, b, h) do { _Pragma("unroll") for (int m = 0; m < 4; ++m) _Pragma("unroll") for (int k = 0; k < 2; ++k) dst[m][k] = *(const PG8_LAS bf16x8*)(lds + PG8_SA(b, h) + aoff + m * 2048 + k * 1024); } while (0)
; #define PG8_LDB(dst, b, h) do { _Pragma("unroll") for (int n = 0; n < 2; ++n) _Pragma("unroll") for (int k = 0; k < 2; ++k) dst[n][k] = *(const PG8_LAS bf16x8*)(lds + PG8_SB(b, h) + boff + n * 2048 + k * 1024); } while (0)
; #define PG8_MMA(ai, bj, At, Bt) do { __builtin_amdgcn_s_setprio(1); _Pragma("unroll") for (int m = 0; m < 4; ++m) _Pragma("unroll") for (int n = 0; n < 2; ++n) _Pragma("unroll") for (int k = 0; k < 2; ++k) \
;         acc[ai][bj][m][n] = __builtin_amdgcn_mfma_f32_16x16x32_bf16(Bt[n][k], At[m][k], acc[ai][bj][m][n], 0, 0, 0); __builtin_amdgcn_s_setprio(0); } while (0)
; #define PG8_WAIT_V(n) asm volatile("s_waitcnt vmcnt(" #n ")" ::: "memory")
; #define PG8_WAIT_L(n) asm volatile("s_waitcnt lgkmcnt(" #n ")" ::: "memory")
; #define PG8_BAR __builtin_amdgcn_s_barrier()
; #define PG8_SCHED __builtin_amdgcn_sched_barrier(0)
; template <class Epi, class Sched, bool ALIGN_EPI = false, bool SP2 = false>
; __device__ __forceinline__ void gemm_phase(PG8_LAS unsigned char* lds, const Gemm g, const Sched& S, const Epi& E) {
;     ...
;             const char* a2 = last ? nA : cA + (size_t)(t + 2) * kstep; const char* b2 = last ? nB : cB + (size_t)(t + 2) * kstep;
;             const char* a3 = a2 + kstep; const char* b3 = b2 + kstep;
;             if (last && has_next) S.a_ready(nxt);
;             if constexpr (SP2) {
;             PG8_LDB(B0, 0, 0); PG8_LDB(B1, 0, 1); PG8_SCHED; PG8_LDA(At, 0, 0); PG8_STAGE(PG8_SA(1, 1), a1 + hstep, voffA);
;             PG8_WAIT_V(8); PG8_WAIT_L(0); PG8_BAR; PG8_MMA(0, 0, At, B0); PG8_MMA(0, 1, At, B1); PG8_BAR; PG8_SCHED;
;             PG8_LDA(At, 0, 1); PG8_STAGE(PG8_SB(0, 0), b2, voffB); PG8_STAGE(PG8_SB(0, 1), b2 + hstep, voffB); PG8_STAGE(PG8_SA(0, 0), a2, voffA);
;             PG8_WAIT_V(8); PG8_WAIT_L(0); PG8_BAR; PG8_MMA(1, 0, At, B0); PG8_MMA(1, 1, At, B1); PG8_BAR; PG8_SCHED;
.Lg3_peel:
	s_add_u32 s28, vcc_lo, 0xfffc0080
	s_addc_u32 s38, vcc_hi, -1
	s_add_i32 s39, 0, 0x10000
	s_cmp_eq_u32 s80, 12
	s_cselect_b32 s67, s41, s38
	s_cselect_b32 s66, s76, s28
	v_add_u32_e32 v138, s39, v142
	s_cselect_b32 s65, s37, s79
	s_cselect_b32 s64, s77, s78
	s_add_i32 s28, 0, 0x14000
	ds_read_b128 v[144:147], v138
	ds_read_b128 v[148:151], v138 offset:1024
	ds_read_b128 v[152:155], v138 offset:2048
	ds_read_b128 v[156:159], v138 offset:3072
	v_add_u32_e32 v138, s28, v142
	ds_read_b128 v[160:163], v138
	ds_read_b128 v[164:167], v138 offset:1024
	ds_read_b128 v[168:171], v138 offset:2048
	ds_read_b128 v[172:175], v138 offset:3072
	v_lshl_add_u64 v[138:139], vcc, 0, v[134:135]
	s_add_i32 m0, s30, 0xc000
	ds_read_b128 v[182:185], v143
	ds_read_b128 v[186:189], v143 offset:1024
	ds_read_b128 v[190:193], v143 offset:2048
	ds_read_b128 v[194:197], v143 offset:3072
	ds_read_b128 v[198:201], v143 offset:4096
	ds_read_b128 v[202:205], v143 offset:5120
	ds_read_b128 v[206:209], v143 offset:6144
	ds_read_b128 v[210:213], v143 offset:7168
	global_load_lds_dwordx4 v[138:139], off
	v_lshl_add_u64 v[138:139], vcc, 0, v[136:137]
	s_add_i32 m0, s30, 0xe000
	s_nop 0
	global_load_lds_dwordx4 v[138:139], off
	s_waitcnt vmcnt(24)
	s_waitcnt lgkmcnt(0)
	s_barrier
	s_setprio 1
	s_waitcnt lgkmcnt(0)
	v_mfma_f32_16x16x32_bf16 v[124:127], v[144:147], v[182:185], 0
	v_mfma_f32_16x16x32_bf16 v[120:123], v[152:155], v[182:185], 0
	v_mfma_f32_16x16x32_bf16 v[104:107], v[152:155], v[190:193], 0
	v_mfma_f32_16x16x32_bf16 v[108:111], v[144:147], v[190:193], 0
	v_mfma_f32_16x16x32_bf16 v[92:95], v[144:147], v[198:201], 0
	v_mfma_f32_16x16x32_bf16 v[88:91], v[152:155], v[198:201], 0
	v_mfma_f32_16x16x32_bf16 v[72:75], v[152:155], v[206:209], 0
	v_mfma_f32_16x16x32_bf16 v[76:79], v[144:147], v[206:209], 0
	v_mfma_f32_16x16x32_bf16 v[124:127], v[148:151], v[186:189], v[124:127]
	v_mfma_f32_16x16x32_bf16 v[120:123], v[156:159], v[186:189], v[120:123]
	v_mfma_f32_16x16x32_bf16 v[104:107], v[156:159], v[194:197], v[104:107]
	v_mfma_f32_16x16x32_bf16 v[108:111], v[148:151], v[194:197], v[108:111]
	v_mfma_f32_16x16x32_bf16 v[92:95], v[148:151], v[202:205], v[92:95]
	v_mfma_f32_16x16x32_bf16 v[88:91], v[156:159], v[202:205], v[88:91]
	v_mfma_f32_16x16x32_bf16 v[72:75], v[156:159], v[210:213], v[72:75]
	v_mfma_f32_16x16x32_bf16 v[76:79], v[148:151], v[210:213], v[76:79]
	s_setprio 0
	s_setprio 1
	v_mfma_f32_16x16x32_bf16 v[116:119], v[160:163], v[182:185], 0
	v_mfma_f32_16x16x32_bf16 v[112:115], v[168:171], v[182:185], 0
	v_mfma_f32_16x16x32_bf16 v[96:99], v[168:171], v[190:193], 0
	v_mfma_f32_16x16x32_bf16 v[100:103], v[160:163], v[190:193], 0
	v_mfma_f32_16x16x32_bf16 v[84:87], v[160:163], v[198:201], 0
	v_mfma_f32_16x16x32_bf16 v[80:83], v[168:171], v[198:201], 0
	v_mfma_f32_16x16x32_bf16 v[64:67], v[168:171], v[206:209], 0
	v_mfma_f32_16x16x32_bf16 v[68:71], v[160:163], v[206:209], 0
	v_mfma_f32_16x16x32_bf16 v[116:119], v[164:167], v[186:189], v[116:119]
	v_mfma_f32_16x16x32_bf16 v[112:115], v[172:175], v[186:189], v[112:115]
	v_mfma_f32_16x16x32_bf16 v[96:99], v[172:175], v[194:197], v[96:99]
	v_mfma_f32_16x16x32_bf16 v[100:103], v[164:167], v[194:197], v[100:103]
	v_mfma_f32_16x16x32_bf16 v[84:87], v[164:167], v[202:205], v[84:87]
	v_mfma_f32_16x16x32_bf16 v[80:83], v[172:175], v[202:205], v[80:83]
	v_mfma_f32_16x16x32_bf16 v[64:67], v[172:175], v[210:213], v[64:67]
	v_mfma_f32_16x16x32_bf16 v[68:71], v[164:167], v[210:213], v[68:71]
	s_setprio 0
	s_barrier
	s_add_i32 s38, s39, s23
	v_lshl_add_u64 v[138:139], s[64:65], 0, v[176:177]
	s_mov_b32 m0, s38
	ds_read_b128 v[182:185], v143 offset:16384
	ds_read_b128 v[186:189], v143 offset:17408
	ds_read_b128 v[190:193], v143 offset:18432
	ds_read_b128 v[194:197], v143 offset:19456
	ds_read_b128 v[198:201], v143 offset:20480
	ds_read_b128 v[202:205], v143 offset:21504
	ds_read_b128 v[206:209], v143 offset:22528
	ds_read_b128 v[210:213], v143 offset:23552
	global_load_lds_dwordx4 v[138:139], off
	s_add_i32 m0, s38, 0x2000
	s_add_u32 s38, s64, 0x40000
	v_lshl_add_u64 v[214:215], s[64:65], 0, v[128:129]
	s_addc_u32 s39, s65, 0
	s_add_i32 s28, s28, s23
	global_load_lds_dwordx4 v[214:215], off
	v_lshl_add_u64 v[216:217], s[38:39], 0, v[176:177]
	s_mov_b32 m0, s28
	v_lshl_add_u64 v[218:219], s[66:67], 0, v[130:131]
	global_load_lds_dwordx4 v[216:217], off
	v_lshl_add_u64 v[216:217], s[38:39], 0, v[128:129]
	s_add_i32 m0, s28, 0x2000
	s_nop 0
	global_load_lds_dwordx4 v[216:217], off
	v_lshl_add_u64 v[216:217], s[66:67], 0, v[132:133]
	s_mov_b32 m0, s30
	s_nop 0
	global_load_lds_dwordx4 v[216:217], off
	s_mov_b32 m0, s31
	s_nop 0
	global_load_lds_dwordx4 v[218:219], off
	s_waitcnt vmcnt(24)
	s_waitcnt lgkmcnt(0)
	s_barrier
; #define PG8_STAGE(bufoff, gbase, voff) do { _Pragma("unroll") for (int _i = 0; _i < 2; ++_i) \
;         __builtin_amdgcn_global_load_lds((const unsigned*)((const char*)(gbase) + (voff)[_i]), (PG8_LAS unsigned*)(lds + (bufoff) + ldsw + _i * 8192), 16, 0, 0); } while (0)
; #define PG8_LDA(dst, b, h) do { _Pragma("unroll") for (int m = 0; m < 4; ++m) _Pragma("unroll") for (int k = 0; k < 2; ++k) dst[m][k] = *(const PG8_LAS bf16x8*)(lds + PG8_SA(b, h) + aoff + m * 2048 + k * 1024); } while (0)
; #define PG8_LDB(dst, b, h) do { _Pragma("unroll") for (int n = 0; n < 2; ++n) _Pragma("unroll") for (int k = 0; k < 2; ++k) dst[n][k] = *(const PG8_LAS bf16x8*)(lds + PG8_SB(b, h) + boff + n * 2048 + k * 1024); } while (0)
; #define PG8_MMA(ai, bj, At, Bt) do { __builtin_amdgcn_s_setprio(1); _Pragma("unroll") for (int m = 0; m < 4; ++m) _Pragma("unroll") for (int n = 0; n < 2; ++n) _Pragma("unroll") for (int k = 0; k < 2; ++k) \
;         acc[ai][bj][m][n] = __builtin_amdgcn_mfma_f32_16x16x32_bf16(Bt[n][k], At[m][k], acc[ai][bj][m][n], 0, 0, 0); __builtin_amdgcn_s_setprio(0); } while (0)
; #define PG8_WAIT_V(n) asm volatile("s_waitcnt vmcnt(" #n ")" ::: "memory")
; #define PG8_WAIT_L(n) asm volatile("s_waitcnt lgkmcnt(" #n ")" ::: "memory")
; #define PG8_BAR __builtin_amdgcn_s_barrier()
; #define PG8_SCHED __builtin_amdgcn_sched_barrier(0)
; template <class Epi, class Sched, bool ALIGN_EPI = false, bool SP2 = false>
; __device__ __forceinline__ void gemm_phase(PG8_LAS unsigned char* lds, const Gemm g, const Sched& S, const Epi& E) {
;     ...
;             PG8_WAIT_V(8); PG8_WAIT_L(0); PG8_BAR; PG8_MMA(1, 0, At, B0); PG8_MMA(1, 1, At, B1); PG8_BAR; PG8_SCHED;
;             PG8_LDB(B0, 1, 0); PG8_LDB(B1, 1, 1); PG8_SCHED; PG8_LDA(At, 1, 0); PG8_STAGE(PG8_SA(0, 1), a2 + hstep, voffA);
;             PG8_WAIT_V(8); PG8_WAIT_L(0); PG8_BAR; PG8_MMA(0, 0, At, B0); PG8_MMA(0, 1, At, B1); PG8_BAR; PG8_SCHED;
;             PG8_LDA(At, 1, 1); PG8_STAGE(PG8_SB(1, 0), b3, voffB); PG8_STAGE(PG8_SB(1, 1), b3 + hstep, voffB); PG8_STAGE(PG8_SA(1, 0), a3, voffA);
	s_setprio 1
	s_waitcnt lgkmcnt(0)
	v_mfma_f32_16x16x32_bf16 v[60:63], v[144:147], v[182:185], 0
	v_mfma_f32_16x16x32_bf16 v[56:59], v[152:155], v[182:185], 0
	v_mfma_f32_16x16x32_bf16 v[40:43], v[152:155], v[190:193], 0
	v_mfma_f32_16x16x32_bf16 v[44:47], v[144:147], v[190:193], 0
	v_mfma_f32_16x16x32_bf16 v[28:31], v[144:147], v[198:201], 0
	v_mfma_f32_16x16x32_bf16 v[24:27], v[152:155], v[198:201], 0
	v_mfma_f32_16x16x32_bf16 v[8:11], v[152:155], v[206:209], 0
	v_mfma_f32_16x16x32_bf16 v[12:15], v[144:147], v[206:209], 0
	v_mfma_f32_16x16x32_bf16 v[60:63], v[148:151], v[186:189], v[60:63]
	v_mfma_f32_16x16x32_bf16 v[56:59], v[156:159], v[186:189], v[56:59]
	v_mfma_f32_16x16x32_bf16 v[40:43], v[156:159], v[194:197], v[40:43]
	v_mfma_f32_16x16x32_bf16 v[44:47], v[148:151], v[194:197], v[44:47]
	v_mfma_f32_16x16x32_bf16 v[28:31], v[148:151], v[202:205], v[28:31]
	v_mfma_f32_16x16x32_bf16 v[24:27], v[156:159], v[202:205], v[24:27]
	v_mfma_f32_16x16x32_bf16 v[8:11], v[156:159], v[210:213], v[8:11]
	v_mfma_f32_16x16x32_bf16 v[12:15], v[148:151], v[210:213], v[12:15]
	s_setprio 0
	s_setprio 1
	v_mfma_f32_16x16x32_bf16 v[52:55], v[160:163], v[182:185], 0
	v_mfma_f32_16x16x32_bf16 v[48:51], v[168:171], v[182:185], 0
	v_mfma_f32_16x16x32_bf16 v[32:35], v[168:171], v[190:193], 0
	v_mfma_f32_16x16x32_bf16 v[36:39], v[160:163], v[190:193], 0
	v_mfma_f32_16x16x32_bf16 v[20:23], v[160:163], v[198:201], 0
	v_mfma_f32_16x16x32_bf16 v[16:19], v[168:171], v[198:201], 0
	v_mfma_f32_16x16x32_bf16 v[0:3], v[168:171], v[206:209], 0
	v_mfma_f32_16x16x32_bf16 v[4:7], v[160:163], v[206:209], 0
	v_mfma_f32_16x16x32_bf16 v[52:55], v[164:167], v[186:189], v[52:55]
	v_mfma_f32_16x16x32_bf16 v[48:51], v[172:175], v[186:189], v[48:51]
	v_mfma_f32_16x16x32_bf16 v[32:35], v[172:175], v[194:197], v[32:35]
	v_mfma_f32_16x16x32_bf16 v[36:39], v[164:167], v[194:197], v[36:39]
	v_mfma_f32_16x16x32_bf16 v[20:23], v[164:167], v[202:205], v[20:23]
	v_mfma_f32_16x16x32_bf16 v[16:19], v[172:175], v[202:205], v[16:19]
	v_mfma_f32_16x16x32_bf16 v[0:3], v[172:175], v[210:213], v[0:3]
	v_mfma_f32_16x16x32_bf16 v[4:7], v[164:167], v[210:213], v[4:7]
	s_setprio 0
	s_barrier
	s_add_i32 s28, 0, 0x18000
	s_add_i32 s48, 0, 0x1c000
	v_add_u32_e32 v156, s28, v142
	v_add_u32_e32 v172, s48, v142
	ds_read_b128 v[144:147], v156
	ds_read_b128 v[148:151], v156 offset:1024
	ds_read_b128 v[152:155], v156 offset:2048
	ds_read_b128 v[156:159], v156 offset:3072
	ds_read_b128 v[160:163], v172
	ds_read_b128 v[164:167], v172 offset:1024
	ds_read_b128 v[168:171], v172 offset:2048
	ds_read_b128 v[172:175], v172 offset:3072
	s_add_u32 s38, s66, 0x40000
	s_addc_u32 s39, s67, 0
	s_mov_b32 m0, s63
	v_lshl_add_u64 v[220:221], s[38:39], 0, v[132:133]
	ds_read_b128 v[182:185], v143 offset:32768
	ds_read_b128 v[186:189], v143 offset:33792
	ds_read_b128 v[190:193], v143 offset:34816
	ds_read_b128 v[194:197], v143 offset:35840
	ds_read_b128 v[198:201], v143 offset:36864
	ds_read_b128 v[202:205], v143 offset:37888
	ds_read_b128 v[206:209], v143 offset:38912
	ds_read_b128 v[210:213], v143 offset:39936
	global_load_lds_dwordx4 v[220:221], off
	v_lshl_add_u64 v[220:221], s[38:39], 0, v[130:131]
	s_mov_b32 m0, s69
	s_nop 0
	global_load_lds_dwordx4 v[220:221], off
	s_waitcnt vmcnt(8)
	s_waitcnt lgkmcnt(0)
	s_barrier
	s_setprio 1
	s_waitcnt lgkmcnt(0)
	v_mfma_f32_16x16x32_bf16 v[124:127], v[144:147], v[182:185], v[124:127]
	v_mfma_f32_16x16x32_bf16 v[120:123], v[152:155], v[182:185], v[120:123]
	v_mfma_f32_16x16x32_bf16 v[104:107], v[152:155], v[190:193], v[104:107]
	v_mfma_f32_16x16x32_bf16 v[108:111], v[144:147], v[190:193], v[108:111]
	v_mfma_f32_16x16x32_bf16 v[92:95], v[144:147], v[198:201], v[92:95]
	v_mfma_f32_16x16x32_bf16 v[88:91], v[152:155], v[198:201], v[88:91]
	v_mfma_f32_16x16x32_bf16 v[72:75], v[152:155], v[206:209], v[72:75]
	v_mfma_f32_16x16x32_bf16 v[76:79], v[144:147], v[206:209], v[76:79]
	v_mfma_f32_16x16x32_bf16 v[124:127], v[148:151], v[186:189], v[124:127]
	v_mfma_f32_16x16x32_bf16 v[120:123], v[156:159], v[186:189], v[120:123]
	v_mfma_f32_16x16x32_bf16 v[104:107], v[156:159], v[194:197], v[104:107]
	v_mfma_f32_16x16x32_bf16 v[108:111], v[148:151], v[194:197], v[108:111]
	v_mfma_f32_16x16x32_bf16 v[92:95], v[148:151], v[202:205], v[92:95]
	v_mfma_f32_16x16x32_bf16 v[88:91], v[156:159], v[202:205], v[88:91]
	v_mfma_f32_16x16x32_bf16 v[72:75], v[156:159], v[210:213], v[72:75]
	v_mfma_f32_16x16x32_bf16 v[76:79], v[148:151], v[210:213], v[76:79]
	s_setprio 0
	s_setprio 1
	v_mfma_f32_16x16x32_bf16 v[116:119], v[160:163], v[182:185], v[116:119]
	v_mfma_f32_16x16x32_bf16 v[112:115], v[168:171], v[182:185], v[112:115]
	v_mfma_f32_16x16x32_bf16 v[96:99], v[168:171], v[190:193], v[96:99]
	v_mfma_f32_16x16x32_bf16 v[100:103], v[160:163], v[190:193], v[100:103]
	v_mfma_f32_16x16x32_bf16 v[84:87], v[160:163], v[198:201], v[84:87]
	v_mfma_f32_16x16x32_bf16 v[80:83], v[168:171], v[198:201], v[80:83]
	v_mfma_f32_16x16x32_bf16 v[64:67], v[168:171], v[206:209], v[64:67]
	v_mfma_f32_16x16x32_bf16 v[68:71], v[160:163], v[206:209], v[68:71]
	v_mfma_f32_16x16x32_bf16 v[116:119], v[164:167], v[186:189], v[116:119]
	v_mfma_f32_16x16x32_bf16 v[112:115], v[172:175], v[186:189], v[112:115]
	v_mfma_f32_16x16x32_bf16 v[96:99], v[172:175], v[194:197], v[96:99]
	v_mfma_f32_16x16x32_bf16 v[100:103], v[164:167], v[194:197], v[100:103]
	v_mfma_f32_16x16x32_bf16 v[84:87], v[164:167], v[202:205], v[84:87]
	v_mfma_f32_16x16x32_bf16 v[80:83], v[172:175], v[202:205], v[80:83]
	v_mfma_f32_16x16x32_bf16 v[64:67], v[172:175], v[210:213], v[64:67]
	v_mfma_f32_16x16x32_bf16 v[68:71], v[164:167], v[210:213], v[68:71]
	s_setprio 0
	s_barrier
; #define PG8_STAGE(bufoff, gbase, voff) do { _Pragma("unroll") for (int _i = 0; _i < 2; ++_i) \
;         __builtin_amdgcn_global_load_lds((const unsigned*)((const char*)(gbase) + (voff)[_i]), (PG8_LAS unsigned*)(lds + (bufoff) + ldsw + _i * 8192), 16, 0, 0); } while (0)
; #define PG8_LDA(dst, b, h) do { _Pragma("unroll") for (int m = 0; m < 4; ++m) _Pragma("unroll") for (int k = 0; k < 2; ++k) dst[m][k] = *(const PG8_LAS bf16x8*)(lds + PG8_SA(b, h) + aoff + m * 2048 + k * 1024); } while (0)
; #define PG8_MMA(ai, bj, At, Bt) do { __builtin_amdgcn_s_setprio(1); _Pragma("unroll") for (int m = 0; m < 4; ++m) _Pragma("unroll") for (int n = 0; n < 2; ++n) _Pragma("unroll") for (int k = 0; k < 2; ++k) \
;         acc[ai][bj][m][n] = __builtin_amdgcn_mfma_f32_16x16x32_bf16(Bt[n][k], At[m][k], acc[ai][bj][m][n], 0, 0, 0); __builtin_amdgcn_s_setprio(0); } while (0)
; #define PG8_WAIT_V(n) asm volatile("s_waitcnt vmcnt(" #n ")" ::: "memory")
; #define PG8_WAIT_L(n) asm volatile("s_waitcnt lgkmcnt(" #n ")" ::: "memory")
; #define PG8_BAR __builtin_amdgcn_s_barrier()
; #define PG8_SCHED __builtin_amdgcn_sched_barrier(0)
; template <class Epi, class Sched, bool ALIGN_EPI = false, bool SP2 = false>
; __device__ __forceinline__ void gemm_phase(PG8_LAS unsigned char* lds, const Gemm g, const Sched& S, const Epi& E) {
;     ...
;             PG8_LDA(At, 1, 1); PG8_STAGE(PG8_SB(1, 0), b3, voffB); PG8_STAGE(PG8_SB(1, 1), b3 + hstep, voffB); PG8_STAGE(PG8_SA(1, 0), a3, voffA);
;             PG8_WAIT_V(8); PG8_WAIT_L(0); PG8_BAR; PG8_MMA(1, 0, At, B0); PG8_MMA(1, 1, At, B1); PG8_BAR; PG8_SCHED;
	s_add_i32 s28, s28, s23
	v_lshl_add_u64 v[138:139], v[138:139], 0, s[44:45]
	s_mov_b32 m0, s28
	ds_read_b128 v[182:185], v143 offset:49152
	ds_read_b128 v[186:189], v143 offset:50176
	ds_read_b128 v[190:193], v143 offset:51200
	ds_read_b128 v[194:197], v143 offset:52224
	ds_read_b128 v[198:201], v143 offset:53248
	ds_read_b128 v[202:205], v143 offset:54272
	ds_read_b128 v[206:209], v143 offset:55296
	ds_read_b128 v[210:213], v143 offset:56320
	global_load_lds_dwordx4 v[138:139], off
	s_add_i32 m0, s28, 0x2000
	s_add_u32 s38, s64, 0x40080
	v_lshl_add_u64 v[138:139], v[214:215], 0, s[44:45]
	s_addc_u32 s39, s65, 0
	s_add_i32 s28, s48, s23
	global_load_lds_dwordx4 v[138:139], off
	v_lshl_add_u64 v[138:139], s[38:39], 0, v[176:177]
	s_mov_b32 m0, s28
	s_nop 0
	global_load_lds_dwordx4 v[138:139], off
	v_lshl_add_u64 v[138:139], s[38:39], 0, v[128:129]
	s_add_i32 m0, s28, 0x2000
	s_nop 0
	global_load_lds_dwordx4 v[138:139], off
	v_lshl_add_u64 v[138:139], v[216:217], 0, s[44:45]
	s_mov_b32 m0, s73
	s_nop 0
	global_load_lds_dwordx4 v[138:139], off
	v_lshl_add_u64 v[138:139], v[218:219], 0, s[44:45]
	s_mov_b32 m0, s74
	s_nop 0
	global_load_lds_dwordx4 v[138:139], off
	s_waitcnt vmcnt(8)
	s_waitcnt lgkmcnt(0)
	s_barrier
	s_setprio 1
	s_waitcnt lgkmcnt(0)
	v_mfma_f32_16x16x32_bf16 v[60:63], v[144:147], v[182:185], v[60:63]
	v_mfma_f32_16x16x32_bf16 v[56:59], v[152:155], v[182:185], v[56:59]
	v_mfma_f32_16x16x32_bf16 v[40:43], v[152:155], v[190:193], v[40:43]
	v_mfma_f32_16x16x32_bf16 v[44:47], v[144:147], v[190:193], v[44:47]
	v_mfma_f32_16x16x32_bf16 v[28:31], v[144:147], v[198:201], v[28:31]
	v_mfma_f32_16x16x32_bf16 v[24:27], v[152:155], v[198:201], v[24:27]
	v_mfma_f32_16x16x32_bf16 v[8:11], v[152:155], v[206:209], v[8:11]
	v_mfma_f32_16x16x32_bf16 v[12:15], v[144:147], v[206:209], v[12:15]
	v_mfma_f32_16x16x32_bf16 v[60:63], v[148:151], v[186:189], v[60:63]
	v_mfma_f32_16x16x32_bf16 v[56:59], v[156:159], v[186:189], v[56:59]
	v_mfma_f32_16x16x32_bf16 v[40:43], v[156:159], v[194:197], v[40:43]
	v_mfma_f32_16x16x32_bf16 v[44:47], v[148:151], v[194:197], v[44:47]
	v_mfma_f32_16x16x32_bf16 v[28:31], v[148:151], v[202:205], v[28:31]
	v_mfma_f32_16x16x32_bf16 v[24:27], v[156:159], v[202:205], v[24:27]
	v_mfma_f32_16x16x32_bf16 v[8:11], v[156:159], v[210:213], v[8:11]
	v_mfma_f32_16x16x32_bf16 v[12:15], v[148:151], v[210:213], v[12:15]
	s_setprio 0
	s_setprio 1
	v_mfma_f32_16x16x32_bf16 v[52:55], v[160:163], v[182:185], v[52:55]
	v_mfma_f32_16x16x32_bf16 v[48:51], v[168:171], v[182:185], v[48:51]
	v_mfma_f32_16x16x32_bf16 v[36:39], v[160:163], v[190:193], v[36:39]
	v_mfma_f32_16x16x32_bf16 v[32:35], v[168:171], v[190:193], v[32:35]
	v_mfma_f32_16x16x32_bf16 v[20:23], v[160:163], v[198:201], v[20:23]
	v_mfma_f32_16x16x32_bf16 v[16:19], v[168:171], v[198:201], v[16:19]
	v_mfma_f32_16x16x32_bf16 v[4:7], v[160:163], v[206:209], v[4:7]
	v_mfma_f32_16x16x32_bf16 v[0:3], v[168:171], v[206:209], v[0:3]
	v_mfma_f32_16x16x32_bf16 v[52:55], v[164:167], v[186:189], v[52:55]
	v_mfma_f32_16x16x32_bf16 v[48:51], v[172:175], v[186:189], v[48:51]
	s_add_i32 s80, s80, 2
	v_mfma_f32_16x16x32_bf16 v[36:39], v[164:167], v[194:197], v[36:39]
	s_add_u32 vcc_lo, vcc_lo, 0x100
	v_mfma_f32_16x16x32_bf16 v[32:35], v[172:175], v[194:197], v[32:35]
	s_addc_u32 vcc_hi, vcc_hi, 0
	v_mfma_f32_16x16x32_bf16 v[20:23], v[164:167], v[202:205], v[20:23]
	s_add_u32 s78, s78, 0x100
	v_mfma_f32_16x16x32_bf16 v[16:19], v[172:175], v[202:205], v[16:19]
	s_addc_u32 s79, s79, 0
	v_mfma_f32_16x16x32_bf16 v[4:7], v[164:167], v[210:213], v[4:7]
	s_cmp_gt_u32 s80, 13
	v_mfma_f32_16x16x32_bf16 v[0:3], v[172:175], v[210:213], v[0:3]
	s_setprio 0
	s_barrier
	s_cbranch_scc0 .LBB0_718
	s_branch .Lg3_post

; #define PG8_STAGE(bufoff, gbase, voff) do { _Pragma("unroll") for (int _i = 0; _i < 2; ++_i) \
;         __builtin_amdgcn_global_load_lds((const unsigned*)((const char*)(gbase) + (voff)[_i]), (PG8_LAS unsigned*)(lds + (bufoff) + ldsw + _i * 8192), 16, 0, 0); } while (0)
; #define PG8_LDA(dst, b, h) do { _Pragma("unroll") for (int m = 0; m < 4; ++m) _Pragma("unroll") for (int k = 0; k < 2; ++k) dst[m][k] = *(const PG8_LAS bf16x8*)(lds + PG8_SA(b, h) + aoff + m * 2048 + k * 1024); } while (0)
; #define PG8_LDB(dst, b, h) do { _Pragma("unroll") for (int n = 0; n < 2; ++n) _Pragma("unroll") for (int k = 0; k < 2; ++k) dst[n][k] = *(const PG8_LAS bf16x8*)(lds + PG8_SB(b, h) + boff + n * 2048 + k * 1024); } while (0)
; #define PG8_WAIT_V(n) asm volatile("s_waitcnt vmcnt(" #n ")" ::: "memory")
; #define PG8_WAIT_L(n) asm volatile("s_waitcnt lgkmcnt(" #n ")" ::: "memory")
; #define PG8_BAR __builtin_amdgcn_s_barrier()
; #define PG8_SCHED __builtin_amdgcn_sched_barrier(0)
; template <class Epi, class Sched, bool ALIGN_EPI = false, bool SP2 = false>
; __device__ __forceinline__ void gemm_phase(PG8_LAS unsigned char* lds, const Gemm g, const Sched& S, const Epi& E) {
;     ...
;         const char* nA = has_next ? (const char*)g.A + (size_t)nxt.pm * tstep + nxt.ko : cA; const char* nB = has_next ? (const char*)g.Bt + (size_t)nxt.pn * tstep + nxt.ko : cB;
;         for (int t = 0; t < nt; t += 2) {
;             const bool last = (t == nt - 2);
;             const char* a1 = cA + (size_t)(t + 1) * kstep;
;             const char* a2 = last ? nA : cA + (size_t)(t + 2) * kstep; const char* b2 = last ? nB : cB + (size_t)(t + 2) * kstep;
;             const char* a3 = a2 + kstep; const char* b3 = b2 + kstep;
;             if (last && has_next) S.a_ready(nxt);
;             if constexpr (SP2) {
;             PG8_LDB(B0, 0, 0); PG8_LDB(B1, 0, 1); PG8_SCHED; PG8_LDA(At, 0, 0); PG8_STAGE(PG8_SA(1, 1), a1 + hstep, voffA);
;             PG8_WAIT_V(8); PG8_WAIT_L(0); PG8_BAR; PG8_MMA(0, 0, At, B0); PG8_MMA(0, 1, At, B1); PG8_BAR; PG8_SCHED;
;             PG8_LDA(At, 0, 1); PG8_STAGE(PG8_SB(0, 0), b2, voffB); PG8_STAGE(PG8_SB(0, 1), b2 + hstep, voffB); PG8_STAGE(PG8_SA(0, 0), a2, voffA);
;             PG8_WAIT_V(8); PG8_WAIT_L(0); PG8_BAR; PG8_MMA(1, 0, At, B0); PG8_MMA(1, 1, At, B1); PG8_BAR; PG8_SCHED;
.LBB0_790:
	s_add_u32 s4, s64, 0xfff00080
	s_addc_u32 s5, s65, -1
	s_add_i32 s28, 0, 0x10000
	s_cmp_eq_u32 s74, 60
	s_cselect_b32 s7, s35, s5
	s_cselect_b32 s6, s72, s4
	v_add_u32_e32 v138, s28, v142
	s_cselect_b32 s5, s27, s67
	s_cselect_b32 s4, s73, s66
	s_add_i32 s48, 0, 0x14000
	ds_read_b128 v[144:147], v138
	ds_read_b128 v[148:151], v138 offset:1024
	ds_read_b128 v[152:155], v138 offset:2048
	ds_read_b128 v[156:159], v138 offset:3072
	v_add_u32_e32 v138, s48, v142
	ds_read_b128 v[160:163], v138
	ds_read_b128 v[164:167], v138 offset:1024
	ds_read_b128 v[168:171], v138 offset:2048
	ds_read_b128 v[172:175], v138 offset:3072
	v_lshl_add_u64 v[138:139], s[64:65], 0, v[134:135]
	s_add_i32 m0, s23, 0xc000
	ds_read_b128 v[182:185], v143
	ds_read_b128 v[186:189], v143 offset:1024
	ds_read_b128 v[190:193], v143 offset:2048
	ds_read_b128 v[194:197], v143 offset:3072
	ds_read_b128 v[198:201], v143 offset:4096
	ds_read_b128 v[202:205], v143 offset:5120
	ds_read_b128 v[206:209], v143 offset:6144
	ds_read_b128 v[210:213], v143 offset:7168
	global_load_lds_dwordx4 v[138:139], off
	v_lshl_add_u64 v[138:139], s[64:65], 0, v[136:137]
	s_add_i32 m0, s23, 0xe000
	s_nop 0
	global_load_lds_dwordx4 v[138:139], off
	s_waitcnt vmcnt(8)
	s_waitcnt lgkmcnt(0)
	s_barrier
	s_setprio 1
	s_waitcnt lgkmcnt(0)
	v_mfma_f32_16x16x32_bf16 v[124:127], v[144:147], v[182:185], v[124:127]
	v_mfma_f32_16x16x32_bf16 v[120:123], v[152:155], v[182:185], v[120:123]
	v_mfma_f32_16x16x32_bf16 v[108:111], v[152:155], v[190:193], v[108:111]
	v_mfma_f32_16x16x32_bf16 v[116:119], v[144:147], v[190:193], v[116:119]
	v_mfma_f32_16x16x32_bf16 v[100:103], v[144:147], v[198:201], v[100:103]
	v_mfma_f32_16x16x32_bf16 v[92:95], v[152:155], v[198:201], v[92:95]
	v_mfma_f32_16x16x32_bf16 v[76:79], v[152:155], v[206:209], v[76:79]
	v_mfma_f32_16x16x32_bf16 v[84:87], v[144:147], v[206:209], v[84:87]
	v_mfma_f32_16x16x32_bf16 v[124:127], v[148:151], v[186:189], v[124:127]
	v_mfma_f32_16x16x32_bf16 v[120:123], v[156:159], v[186:189], v[120:123]
	v_mfma_f32_16x16x32_bf16 v[108:111], v[156:159], v[194:197], v[108:111]
	v_mfma_f32_16x16x32_bf16 v[116:119], v[148:151], v[194:197], v[116:119]
	v_mfma_f32_16x16x32_bf16 v[100:103], v[148:151], v[202:205], v[100:103]
	v_mfma_f32_16x16x32_bf16 v[92:95], v[156:159], v[202:205], v[92:95]
	v_mfma_f32_16x16x32_bf16 v[76:79], v[156:159], v[210:213], v[76:79]
	v_mfma_f32_16x16x32_bf16 v[84:87], v[148:151], v[210:213], v[84:87]
	s_setprio 0
	s_setprio 1
	v_mfma_f32_16x16x32_bf16 v[112:115], v[160:163], v[182:185], v[112:115]
	v_mfma_f32_16x16x32_bf16 v[104:107], v[168:171], v[182:185], v[104:107]
	v_mfma_f32_16x16x32_bf16 v[88:91], v[168:171], v[190:193], v[88:91]
	v_mfma_f32_16x16x32_bf16 v[96:99], v[160:163], v[190:193], v[96:99]
	v_mfma_f32_16x16x32_bf16 v[80:83], v[160:163], v[198:201], v[80:83]
	v_mfma_f32_16x16x32_bf16 v[72:75], v[168:171], v[198:201], v[72:75]
	v_mfma_f32_16x16x32_bf16 v[64:67], v[168:171], v[206:209], v[64:67]
	v_mfma_f32_16x16x32_bf16 v[68:71], v[160:163], v[206:209], v[68:71]
	v_mfma_f32_16x16x32_bf16 v[112:115], v[164:167], v[186:189], v[112:115]
	v_mfma_f32_16x16x32_bf16 v[104:107], v[172:175], v[186:189], v[104:107]
	v_mfma_f32_16x16x32_bf16 v[88:91], v[172:175], v[194:197], v[88:91]
	v_mfma_f32_16x16x32_bf16 v[96:99], v[164:167], v[194:197], v[96:99]
	v_mfma_f32_16x16x32_bf16 v[80:83], v[164:167], v[202:205], v[80:83]
	v_mfma_f32_16x16x32_bf16 v[72:75], v[172:175], v[202:205], v[72:75]
	v_mfma_f32_16x16x32_bf16 v[64:67], v[172:175], v[210:213], v[64:67]
	v_mfma_f32_16x16x32_bf16 v[68:71], v[164:167], v[210:213], v[68:71]
	s_setprio 0
	s_barrier
	s_add_i32 s28, s28, s22
	v_lshl_add_u64 v[138:139], s[4:5], 0, v[176:177]
	s_mov_b32 m0, s28
	ds_read_b128 v[182:185], v143 offset:16384
	ds_read_b128 v[186:189], v143 offset:17408
	ds_read_b128 v[190:193], v143 offset:18432
	ds_read_b128 v[194:197], v143 offset:19456
	ds_read_b128 v[198:201], v143 offset:20480
	ds_read_b128 v[202:205], v143 offset:21504
	ds_read_b128 v[206:209], v143 offset:22528
	ds_read_b128 v[210:213], v143 offset:23552
	global_load_lds_dwordx4 v[138:139], off
	s_add_i32 m0, s28, 0x2000
	s_add_u32 s38, s4, 0x100000
	v_lshl_add_u64 v[214:215], s[4:5], 0, v[128:129]
	s_addc_u32 s39, s5, 0
	s_add_i32 s28, s48, s22
	global_load_lds_dwordx4 v[214:215], off
	v_lshl_add_u64 v[216:217], s[38:39], 0, v[176:177]
	s_mov_b32 m0, s28
	v_lshl_add_u64 v[218:219], s[6:7], 0, v[130:131]
	global_load_lds_dwordx4 v[216:217], off
	v_lshl_add_u64 v[216:217], s[38:39], 0, v[128:129]
	s_add_i32 m0, s28, 0x2000
	s_nop 0
	global_load_lds_dwordx4 v[216:217], off
	v_lshl_add_u64 v[216:217], s[6:7], 0, v[132:133]
	s_mov_b32 m0, s23
	s_nop 0
	global_load_lds_dwordx4 v[216:217], off
	s_mov_b32 m0, s24
	s_nop 0
	global_load_lds_dwordx4 v[218:219], off
	s_waitcnt vmcnt(8)
	s_waitcnt lgkmcnt(0)
	s_barrier
; #define PG8_STAGE(bufoff, gbase, voff) do { _Pragma("unroll") for (int _i = 0; _i < 2; ++_i) \
;         __builtin_amdgcn_global_load_lds((const unsigned*)((const char*)(gbase) + (voff)[_i]), (PG8_LAS unsigned*)(lds + (bufoff) + ldsw + _i * 8192), 16, 0, 0); } while (0)
; #define PG8_LDA(dst, b, h) do { _Pragma("unroll") for (int m = 0; m < 4; ++m) _Pragma("unroll") for (int k = 0; k < 2; ++k) dst[m][k] = *(const PG8_LAS bf16x8*)(lds + PG8_SA(b, h) + aoff + m * 2048 + k * 1024); } while (0)
; #define PG8_LDB(dst, b, h) do { _Pragma("unroll") for (int n = 0; n < 2; ++n) _Pragma("unroll") for (int k = 0; k < 2; ++k) dst[n][k] = *(const PG8_LAS bf16x8*)(lds + PG8_SB(b, h) + boff + n * 2048 + k * 1024); } while (0)
; #define PG8_MMA(ai, bj, At, Bt) do { __builtin_amdgcn_s_setprio(1); _Pragma("unroll") for (int m = 0; m < 4; ++m) _Pragma("unroll") for (int n = 0; n < 2; ++n) _Pragma("unroll") for (int k = 0; k < 2; ++k) \
;         acc[ai][bj][m][n] = __builtin_amdgcn_mfma_f32_16x16x32_bf16(Bt[n][k], At[m][k], acc[ai][bj][m][n], 0, 0, 0); __builtin_amdgcn_s_setprio(0); } while (0)
; #define PG8_WAIT_V(n) asm volatile("s_waitcnt vmcnt(" #n ")" ::: "memory")
; #define PG8_WAIT_L(n) asm volatile("s_waitcnt lgkmcnt(" #n ")" ::: "memory")
; #define PG8_BAR __builtin_amdgcn_s_barrier()
; #define PG8_SCHED __builtin_amdgcn_sched_barrier(0)
; template <class Epi, class Sched, bool ALIGN_EPI = false, bool SP2 = false>
; __device__ __forceinline__ void gemm_phase(PG8_LAS unsigned char* lds, const Gemm g, const Sched& S, const Epi& E) {
;     ...
;             PG8_WAIT_V(8); PG8_WAIT_L(0); PG8_BAR; PG8_MMA(1, 0, At, B0); PG8_MMA(1, 1, At, B1); PG8_BAR; PG8_SCHED;
;             PG8_LDB(B0, 1, 0); PG8_LDB(B1, 1, 1); PG8_SCHED; PG8_LDA(At, 1, 0); PG8_STAGE(PG8_SA(0, 1), a2 + hstep, voffA);
;             PG8_WAIT_V(8); PG8_WAIT_L(0); PG8_BAR; PG8_MMA(0, 0, At, B0); PG8_MMA(0, 1, At, B1); PG8_BAR; PG8_SCHED;
	s_setprio 1
	s_waitcnt lgkmcnt(0)
	v_mfma_f32_16x16x32_bf16 v[60:63], v[144:147], v[182:185], v[60:63]
	v_mfma_f32_16x16x32_bf16 v[56:59], v[152:155], v[182:185], v[56:59]
	v_mfma_f32_16x16x32_bf16 v[44:47], v[152:155], v[190:193], v[44:47]
	v_mfma_f32_16x16x32_bf16 v[52:55], v[144:147], v[190:193], v[52:55]
	v_mfma_f32_16x16x32_bf16 v[36:39], v[144:147], v[198:201], v[36:39]
	v_mfma_f32_16x16x32_bf16 v[28:31], v[152:155], v[198:201], v[28:31]
	v_mfma_f32_16x16x32_bf16 v[12:15], v[152:155], v[206:209], v[12:15]
	v_mfma_f32_16x16x32_bf16 v[20:23], v[144:147], v[206:209], v[20:23]
	v_mfma_f32_16x16x32_bf16 v[60:63], v[148:151], v[186:189], v[60:63]
	v_mfma_f32_16x16x32_bf16 v[56:59], v[156:159], v[186:189], v[56:59]
	v_mfma_f32_16x16x32_bf16 v[44:47], v[156:159], v[194:197], v[44:47]
	v_mfma_f32_16x16x32_bf16 v[52:55], v[148:151], v[194:197], v[52:55]
	v_mfma_f32_16x16x32_bf16 v[36:39], v[148:151], v[202:205], v[36:39]
	v_mfma_f32_16x16x32_bf16 v[28:31], v[156:159], v[202:205], v[28:31]
	v_mfma_f32_16x16x32_bf16 v[12:15], v[156:159], v[210:213], v[12:15]
	v_mfma_f32_16x16x32_bf16 v[20:23], v[148:151], v[210:213], v[20:23]
	s_setprio 0
	s_setprio 1
	v_mfma_f32_16x16x32_bf16 v[48:51], v[160:163], v[182:185], v[48:51]
	v_mfma_f32_16x16x32_bf16 v[40:43], v[168:171], v[182:185], v[40:43]
	v_mfma_f32_16x16x32_bf16 v[24:27], v[168:171], v[190:193], v[24:27]
	v_mfma_f32_16x16x32_bf16 v[32:35], v[160:163], v[190:193], v[32:35]
	v_mfma_f32_16x16x32_bf16 v[16:19], v[160:163], v[198:201], v[16:19]
	v_mfma_f32_16x16x32_bf16 v[8:11], v[168:171], v[198:201], v[8:11]
	v_mfma_f32_16x16x32_bf16 v[0:3], v[168:171], v[206:209], v[0:3]
	v_mfma_f32_16x16x32_bf16 v[4:7], v[160:163], v[206:209], v[4:7]
	v_mfma_f32_16x16x32_bf16 v[48:51], v[164:167], v[186:189], v[48:51]
	v_mfma_f32_16x16x32_bf16 v[40:43], v[172:175], v[186:189], v[40:43]
	v_mfma_f32_16x16x32_bf16 v[24:27], v[172:175], v[194:197], v[24:27]
	v_mfma_f32_16x16x32_bf16 v[32:35], v[164:167], v[194:197], v[32:35]
	v_mfma_f32_16x16x32_bf16 v[16:19], v[164:167], v[202:205], v[16:19]
	v_mfma_f32_16x16x32_bf16 v[8:11], v[172:175], v[202:205], v[8:11]
	v_mfma_f32_16x16x32_bf16 v[0:3], v[172:175], v[210:213], v[0:3]
	v_mfma_f32_16x16x32_bf16 v[4:7], v[164:167], v[210:213], v[4:7]
	s_setprio 0
	s_barrier
	s_add_i32 s28, 0, 0x18000
	s_add_i32 s38, 0, 0x1c000
	v_add_u32_e32 v156, s28, v142
	v_add_u32_e32 v172, s38, v142
	ds_read_b128 v[144:147], v156
	ds_read_b128 v[148:151], v156 offset:1024
	ds_read_b128 v[152:155], v156 offset:2048
	ds_read_b128 v[156:159], v156 offset:3072
	ds_read_b128 v[160:163], v172
	ds_read_b128 v[164:167], v172 offset:1024
	ds_read_b128 v[168:171], v172 offset:2048
	ds_read_b128 v[172:175], v172 offset:3072
	s_add_u32 s6, s6, 0x100000
	s_addc_u32 s7, s7, 0
	s_mov_b32 m0, s25
	v_lshl_add_u64 v[220:221], s[6:7], 0, v[132:133]
	ds_read_b128 v[182:185], v143 offset:32768
	ds_read_b128 v[186:189], v143 offset:33792
	ds_read_b128 v[190:193], v143 offset:34816
	ds_read_b128 v[194:197], v143 offset:35840
	ds_read_b128 v[198:201], v143 offset:36864
	ds_read_b128 v[202:205], v143 offset:37888
	ds_read_b128 v[206:209], v143 offset:38912
	ds_read_b128 v[210:213], v143 offset:39936
	global_load_lds_dwordx4 v[220:221], off
	v_lshl_add_u64 v[220:221], s[6:7], 0, v[130:131]
	s_mov_b32 m0, s30
	s_nop 0
	global_load_lds_dwordx4 v[220:221], off
	s_waitcnt vmcnt(8)
	s_waitcnt lgkmcnt(0)
	s_barrier
	s_setprio 1
	s_waitcnt lgkmcnt(0)
	v_mfma_f32_16x16x32_bf16 v[124:127], v[144:147], v[182:185], v[124:127]
	v_mfma_f32_16x16x32_bf16 v[120:123], v[152:155], v[182:185], v[120:123]
	v_mfma_f32_16x16x32_bf16 v[108:111], v[152:155], v[190:193], v[108:111]
	v_mfma_f32_16x16x32_bf16 v[116:119], v[144:147], v[190:193], v[116:119]
	v_mfma_f32_16x16x32_bf16 v[100:103], v[144:147], v[198:201], v[100:103]
	v_mfma_f32_16x16x32_bf16 v[92:95], v[152:155], v[198:201], v[92:95]
	v_mfma_f32_16x16x32_bf16 v[76:79], v[152:155], v[206:209], v[76:79]
	v_mfma_f32_16x16x32_bf16 v[84:87], v[144:147], v[206:209], v[84:87]
	v_mfma_f32_16x16x32_bf16 v[124:127], v[148:151], v[186:189], v[124:127]
	v_mfma_f32_16x16x32_bf16 v[120:123], v[156:159], v[186:189], v[120:123]
	v_mfma_f32_16x16x32_bf16 v[108:111], v[156:159], v[194:197], v[108:111]
	v_mfma_f32_16x16x32_bf16 v[116:119], v[148:151], v[194:197], v[116:119]
	v_mfma_f32_16x16x32_bf16 v[100:103], v[148:151], v[202:205], v[100:103]
	v_mfma_f32_16x16x32_bf16 v[92:95], v[156:159], v[202:205], v[92:95]
	v_mfma_f32_16x16x32_bf16 v[76:79], v[156:159], v[210:213], v[76:79]
	v_mfma_f32_16x16x32_bf16 v[84:87], v[148:151], v[210:213], v[84:87]
	s_setprio 0
	s_setprio 1
	v_mfma_f32_16x16x32_bf16 v[112:115], v[160:163], v[182:185], v[112:115]
	v_mfma_f32_16x16x32_bf16 v[104:107], v[168:171], v[182:185], v[104:107]
	v_mfma_f32_16x16x32_bf16 v[88:91], v[168:171], v[190:193], v[88:91]
	v_mfma_f32_16x16x32_bf16 v[96:99], v[160:163], v[190:193], v[96:99]
	v_mfma_f32_16x16x32_bf16 v[80:83], v[160:163], v[198:201], v[80:83]
	v_mfma_f32_16x16x32_bf16 v[72:75], v[168:171], v[198:201], v[72:75]
	v_mfma_f32_16x16x32_bf16 v[64:67], v[168:171], v[206:209], v[64:67]
	v_mfma_f32_16x16x32_bf16 v[68:71], v[160:163], v[206:209], v[68:71]
	v_mfma_f32_16x16x32_bf16 v[112:115], v[164:167], v[186:189], v[112:115]
	v_mfma_f32_16x16x32_bf16 v[104:107], v[172:175], v[186:189], v[104:107]
	v_mfma_f32_16x16x32_bf16 v[88:91], v[172:175], v[194:197], v[88:91]
	v_mfma_f32_16x16x32_bf16 v[96:99], v[164:167], v[194:197], v[96:99]
	v_mfma_f32_16x16x32_bf16 v[80:83], v[164:167], v[202:205], v[80:83]
	v_mfma_f32_16x16x32_bf16 v[72:75], v[172:175], v[202:205], v[72:75]
	v_mfma_f32_16x16x32_bf16 v[64:67], v[172:175], v[210:213], v[64:67]
	v_mfma_f32_16x16x32_bf16 v[68:71], v[164:167], v[210:213], v[68:71]
	s_setprio 0
	s_barrier
; #define PG8_STAGE(bufoff, gbase, voff) do { _Pragma("unroll") for (int _i = 0; _i < 2; ++_i) \
;         __builtin_amdgcn_global_load_lds((const unsigned*)((const char*)(gbase) + (voff)[_i]), (PG8_LAS unsigned*)(lds + (bufoff) + ldsw + _i * 8192), 16, 0, 0); } while (0)
; #define PG8_LDA(dst, b, h) do { _Pragma("unroll") for (int m = 0; m < 4; ++m) _Pragma("unroll") for (int k = 0; k < 2; ++k) dst[m][k] = *(const PG8_LAS bf16x8*)(lds + PG8_SA(b, h) + aoff + m * 2048 + k * 1024); } while (0)
; #define PG8_MMA(ai, bj, At, Bt) do { __builtin_amdgcn_s_setprio(1); _Pragma("unroll") for (int m = 0; m < 4; ++m) _Pragma("unroll") for (int n = 0; n < 2; ++n) _Pragma("unroll") for (int k = 0; k < 2; ++k) \
;         acc[ai][bj][m][n] = __builtin_amdgcn_mfma_f32_16x16x32_bf16(Bt[n][k], At[m][k], acc[ai][bj][m][n], 0, 0, 0); __builtin_amdgcn_s_setprio(0); } while (0)
; #define PG8_WAIT_V(n) asm volatile("s_waitcnt vmcnt(" #n ")" ::: "memory")
; #define PG8_WAIT_L(n) asm volatile("s_waitcnt lgkmcnt(" #n ")" ::: "memory")
; #define PG8_BAR __builtin_amdgcn_s_barrier()
; #define PG8_SCHED __builtin_amdgcn_sched_barrier(0)
; template <class Epi, class Sched, bool ALIGN_EPI = false, bool SP2 = false>
; __device__ __forceinline__ void gemm_phase(PG8_LAS unsigned char* lds, const Gemm g, const Sched& S, const Epi& E) {
;     ...
;         for (int t = 0; t < nt; t += 2) {
;     ...
;             PG8_LDA(At, 1, 1); PG8_STAGE(PG8_SB(1, 0), b3, voffB); PG8_STAGE(PG8_SB(1, 1), b3 + hstep, voffB); PG8_STAGE(PG8_SA(1, 0), a3, voffA);
;             PG8_WAIT_V(8); PG8_WAIT_L(0); PG8_BAR; PG8_MMA(1, 0, At, B0); PG8_MMA(1, 1, At, B1); PG8_BAR; PG8_SCHED;
	s_add_i32 s6, s28, s22
	v_lshl_add_u64 v[138:139], v[138:139], 0, s[44:45]
	s_mov_b32 m0, s6
	ds_read_b128 v[182:185], v143 offset:49152
	ds_read_b128 v[186:189], v143 offset:50176
	ds_read_b128 v[190:193], v143 offset:51200
	ds_read_b128 v[194:197], v143 offset:52224
	ds_read_b128 v[198:201], v143 offset:53248
	ds_read_b128 v[202:205], v143 offset:54272
	ds_read_b128 v[206:209], v143 offset:55296
	ds_read_b128 v[210:213], v143 offset:56320
	global_load_lds_dwordx4 v[138:139], off
	s_add_i32 m0, s6, 0x2000
	s_add_u32 s4, s4, 0x100080
	v_lshl_add_u64 v[138:139], v[214:215], 0, s[44:45]
	s_addc_u32 s5, s5, 0
	s_add_i32 s6, s38, s22
	global_load_lds_dwordx4 v[138:139], off
	v_lshl_add_u64 v[138:139], s[4:5], 0, v[176:177]
	s_mov_b32 m0, s6
	s_nop 0
	global_load_lds_dwordx4 v[138:139], off
	v_lshl_add_u64 v[138:139], s[4:5], 0, v[128:129]
	s_add_i32 m0, s6, 0x2000
	s_nop 0
	global_load_lds_dwordx4 v[138:139], off
	v_lshl_add_u64 v[138:139], v[216:217], 0, s[44:45]
	s_mov_b32 m0, s63
	s_nop 0
	global_load_lds_dwordx4 v[138:139], off
	v_lshl_add_u64 v[138:139], v[218:219], 0, s[44:45]
	s_mov_b32 m0, s68
	s_nop 0
	global_load_lds_dwordx4 v[138:139], off
	s_waitcnt vmcnt(8)
	s_waitcnt lgkmcnt(0)
	s_barrier
	s_setprio 1
	s_waitcnt lgkmcnt(0)
	v_mfma_f32_16x16x32_bf16 v[60:63], v[144:147], v[182:185], v[60:63]
	v_mfma_f32_16x16x32_bf16 v[56:59], v[152:155], v[182:185], v[56:59]
	v_mfma_f32_16x16x32_bf16 v[44:47], v[152:155], v[190:193], v[44:47]
	v_mfma_f32_16x16x32_bf16 v[52:55], v[144:147], v[190:193], v[52:55]
	v_mfma_f32_16x16x32_bf16 v[36:39], v[144:147], v[198:201], v[36:39]
	v_mfma_f32_16x16x32_bf16 v[28:31], v[152:155], v[198:201], v[28:31]
	v_mfma_f32_16x16x32_bf16 v[12:15], v[152:155], v[206:209], v[12:15]
	v_mfma_f32_16x16x32_bf16 v[20:23], v[144:147], v[206:209], v[20:23]
	v_mfma_f32_16x16x32_bf16 v[60:63], v[148:151], v[186:189], v[60:63]
	v_mfma_f32_16x16x32_bf16 v[56:59], v[156:159], v[186:189], v[56:59]
	v_mfma_f32_16x16x32_bf16 v[44:47], v[156:159], v[194:197], v[44:47]
	v_mfma_f32_16x16x32_bf16 v[52:55], v[148:151], v[194:197], v[52:55]
	v_mfma_f32_16x16x32_bf16 v[36:39], v[148:151], v[202:205], v[36:39]
	v_mfma_f32_16x16x32_bf16 v[28:31], v[156:159], v[202:205], v[28:31]
	v_mfma_f32_16x16x32_bf16 v[12:15], v[156:159], v[210:213], v[12:15]
	v_mfma_f32_16x16x32_bf16 v[20:23], v[148:151], v[210:213], v[20:23]
	s_setprio 0
	s_setprio 1
	v_mfma_f32_16x16x32_bf16 v[48:51], v[160:163], v[182:185], v[48:51]
	v_mfma_f32_16x16x32_bf16 v[40:43], v[168:171], v[182:185], v[40:43]
	v_mfma_f32_16x16x32_bf16 v[32:35], v[160:163], v[190:193], v[32:35]
	v_mfma_f32_16x16x32_bf16 v[24:27], v[168:171], v[190:193], v[24:27]
	v_mfma_f32_16x16x32_bf16 v[16:19], v[160:163], v[198:201], v[16:19]
	v_mfma_f32_16x16x32_bf16 v[8:11], v[168:171], v[198:201], v[8:11]
	v_mfma_f32_16x16x32_bf16 v[4:7], v[160:163], v[206:209], v[4:7]
	v_mfma_f32_16x16x32_bf16 v[0:3], v[168:171], v[206:209], v[0:3]
	v_mfma_f32_16x16x32_bf16 v[48:51], v[164:167], v[186:189], v[48:51]
	v_mfma_f32_16x16x32_bf16 v[40:43], v[172:175], v[186:189], v[40:43]
	s_add_i32 s74, s74, 2
	v_mfma_f32_16x16x32_bf16 v[32:35], v[164:167], v[194:197], v[32:35]
	s_add_u32 s64, s64, 0x100
	v_mfma_f32_16x16x32_bf16 v[24:27], v[172:175], v[194:197], v[24:27]
	s_addc_u32 s65, s65, 0
	v_mfma_f32_16x16x32_bf16 v[16:19], v[164:167], v[202:205], v[16:19]
	s_add_u32 s66, s66, 0x100
	v_mfma_f32_16x16x32_bf16 v[8:11], v[172:175], v[202:205], v[8:11]
	s_addc_u32 s67, s67, 0
	v_mfma_f32_16x16x32_bf16 v[4:7], v[164:167], v[210:213], v[4:7]
	s_cmp_gt_u32 s74, 61
	v_mfma_f32_16x16x32_bf16 v[0:3], v[172:175], v[210:213], v[0:3]
	s_setprio 0
	s_barrier
	s_cbranch_scc0 .LBB0_790

; #define PG8_STAGE(bufoff, gbase, voff) do { _Pragma("unroll") for (int _i = 0; _i < 2; ++_i) \
;         __builtin_amdgcn_global_load_lds((const unsigned*)((const char*)(gbase) + (voff)[_i]), (PG8_LAS unsigned*)(lds + (bufoff) + ldsw + _i * 8192), 16, 0, 0); } while (0)
; #define PG8_LDA(dst, b, h) do { _Pragma("unroll") for (int m = 0; m < 4; ++m) _Pragma("unroll") for (int k = 0; k < 2; ++k) dst[m][k] = *(const PG8_LAS bf16x8*)(lds + PG8_SA(b, h) + aoff + m * 2048 + k * 1024); } while (0)
; #define PG8_LDB(dst, b, h) do { _Pragma("unroll") for (int n = 0; n < 2; ++n) _Pragma("unroll") for (int k = 0; k < 2; ++k) dst[n][k] = *(const PG8_LAS bf16x8*)(lds + PG8_SB(b, h) + boff + n * 2048 + k * 1024); } while (0)
; #define PG8_MMA(ai, bj, At, Bt) do { __builtin_amdgcn_s_setprio(1); _Pragma("unroll") for (int m = 0; m < 4; ++m) _Pragma("unroll") for (int n = 0; n < 2; ++n) _Pragma("unroll") for (int k = 0; k < 2; ++k) \
;         acc[ai][bj][m][n] = __builtin_amdgcn_mfma_f32_16x16x32_bf16(Bt[n][k], At[m][k], acc[ai][bj][m][n], 0, 0, 0); __builtin_amdgcn_s_setprio(0); } while (0)
; #define PG8_WAIT_V(n) asm volatile("s_waitcnt vmcnt(" #n ")" ::: "memory")
; #define PG8_WAIT_L(n) asm volatile("s_waitcnt lgkmcnt(" #n ")" ::: "memory")
; #define PG8_BAR __builtin_amdgcn_s_barrier()
; #define PG8_SCHED __builtin_amdgcn_sched_barrier(0)
; template <class Epi, class Sched, bool ALIGN_EPI = false, bool SP2 = false>
; __device__ __forceinline__ void gemm_phase(PG8_LAS unsigned char* lds, const Gemm g, const Sched& S, const Epi& E) {
;     ...
;             const bool last = (t == nt - 2);
;             const char* a1 = cA + (size_t)(t + 1) * kstep;
;             const char* a2 = last ? nA : cA + (size_t)(t + 2) * kstep; const char* b2 = last ? nB : cB + (size_t)(t + 2) * kstep;
;             const char* a3 = a2 + kstep; const char* b3 = b2 + kstep;
;             if (last && has_next) S.a_ready(nxt);
;             if constexpr (SP2) {
;             PG8_LDB(B0, 0, 0); PG8_LDB(B1, 0, 1); PG8_SCHED; PG8_LDA(At, 0, 0); PG8_STAGE(PG8_SA(1, 1), a1 + hstep, voffA);
;             PG8_WAIT_V(8); PG8_WAIT_L(0); PG8_BAR; PG8_MMA(0, 0, At, B0); PG8_MMA(0, 1, At, B1); PG8_BAR; PG8_SCHED;
;             PG8_LDA(At, 0, 1); PG8_STAGE(PG8_SB(0, 0), b2, voffB); PG8_STAGE(PG8_SB(0, 1), b2 + hstep, voffB); PG8_STAGE(PG8_SA(0, 0), a2, voffA);
.Lg4_peel:
	s_add_u32 s4, s64, 0xfff00080
	s_addc_u32 s5, s65, -1
	s_add_i32 s28, 0, 0x10000
	s_cmp_eq_u32 s74, 60
	s_cselect_b32 s7, s35, s5
	s_cselect_b32 s6, s72, s4
	v_add_u32_e32 v138, s28, v142
	s_cselect_b32 s5, s27, s67
	s_cselect_b32 s4, s73, s66
	s_add_i32 s48, 0, 0x14000
	ds_read_b128 v[144:147], v138
	ds_read_b128 v[148:151], v138 offset:1024
	ds_read_b128 v[152:155], v138 offset:2048
	ds_read_b128 v[156:159], v138 offset:3072
	v_add_u32_e32 v138, s48, v142
	ds_read_b128 v[160:163], v138
	ds_read_b128 v[164:167], v138 offset:1024
	ds_read_b128 v[168:171], v138 offset:2048
	ds_read_b128 v[172:175], v138 offset:3072
	v_lshl_add_u64 v[138:139], s[64:65], 0, v[134:135]
	s_add_i32 m0, s23, 0xc000
	ds_read_b128 v[182:185], v143
	ds_read_b128 v[186:189], v143 offset:1024
	ds_read_b128 v[190:193], v143 offset:2048
	ds_read_b128 v[194:197], v143 offset:3072
	ds_read_b128 v[198:201], v143 offset:4096
	ds_read_b128 v[202:205], v143 offset:5120
	ds_read_b128 v[206:209], v143 offset:6144
	ds_read_b128 v[210:213], v143 offset:7168
	global_load_lds_dwordx4 v[138:139], off
	v_lshl_add_u64 v[138:139], s[64:65], 0, v[136:137]
	s_add_i32 m0, s23, 0xe000
	s_nop 0
	global_load_lds_dwordx4 v[138:139], off
	s_waitcnt vmcnt(24)
	s_waitcnt lgkmcnt(0)
	s_barrier
	s_setprio 1
	s_waitcnt lgkmcnt(0)
	v_mfma_f32_16x16x32_bf16 v[124:127], v[144:147], v[182:185], 0
	v_mfma_f32_16x16x32_bf16 v[120:123], v[152:155], v[182:185], 0
	v_mfma_f32_16x16x32_bf16 v[108:111], v[152:155], v[190:193], 0
	v_mfma_f32_16x16x32_bf16 v[116:119], v[144:147], v[190:193], 0
	v_mfma_f32_16x16x32_bf16 v[100:103], v[144:147], v[198:201], 0
	v_mfma_f32_16x16x32_bf16 v[92:95], v[152:155], v[198:201], 0
	v_mfma_f32_16x16x32_bf16 v[76:79], v[152:155], v[206:209], 0
	v_mfma_f32_16x16x32_bf16 v[84:87], v[144:147], v[206:209], 0
	v_mfma_f32_16x16x32_bf16 v[124:127], v[148:151], v[186:189], v[124:127]
	v_mfma_f32_16x16x32_bf16 v[120:123], v[156:159], v[186:189], v[120:123]
	v_mfma_f32_16x16x32_bf16 v[108:111], v[156:159], v[194:197], v[108:111]
	v_mfma_f32_16x16x32_bf16 v[116:119], v[148:151], v[194:197], v[116:119]
	v_mfma_f32_16x16x32_bf16 v[100:103], v[148:151], v[202:205], v[100:103]
	v_mfma_f32_16x16x32_bf16 v[92:95], v[156:159], v[202:205], v[92:95]
	v_mfma_f32_16x16x32_bf16 v[76:79], v[156:159], v[210:213], v[76:79]
	v_mfma_f32_16x16x32_bf16 v[84:87], v[148:151], v[210:213], v[84:87]
	s_setprio 0
	s_setprio 1
	v_mfma_f32_16x16x32_bf16 v[112:115], v[160:163], v[182:185], 0
	v_mfma_f32_16x16x32_bf16 v[104:107], v[168:171], v[182:185], 0
	v_mfma_f32_16x16x32_bf16 v[88:91], v[168:171], v[190:193], 0
	v_mfma_f32_16x16x32_bf16 v[96:99], v[160:163], v[190:193], 0
	v_mfma_f32_16x16x32_bf16 v[80:83], v[160:163], v[198:201], 0
	v_mfma_f32_16x16x32_bf16 v[72:75], v[168:171], v[198:201], 0
	v_mfma_f32_16x16x32_bf16 v[64:67], v[168:171], v[206:209], 0
	v_mfma_f32_16x16x32_bf16 v[68:71], v[160:163], v[206:209], 0
	v_mfma_f32_16x16x32_bf16 v[112:115], v[164:167], v[186:189], v[112:115]
	v_mfma_f32_16x16x32_bf16 v[104:107], v[172:175], v[186:189], v[104:107]
	v_mfma_f32_16x16x32_bf16 v[88:91], v[172:175], v[194:197], v[88:91]
	v_mfma_f32_16x16x32_bf16 v[96:99], v[164:167], v[194:197], v[96:99]
	v_mfma_f32_16x16x32_bf16 v[80:83], v[164:167], v[202:205], v[80:83]
	v_mfma_f32_16x16x32_bf16 v[72:75], v[172:175], v[202:205], v[72:75]
	v_mfma_f32_16x16x32_bf16 v[64:67], v[172:175], v[210:213], v[64:67]
	v_mfma_f32_16x16x32_bf16 v[68:71], v[164:167], v[210:213], v[68:71]
	s_setprio 0
	s_barrier
	s_add_i32 s28, s28, s22
	v_lshl_add_u64 v[138:139], s[4:5], 0, v[176:177]
	s_mov_b32 m0, s28
	ds_read_b128 v[182:185], v143 offset:16384
	ds_read_b128 v[186:189], v143 offset:17408
	ds_read_b128 v[190:193], v143 offset:18432
	ds_read_b128 v[194:197], v143 offset:19456
	ds_read_b128 v[198:201], v143 offset:20480
	ds_read_b128 v[202:205], v143 offset:21504
	ds_read_b128 v[206:209], v143 offset:22528
	ds_read_b128 v[210:213], v143 offset:23552
	global_load_lds_dwordx4 v[138:139], off
	s_add_i32 m0, s28, 0x2000
	s_add_u32 s38, s4, 0x100000
	v_lshl_add_u64 v[214:215], s[4:5], 0, v[128:129]
	s_addc_u32 s39, s5, 0
	s_add_i32 s28, s48, s22
	global_load_lds_dwordx4 v[214:215], off
	v_lshl_add_u64 v[216:217], s[38:39], 0, v[176:177]
	s_mov_b32 m0, s28
	v_lshl_add_u64 v[218:219], s[6:7], 0, v[130:131]
	global_load_lds_dwordx4 v[216:217], off
	v_lshl_add_u64 v[216:217], s[38:39], 0, v[128:129]
	s_add_i32 m0, s28, 0x2000
	s_nop 0
	global_load_lds_dwordx4 v[216:217], off
	v_lshl_add_u64 v[216:217], s[6:7], 0, v[132:133]
	s_mov_b32 m0, s23
	s_nop 0
	global_load_lds_dwordx4 v[216:217], off
	s_mov_b32 m0, s24
	s_nop 0
	global_load_lds_dwordx4 v[218:219], off
	s_waitcnt vmcnt(24)
	s_waitcnt lgkmcnt(0)
	s_barrier
; #define PG8_STAGE(bufoff, gbase, voff) do { _Pragma("unroll") for (int _i = 0; _i < 2; ++_i) \
;         __builtin_amdgcn_global_load_lds((const unsigned*)((const char*)(gbase) + (voff)[_i]), (PG8_LAS unsigned*)(lds + (bufoff) + ldsw + _i * 8192), 16, 0, 0); } while (0)
; #define PG8_LDA(dst, b, h) do { _Pragma("unroll") for (int m = 0; m < 4; ++m) _Pragma("unroll") for (int k = 0; k < 2; ++k) dst[m][k] = *(const PG8_LAS bf16x8*)(lds + PG8_SA(b, h) + aoff + m * 2048 + k * 1024); } while (0)
; #define PG8_LDB(dst, b, h) do { _Pragma("unroll") for (int n = 0; n < 2; ++n) _Pragma("unroll") for (int k = 0; k < 2; ++k) dst[n][k] = *(const PG8_LAS bf16x8*)(lds + PG8_SB(b, h) + boff + n * 2048 + k * 1024); } while (0)
; #define PG8_MMA(ai, bj, At, Bt) do { __builtin_amdgcn_s_setprio(1); _Pragma("unroll") for (int m = 0; m < 4; ++m) _Pragma("unroll") for (int n = 0; n < 2; ++n) _Pragma("unroll") for (int k = 0; k < 2; ++k) \
;         acc[ai][bj][m][n] = __builtin_amdgcn_mfma_f32_16x16x32_bf16(Bt[n][k], At[m][k], acc[ai][bj][m][n], 0, 0, 0); __builtin_amdgcn_s_setprio(0); } while (0)
; #define PG8_WAIT_V(n) asm volatile("s_waitcnt vmcnt(" #n ")" ::: "memory")
; #define PG8_WAIT_L(n) asm volatile("s_waitcnt lgkmcnt(" #n ")" ::: "memory")
; #define PG8_BAR __builtin_amdgcn_s_barrier()
; #define PG8_SCHED __builtin_amdgcn_sched_barrier(0)
; template <class Epi, class Sched, bool ALIGN_EPI = false, bool SP2 = false>
; __device__ __forceinline__ void gemm_phase(PG8_LAS unsigned char* lds, const Gemm g, const Sched& S, const Epi& E) {
;     ...
;             PG8_WAIT_V(8); PG8_WAIT_L(0); PG8_BAR; PG8_MMA(1, 0, At, B0); PG8_MMA(1, 1, At, B1); PG8_BAR; PG8_SCHED;
;             PG8_LDB(B0, 1, 0); PG8_LDB(B1, 1, 1); PG8_SCHED; PG8_LDA(At, 1, 0); PG8_STAGE(PG8_SA(0, 1), a2 + hstep, voffA);
;             PG8_WAIT_V(8); PG8_WAIT_L(0); PG8_BAR; PG8_MMA(0, 0, At, B0); PG8_MMA(0, 1, At, B1); PG8_BAR; PG8_SCHED;
	s_setprio 1
	s_waitcnt lgkmcnt(0)
	v_mfma_f32_16x16x32_bf16 v[60:63], v[144:147], v[182:185], 0
	v_mfma_f32_16x16x32_bf16 v[56:59], v[152:155], v[182:185], 0
	v_mfma_f32_16x16x32_bf16 v[44:47], v[152:155], v[190:193], 0
	v_mfma_f32_16x16x32_bf16 v[52:55], v[144:147], v[190:193], 0
	v_mfma_f32_16x16x32_bf16 v[36:39], v[144:147], v[198:201], 0
	v_mfma_f32_16x16x32_bf16 v[28:31], v[152:155], v[198:201], 0
	v_mfma_f32_16x16x32_bf16 v[12:15], v[152:155], v[206:209], 0
	v_mfma_f32_16x16x32_bf16 v[20:23], v[144:147], v[206:209], 0
	v_mfma_f32_16x16x32_bf16 v[60:63], v[148:151], v[186:189], v[60:63]
	v_mfma_f32_16x16x32_bf16 v[56:59], v[156:159], v[186:189], v[56:59]
	v_mfma_f32_16x16x32_bf16 v[44:47], v[156:159], v[194:197], v[44:47]
	v_mfma_f32_16x16x32_bf16 v[52:55], v[148:151], v[194:197], v[52:55]
	v_mfma_f32_16x16x32_bf16 v[36:39], v[148:151], v[202:205], v[36:39]
	v_mfma_f32_16x16x32_bf16 v[28:31], v[156:159], v[202:205], v[28:31]
	v_mfma_f32_16x16x32_bf16 v[12:15], v[156:159], v[210:213], v[12:15]
	v_mfma_f32_16x16x32_bf16 v[20:23], v[148:151], v[210:213], v[20:23]
	s_setprio 0
	s_setprio 1
	v_mfma_f32_16x16x32_bf16 v[48:51], v[160:163], v[182:185], 0
	v_mfma_f32_16x16x32_bf16 v[40:43], v[168:171], v[182:185], 0
	v_mfma_f32_16x16x32_bf16 v[24:27], v[168:171], v[190:193], 0
	v_mfma_f32_16x16x32_bf16 v[32:35], v[160:163], v[190:193], 0
	v_mfma_f32_16x16x32_bf16 v[16:19], v[160:163], v[198:201], 0
	v_mfma_f32_16x16x32_bf16 v[8:11], v[168:171], v[198:201], 0
	v_mfma_f32_16x16x32_bf16 v[0:3], v[168:171], v[206:209], 0
	v_mfma_f32_16x16x32_bf16 v[4:7], v[160:163], v[206:209], 0
	v_mfma_f32_16x16x32_bf16 v[48:51], v[164:167], v[186:189], v[48:51]
	v_mfma_f32_16x16x32_bf16 v[40:43], v[172:175], v[186:189], v[40:43]
	v_mfma_f32_16x16x32_bf16 v[24:27], v[172:175], v[194:197], v[24:27]
	v_mfma_f32_16x16x32_bf16 v[32:35], v[164:167], v[194:197], v[32:35]
	v_mfma_f32_16x16x32_bf16 v[16:19], v[164:167], v[202:205], v[16:19]
	v_mfma_f32_16x16x32_bf16 v[8:11], v[172:175], v[202:205], v[8:11]
	v_mfma_f32_16x16x32_bf16 v[0:3], v[172:175], v[210:213], v[0:3]
	v_mfma_f32_16x16x32_bf16 v[4:7], v[164:167], v[210:213], v[4:7]
	s_setprio 0
	s_barrier
	s_add_i32 s28, 0, 0x18000
	s_add_i32 s38, 0, 0x1c000
	v_add_u32_e32 v156, s28, v142
	v_add_u32_e32 v172, s38, v142
	ds_read_b128 v[144:147], v156
	ds_read_b128 v[148:151], v156 offset:1024
	ds_read_b128 v[152:155], v156 offset:2048
	ds_read_b128 v[156:159], v156 offset:3072
	ds_read_b128 v[160:163], v172
	ds_read_b128 v[164:167], v172 offset:1024
	ds_read_b128 v[168:171], v172 offset:2048
	ds_read_b128 v[172:175], v172 offset:3072
	s_add_u32 s6, s6, 0x100000
	s_addc_u32 s7, s7, 0
	s_mov_b32 m0, s25
	v_lshl_add_u64 v[220:221], s[6:7], 0, v[132:133]
	ds_read_b128 v[182:185], v143 offset:32768
	ds_read_b128 v[186:189], v143 offset:33792
	ds_read_b128 v[190:193], v143 offset:34816
	ds_read_b128 v[194:197], v143 offset:35840
	ds_read_b128 v[198:201], v143 offset:36864
	ds_read_b128 v[202:205], v143 offset:37888
	ds_read_b128 v[206:209], v143 offset:38912
	ds_read_b128 v[210:213], v143 offset:39936
	global_load_lds_dwordx4 v[220:221], off
	v_lshl_add_u64 v[220:221], s[6:7], 0, v[130:131]
	s_mov_b32 m0, s30
	s_nop 0
	global_load_lds_dwordx4 v[220:221], off
	s_waitcnt vmcnt(8)
	s_waitcnt lgkmcnt(0)
	s_barrier
	s_setprio 1
	s_waitcnt lgkmcnt(0)
	v_mfma_f32_16x16x32_bf16 v[124:127], v[144:147], v[182:185], v[124:127]
	v_mfma_f32_16x16x32_bf16 v[120:123], v[152:155], v[182:185], v[120:123]
	v_mfma_f32_16x16x32_bf16 v[108:111], v[152:155], v[190:193], v[108:111]
	v_mfma_f32_16x16x32_bf16 v[116:119], v[144:147], v[190:193], v[116:119]
	v_mfma_f32_16x16x32_bf16 v[100:103], v[144:147], v[198:201], v[100:103]
	v_mfma_f32_16x16x32_bf16 v[92:95], v[152:155], v[198:201], v[92:95]
	v_mfma_f32_16x16x32_bf16 v[76:79], v[152:155], v[206:209], v[76:79]
	v_mfma_f32_16x16x32_bf16 v[84:87], v[144:147], v[206:209], v[84:87]
	v_mfma_f32_16x16x32_bf16 v[124:127], v[148:151], v[186:189], v[124:127]
	v_mfma_f32_16x16x32_bf16 v[120:123], v[156:159], v[186:189], v[120:123]
	v_mfma_f32_16x16x32_bf16 v[108:111], v[156:159], v[194:197], v[108:111]
	v_mfma_f32_16x16x32_bf16 v[116:119], v[148:151], v[194:197], v[116:119]
	v_mfma_f32_16x16x32_bf16 v[100:103], v[148:151], v[202:205], v[100:103]
	v_mfma_f32_16x16x32_bf16 v[92:95], v[156:159], v[202:205], v[92:95]
	v_mfma_f32_16x16x32_bf16 v[76:79], v[156:159], v[210:213], v[76:79]
	v_mfma_f32_16x16x32_bf16 v[84:87], v[148:151], v[210:213], v[84:87]
	s_setprio 0
	s_setprio 1
	v_mfma_f32_16x16x32_bf16 v[112:115], v[160:163], v[182:185], v[112:115]
	v_mfma_f32_16x16x32_bf16 v[104:107], v[168:171], v[182:185], v[104:107]
	v_mfma_f32_16x16x32_bf16 v[88:91], v[168:171], v[190:193], v[88:91]
	v_mfma_f32_16x16x32_bf16 v[96:99], v[160:163], v[190:193], v[96:99]
	v_mfma_f32_16x16x32_bf16 v[80:83], v[160:163], v[198:201], v[80:83]
	v_mfma_f32_16x16x32_bf16 v[72:75], v[168:171], v[198:201], v[72:75]
	v_mfma_f32_16x16x32_bf16 v[64:67], v[168:171], v[206:209], v[64:67]
	v_mfma_f32_16x16x32_bf16 v[68:71], v[160:163], v[206:209], v[68:71]
	v_mfma_f32_16x16x32_bf16 v[112:115], v[164:167], v[186:189], v[112:115]
	v_mfma_f32_16x16x32_bf16 v[104:107], v[172:175], v[186:189], v[104:107]
	v_mfma_f32_16x16x32_bf16 v[88:91], v[172:175], v[194:197], v[88:91]
	v_mfma_f32_16x16x32_bf16 v[96:99], v[164:167], v[194:197], v[96:99]
	v_mfma_f32_16x16x32_bf16 v[80:83], v[164:167], v[202:205], v[80:83]
	v_mfma_f32_16x16x32_bf16 v[72:75], v[172:175], v[202:205], v[72:75]
	v_mfma_f32_16x16x32_bf16 v[64:67], v[172:175], v[210:213], v[64:67]
	v_mfma_f32_16x16x32_bf16 v[68:71], v[164:167], v[210:213], v[68:71]
	s_setprio 0
	s_barrier
; #define PG8_STAGE(bufoff, gbase, voff) do { _Pragma("unroll") for (int _i = 0; _i < 2; ++_i) \
;         __builtin_amdgcn_global_load_lds((const unsigned*)((const char*)(gbase) + (voff)[_i]), (PG8_LAS unsigned*)(lds + (bufoff) + ldsw + _i * 8192), 16, 0, 0); } while (0)
; #define PG8_LDA(dst, b, h) do { _Pragma("unroll") for (int m = 0; m < 4; ++m) _Pragma("unroll") for (int k = 0; k < 2; ++k) dst[m][k] = *(const PG8_LAS bf16x8*)(lds + PG8_SA(b, h) + aoff + m * 2048 + k * 1024); } while (0)
; #define PG8_MMA(ai, bj, At, Bt) do { __builtin_amdgcn_s_setprio(1); _Pragma("unroll") for (int m = 0; m < 4; ++m) _Pragma("unroll") for (int n = 0; n < 2; ++n) _Pragma("unroll") for (int k = 0; k < 2; ++k) \
;         acc[ai][bj][m][n] = __builtin_amdgcn_mfma_f32_16x16x32_bf16(Bt[n][k], At[m][k], acc[ai][bj][m][n], 0, 0, 0); __builtin_amdgcn_s_setprio(0); } while (0)
; #define PG8_WAIT_V(n) asm volatile("s_waitcnt vmcnt(" #n ")" ::: "memory")
; #define PG8_WAIT_L(n) asm volatile("s_waitcnt lgkmcnt(" #n ")" ::: "memory")
; #define PG8_BAR __builtin_amdgcn_s_barrier()
; #define PG8_SCHED __builtin_amdgcn_sched_barrier(0)
; template <class Epi, class Sched, bool ALIGN_EPI = false, bool SP2 = false>
; __device__ __forceinline__ void gemm_phase(PG8_LAS unsigned char* lds, const Gemm g, const Sched& S, const Epi& E) {
;     ...
;         for (int t = 0; t < nt; t += 2) {
;     ...
;             PG8_LDA(At, 1, 1); PG8_STAGE(PG8_SB(1, 0), b3, voffB); PG8_STAGE(PG8_SB(1, 1), b3 + hstep, voffB); PG8_STAGE(PG8_SA(1, 0), a3, voffA);
;             PG8_WAIT_V(8); PG8_WAIT_L(0); PG8_BAR; PG8_MMA(1, 0, At, B0); PG8_MMA(1, 1, At, B1); PG8_BAR; PG8_SCHED;
	s_add_i32 s6, s28, s22
	v_lshl_add_u64 v[138:139], v[138:139], 0, s[44:45]
	s_mov_b32 m0, s6
	ds_read_b128 v[182:185], v143 offset:49152
	ds_read_b128 v[186:189], v143 offset:50176
	ds_read_b128 v[190:193], v143 offset:51200
	ds_read_b128 v[194:197], v143 offset:52224
	ds_read_b128 v[198:201], v143 offset:53248
	ds_read_b128 v[202:205], v143 offset:54272
	ds_read_b128 v[206:209], v143 offset:55296
	ds_read_b128 v[210:213], v143 offset:56320
	global_load_lds_dwordx4 v[138:139], off
	s_add_i32 m0, s6, 0x2000
	s_add_u32 s4, s4, 0x100080
	v_lshl_add_u64 v[138:139], v[214:215], 0, s[44:45]
	s_addc_u32 s5, s5, 0
	s_add_i32 s6, s38, s22
	global_load_lds_dwordx4 v[138:139], off
	v_lshl_add_u64 v[138:139], s[4:5], 0, v[176:177]
	s_mov_b32 m0, s6
	s_nop 0
	global_load_lds_dwordx4 v[138:139], off
	v_lshl_add_u64 v[138:139], s[4:5], 0, v[128:129]
	s_add_i32 m0, s6, 0x2000
	s_nop 0
	global_load_lds_dwordx4 v[138:139], off
	v_lshl_add_u64 v[138:139], v[216:217], 0, s[44:45]
	s_mov_b32 m0, s63
	s_nop 0
	global_load_lds_dwordx4 v[138:139], off
	v_lshl_add_u64 v[138:139], v[218:219], 0, s[44:45]
	s_mov_b32 m0, s68
	s_nop 0
	global_load_lds_dwordx4 v[138:139], off
	s_waitcnt vmcnt(8)
	s_waitcnt lgkmcnt(0)
	s_barrier
	s_setprio 1
	s_waitcnt lgkmcnt(0)
	v_mfma_f32_16x16x32_bf16 v[60:63], v[144:147], v[182:185], v[60:63]
	v_mfma_f32_16x16x32_bf16 v[56:59], v[152:155], v[182:185], v[56:59]
	v_mfma_f32_16x16x32_bf16 v[44:47], v[152:155], v[190:193], v[44:47]
	v_mfma_f32_16x16x32_bf16 v[52:55], v[144:147], v[190:193], v[52:55]
	v_mfma_f32_16x16x32_bf16 v[36:39], v[144:147], v[198:201], v[36:39]
	v_mfma_f32_16x16x32_bf16 v[28:31], v[152:155], v[198:201], v[28:31]
	v_mfma_f32_16x16x32_bf16 v[12:15], v[152:155], v[206:209], v[12:15]
	v_mfma_f32_16x16x32_bf16 v[20:23], v[144:147], v[206:209], v[20:23]
	v_mfma_f32_16x16x32_bf16 v[60:63], v[148:151], v[186:189], v[60:63]
	v_mfma_f32_16x16x32_bf16 v[56:59], v[156:159], v[186:189], v[56:59]
	v_mfma_f32_16x16x32_bf16 v[44:47], v[156:159], v[194:197], v[44:47]
	v_mfma_f32_16x16x32_bf16 v[52:55], v[148:151], v[194:197], v[52:55]
	v_mfma_f32_16x16x32_bf16 v[36:39], v[148:151], v[202:205], v[36:39]
	v_mfma_f32_16x16x32_bf16 v[28:31], v[156:159], v[202:205], v[28:31]
	v_mfma_f32_16x16x32_bf16 v[12:15], v[156:159], v[210:213], v[12:15]
	v_mfma_f32_16x16x32_bf16 v[20:23], v[148:151], v[210:213], v[20:23]
	s_setprio 0
	s_setprio 1
	v_mfma_f32_16x16x32_bf16 v[48:51], v[160:163], v[182:185], v[48:51]
	v_mfma_f32_16x16x32_bf16 v[40:43], v[168:171], v[182:185], v[40:43]
	v_mfma_f32_16x16x32_bf16 v[32:35], v[160:163], v[190:193], v[32:35]
	v_mfma_f32_16x16x32_bf16 v[24:27], v[168:171], v[190:193], v[24:27]
	v_mfma_f32_16x16x32_bf16 v[16:19], v[160:163], v[198:201], v[16:19]
	v_mfma_f32_16x16x32_bf16 v[8:11], v[168:171], v[198:201], v[8:11]
	v_mfma_f32_16x16x32_bf16 v[4:7], v[160:163], v[206:209], v[4:7]
	v_mfma_f32_16x16x32_bf16 v[0:3], v[168:171], v[206:209], v[0:3]
	v_mfma_f32_16x16x32_bf16 v[48:51], v[164:167], v[186:189], v[48:51]
	v_mfma_f32_16x16x32_bf16 v[40:43], v[172:175], v[186:189], v[40:43]
	s_add_i32 s74, s74, 2
	v_mfma_f32_16x16x32_bf16 v[32:35], v[164:167], v[194:197], v[32:35]
	s_add_u32 s64, s64, 0x100
	v_mfma_f32_16x16x32_bf16 v[24:27], v[172:175], v[194:197], v[24:27]
	s_addc_u32 s65, s65, 0
	v_mfma_f32_16x16x32_bf16 v[16:19], v[164:167], v[202:205], v[16:19]
	s_add_u32 s66, s66, 0x100
	v_mfma_f32_16x16x32_bf16 v[8:11], v[172:175], v[202:205], v[8:11]
	s_addc_u32 s67, s67, 0
	v_mfma_f32_16x16x32_bf16 v[4:7], v[164:167], v[210:213], v[4:7]
	s_cmp_gt_u32 s74, 61
	v_mfma_f32_16x16x32_bf16 v[0:3], v[172:175], v[210:213], v[0:3]
	s_setprio 0
	s_barrier
	s_cbranch_scc0 .LBB0_790
	s_branch .Lg4_post

; #define PG8_STAGE(bufoff, gbase, voff) do { _Pragma("unroll") for (int _i = 0; _i < 2; ++_i) \
;         __builtin_amdgcn_global_load_lds((const unsigned*)((const char*)(gbase) + (voff)[_i]), (PG8_LAS unsigned*)(lds + (bufoff) + ldsw + _i * 8192), 16, 0, 0); } while (0)
; #define PG8_LDA(dst, b, h) do { _Pragma("unroll") for (int m = 0; m < 4; ++m) _Pragma("unroll") for (int k = 0; k < 2; ++k) dst[m][k] = *(const PG8_LAS bf16x8*)(lds + PG8_SA(b, h) + aoff + m * 2048 + k * 1024); } while (0)
; #define PG8_LDB(dst, b, h) do { _Pragma("unroll") for (int n = 0; n < 2; ++n) _Pragma("unroll") for (int k = 0; k < 2; ++k) dst[n][k] = *(const PG8_LAS bf16x8*)(lds + PG8_SB(b, h) + boff + n * 2048 + k * 1024); } while (0)
; #define PG8_MMA(ai, bj, At, Bt) do { __builtin_amdgcn_s_setprio(1); _Pragma("unroll") for (int m = 0; m < 4; ++m) _Pragma("unroll") for (int n = 0; n < 2; ++n) _Pragma("unroll") for (int k = 0; k < 2; ++k) \
;         acc[ai][bj][m][n] = __builtin_amdgcn_mfma_f32_16x16x32_bf16(Bt[n][k], At[m][k], acc[ai][bj][m][n], 0, 0, 0); __builtin_amdgcn_s_setprio(0); } while (0)
; #define PG8_WAIT_V(n) asm volatile("s_waitcnt vmcnt(" #n ")" ::: "memory")
; #define PG8_WAIT_L(n) asm volatile("s_waitcnt lgkmcnt(" #n ")" ::: "memory")
; #define PG8_BAR __builtin_amdgcn_s_barrier()
; #define PG8_SCHED __builtin_amdgcn_sched_barrier(0)
; template <class Epi, class Sched, bool ALIGN_EPI = false, bool SP2 = false>
; __device__ __forceinline__ void gemm_phase(PG8_LAS unsigned char* lds, const Gemm g, const Sched& S, const Epi& E) {
;     ...
;             const bool last = (t == nt - 2);
;             const char* a1 = cA + (size_t)(t + 1) * kstep;
;             const char* a2 = last ? nA : cA + (size_t)(t + 2) * kstep; const char* b2 = last ? nB : cB + (size_t)(t + 2) * kstep;
;             const char* a3 = a2 + kstep; const char* b3 = b2 + kstep;
;             if (last && has_next) S.a_ready(nxt);
;             if constexpr (SP2) {
;             PG8_LDB(B0, 0, 0); PG8_LDB(B1, 0, 1); PG8_SCHED; PG8_LDA(At, 0, 0); PG8_STAGE(PG8_SA(1, 1), a1 + hstep, voffA);
;             PG8_WAIT_V(8); PG8_WAIT_L(0); PG8_BAR; PG8_MMA(0, 0, At, B0); PG8_MMA(0, 1, At, B1); PG8_BAR; PG8_SCHED;
;             PG8_LDA(At, 0, 1); PG8_STAGE(PG8_SB(0, 0), b2, voffB); PG8_STAGE(PG8_SB(0, 1), b2 + hstep, voffB); PG8_STAGE(PG8_SA(0, 0), a2, voffA);
.LBB0_812:
	s_add_i32 s83, s4, 2
	s_add_u32 s28, s64, 0x80
	s_addc_u32 s5, s65, 0
	s_add_i32 s48, 0, 0x10000
	s_cmp_eq_u32 s72, s4
	s_cselect_b32 s5, s37, s5
	s_cselect_b32 s4, s36, s28
	s_cselect_b32 s39, s41, s67
	s_cselect_b32 s38, s40, s66
	s_add_i32 s28, 0, 0x14000
	v_add_u32_e32 v154, s48, v140
	v_add_u32_e32 v170, s28, v140
	ds_read_b128 v[142:145], v154
	ds_read_b128 v[146:149], v154 offset:1024
	ds_read_b128 v[150:153], v154 offset:2048
	ds_read_b128 v[154:157], v154 offset:3072
	ds_read_b128 v[158:161], v170
	ds_read_b128 v[162:165], v170 offset:1024
	ds_read_b128 v[166:169], v170 offset:2048
	ds_read_b128 v[170:173], v170 offset:3072
	v_lshl_add_u64 v[174:175], s[64:65], 0, v[134:135]
	s_add_i32 m0, s25, 0xc000
	ds_read_b128 v[182:185], v141
	ds_read_b128 v[186:189], v141 offset:1024
	ds_read_b128 v[190:193], v141 offset:2048
	ds_read_b128 v[194:197], v141 offset:3072
	ds_read_b128 v[198:201], v141 offset:4096
	ds_read_b128 v[202:205], v141 offset:5120
	ds_read_b128 v[206:209], v141 offset:6144
	ds_read_b128 v[210:213], v141 offset:7168
	global_load_lds_dwordx4 v[174:175], off
	v_lshl_add_u64 v[174:175], s[64:65], 0, v[136:137]
	s_add_i32 m0, s25, 0xe000
	s_nop 0
	global_load_lds_dwordx4 v[174:175], off
	s_waitcnt vmcnt(8)
	s_waitcnt lgkmcnt(0)
	s_barrier
	s_setprio 1
	s_waitcnt lgkmcnt(0)
	v_mfma_f32_16x16x32_bf16 v[124:127], v[142:145], v[182:185], v[124:127]
	v_mfma_f32_16x16x32_bf16 v[120:123], v[150:153], v[182:185], v[120:123]
	v_mfma_f32_16x16x32_bf16 v[104:107], v[150:153], v[190:193], v[104:107]
	v_mfma_f32_16x16x32_bf16 v[108:111], v[142:145], v[190:193], v[108:111]
	v_mfma_f32_16x16x32_bf16 v[92:95], v[142:145], v[198:201], v[92:95]
	v_mfma_f32_16x16x32_bf16 v[88:91], v[150:153], v[198:201], v[88:91]
	v_mfma_f32_16x16x32_bf16 v[72:75], v[150:153], v[206:209], v[72:75]
	v_mfma_f32_16x16x32_bf16 v[76:79], v[142:145], v[206:209], v[76:79]
	v_mfma_f32_16x16x32_bf16 v[124:127], v[146:149], v[186:189], v[124:127]
	v_mfma_f32_16x16x32_bf16 v[120:123], v[154:157], v[186:189], v[120:123]
	v_mfma_f32_16x16x32_bf16 v[104:107], v[154:157], v[194:197], v[104:107]
	v_mfma_f32_16x16x32_bf16 v[108:111], v[146:149], v[194:197], v[108:111]
	v_mfma_f32_16x16x32_bf16 v[92:95], v[146:149], v[202:205], v[92:95]
	v_mfma_f32_16x16x32_bf16 v[88:91], v[154:157], v[202:205], v[88:91]
	v_mfma_f32_16x16x32_bf16 v[72:75], v[154:157], v[210:213], v[72:75]
	v_mfma_f32_16x16x32_bf16 v[76:79], v[146:149], v[210:213], v[76:79]
	s_setprio 0
	s_setprio 1
	v_mfma_f32_16x16x32_bf16 v[116:119], v[158:161], v[182:185], v[116:119]
	v_mfma_f32_16x16x32_bf16 v[112:115], v[166:169], v[182:185], v[112:115]
	v_mfma_f32_16x16x32_bf16 v[96:99], v[166:169], v[190:193], v[96:99]
	v_mfma_f32_16x16x32_bf16 v[100:103], v[158:161], v[190:193], v[100:103]
	v_mfma_f32_16x16x32_bf16 v[84:87], v[158:161], v[198:201], v[84:87]
	v_mfma_f32_16x16x32_bf16 v[80:83], v[166:169], v[198:201], v[80:83]
	v_mfma_f32_16x16x32_bf16 v[64:67], v[166:169], v[206:209], v[64:67]
	v_mfma_f32_16x16x32_bf16 v[68:71], v[158:161], v[206:209], v[68:71]
	v_mfma_f32_16x16x32_bf16 v[116:119], v[162:165], v[186:189], v[116:119]
	v_mfma_f32_16x16x32_bf16 v[112:115], v[170:173], v[186:189], v[112:115]
	v_mfma_f32_16x16x32_bf16 v[96:99], v[170:173], v[194:197], v[96:99]
	v_mfma_f32_16x16x32_bf16 v[100:103], v[162:165], v[194:197], v[100:103]
	v_mfma_f32_16x16x32_bf16 v[84:87], v[162:165], v[202:205], v[84:87]
	v_mfma_f32_16x16x32_bf16 v[80:83], v[170:173], v[202:205], v[80:83]
	v_mfma_f32_16x16x32_bf16 v[64:67], v[170:173], v[210:213], v[64:67]
	v_mfma_f32_16x16x32_bf16 v[68:71], v[162:165], v[210:213], v[68:71]
	s_setprio 0
	s_barrier
	s_add_i32 s48, s48, s24
	v_lshl_add_u64 v[174:175], s[38:39], 0, v[176:177]
	s_mov_b32 m0, s48
	ds_read_b128 v[182:185], v141 offset:16384
	ds_read_b128 v[186:189], v141 offset:17408
	ds_read_b128 v[190:193], v141 offset:18432
	ds_read_b128 v[194:197], v141 offset:19456
	ds_read_b128 v[198:201], v141 offset:20480
	ds_read_b128 v[202:205], v141 offset:21504
	ds_read_b128 v[206:209], v141 offset:22528
	ds_read_b128 v[210:213], v141 offset:23552
	global_load_lds_dwordx4 v[174:175], off
	s_add_i32 m0, s48, 0x2000
	v_lshl_add_u64 v[214:215], s[38:39], 0, v[128:129]
	s_add_u32 s38, s38, s0
	s_addc_u32 s39, s39, s1
	s_add_i32 s28, s28, s24
	global_load_lds_dwordx4 v[214:215], off
	v_lshl_add_u64 v[216:217], s[38:39], 0, v[176:177]
	s_mov_b32 m0, s28
	v_lshl_add_u64 v[218:219], s[38:39], 0, v[128:129]
	global_load_lds_dwordx4 v[216:217], off
	s_add_i32 m0, s28, 0x2000
	v_lshl_add_u64 v[220:221], s[4:5], 0, v[132:133]
	global_load_lds_dwordx4 v[218:219], off
	s_mov_b32 m0, s25
	v_lshl_add_u64 v[222:223], s[4:5], 0, v[130:131]
	global_load_lds_dwordx4 v[220:221], off
	s_mov_b32 m0, s30
	s_nop 0
	global_load_lds_dwordx4 v[222:223], off
	s_waitcnt vmcnt(8)
	s_waitcnt lgkmcnt(0)
	s_barrier
; #define PG8_STAGE(bufoff, gbase, voff) do { _Pragma("unroll") for (int _i = 0; _i < 2; ++_i) \
;         __builtin_amdgcn_global_load_lds((const unsigned*)((const char*)(gbase) + (voff)[_i]), (PG8_LAS unsigned*)(lds + (bufoff) + ldsw + _i * 8192), 16, 0, 0); } while (0)
; #define PG8_LDA(dst, b, h) do { _Pragma("unroll") for (int m = 0; m < 4; ++m) _Pragma("unroll") for (int k = 0; k < 2; ++k) dst[m][k] = *(const PG8_LAS bf16x8*)(lds + PG8_SA(b, h) + aoff + m * 2048 + k * 1024); } while (0)
; #define PG8_LDB(dst, b, h) do { _Pragma("unroll") for (int n = 0; n < 2; ++n) _Pragma("unroll") for (int k = 0; k < 2; ++k) dst[n][k] = *(const PG8_LAS bf16x8*)(lds + PG8_SB(b, h) + boff + n * 2048 + k * 1024); } while (0)
; #define PG8_MMA(ai, bj, At, Bt) do { __builtin_amdgcn_s_setprio(1); _Pragma("unroll") for (int m = 0; m < 4; ++m) _Pragma("unroll") for (int n = 0; n < 2; ++n) _Pragma("unroll") for (int k = 0; k < 2; ++k) \
;         acc[ai][bj][m][n] = __builtin_amdgcn_mfma_f32_16x16x32_bf16(Bt[n][k], At[m][k], acc[ai][bj][m][n], 0, 0, 0); __builtin_amdgcn_s_setprio(0); } while (0)
; #define PG8_WAIT_V(n) asm volatile("s_waitcnt vmcnt(" #n ")" ::: "memory")
; #define PG8_WAIT_L(n) asm volatile("s_waitcnt lgkmcnt(" #n ")" ::: "memory")
; #define PG8_BAR __builtin_amdgcn_s_barrier()
; #define PG8_SCHED __builtin_amdgcn_sched_barrier(0)
; template <class Epi, class Sched, bool ALIGN_EPI = false, bool SP2 = false>
; __device__ __forceinline__ void gemm_phase(PG8_LAS unsigned char* lds, const Gemm g, const Sched& S, const Epi& E) {
;     ...
;             PG8_WAIT_V(8); PG8_WAIT_L(0); PG8_BAR; PG8_MMA(1, 0, At, B0); PG8_MMA(1, 1, At, B1); PG8_BAR; PG8_SCHED;
;             PG8_LDB(B0, 1, 0); PG8_LDB(B1, 1, 1); PG8_SCHED; PG8_LDA(At, 1, 0); PG8_STAGE(PG8_SA(0, 1), a2 + hstep, voffA);
;             PG8_WAIT_V(8); PG8_WAIT_L(0); PG8_BAR; PG8_MMA(0, 0, At, B0); PG8_MMA(0, 1, At, B1); PG8_BAR; PG8_SCHED;
	s_setprio 1
	s_waitcnt lgkmcnt(0)
	v_mfma_f32_16x16x32_bf16 v[60:63], v[142:145], v[182:185], v[60:63]
	v_mfma_f32_16x16x32_bf16 v[56:59], v[150:153], v[182:185], v[56:59]
	v_mfma_f32_16x16x32_bf16 v[40:43], v[150:153], v[190:193], v[40:43]
	v_mfma_f32_16x16x32_bf16 v[44:47], v[142:145], v[190:193], v[44:47]
	v_mfma_f32_16x16x32_bf16 v[28:31], v[142:145], v[198:201], v[28:31]
	v_mfma_f32_16x16x32_bf16 v[24:27], v[150:153], v[198:201], v[24:27]
	v_mfma_f32_16x16x32_bf16 v[8:11], v[150:153], v[206:209], v[8:11]
	v_mfma_f32_16x16x32_bf16 v[12:15], v[142:145], v[206:209], v[12:15]
	v_mfma_f32_16x16x32_bf16 v[60:63], v[146:149], v[186:189], v[60:63]
	v_mfma_f32_16x16x32_bf16 v[56:59], v[154:157], v[186:189], v[56:59]
	v_mfma_f32_16x16x32_bf16 v[40:43], v[154:157], v[194:197], v[40:43]
	v_mfma_f32_16x16x32_bf16 v[44:47], v[146:149], v[194:197], v[44:47]
	v_mfma_f32_16x16x32_bf16 v[28:31], v[146:149], v[202:205], v[28:31]
	v_mfma_f32_16x16x32_bf16 v[24:27], v[154:157], v[202:205], v[24:27]
	v_mfma_f32_16x16x32_bf16 v[8:11], v[154:157], v[210:213], v[8:11]
	v_mfma_f32_16x16x32_bf16 v[12:15], v[146:149], v[210:213], v[12:15]
	s_setprio 0
	s_setprio 1
	v_mfma_f32_16x16x32_bf16 v[52:55], v[158:161], v[182:185], v[52:55]
	v_mfma_f32_16x16x32_bf16 v[48:51], v[166:169], v[182:185], v[48:51]
	v_mfma_f32_16x16x32_bf16 v[32:35], v[166:169], v[190:193], v[32:35]
	v_mfma_f32_16x16x32_bf16 v[36:39], v[158:161], v[190:193], v[36:39]
	v_mfma_f32_16x16x32_bf16 v[20:23], v[158:161], v[198:201], v[20:23]
	v_mfma_f32_16x16x32_bf16 v[16:19], v[166:169], v[198:201], v[16:19]
	v_mfma_f32_16x16x32_bf16 v[0:3], v[166:169], v[206:209], v[0:3]
	v_mfma_f32_16x16x32_bf16 v[4:7], v[158:161], v[206:209], v[4:7]
	v_mfma_f32_16x16x32_bf16 v[52:55], v[162:165], v[186:189], v[52:55]
	v_mfma_f32_16x16x32_bf16 v[48:51], v[170:173], v[186:189], v[48:51]
	v_mfma_f32_16x16x32_bf16 v[32:35], v[170:173], v[194:197], v[32:35]
	v_mfma_f32_16x16x32_bf16 v[36:39], v[162:165], v[194:197], v[36:39]
	v_mfma_f32_16x16x32_bf16 v[20:23], v[162:165], v[202:205], v[20:23]
	v_mfma_f32_16x16x32_bf16 v[16:19], v[170:173], v[202:205], v[16:19]
	v_mfma_f32_16x16x32_bf16 v[0:3], v[170:173], v[210:213], v[0:3]
	v_mfma_f32_16x16x32_bf16 v[4:7], v[162:165], v[210:213], v[4:7]
	s_setprio 0
	s_barrier
	s_add_i32 s28, 0, 0x18000
	s_add_i32 s38, 0, 0x1c000
	v_add_u32_e32 v154, s28, v140
	v_add_u32_e32 v170, s38, v140
	ds_read_b128 v[142:145], v154
	ds_read_b128 v[146:149], v154 offset:1024
	ds_read_b128 v[150:153], v154 offset:2048
	ds_read_b128 v[154:157], v154 offset:3072
	ds_read_b128 v[158:161], v170
	ds_read_b128 v[162:165], v170 offset:1024
	ds_read_b128 v[166:169], v170 offset:2048
	ds_read_b128 v[170:173], v170 offset:3072
	s_add_u32 s4, s4, s0
	s_addc_u32 s5, s5, s1
	s_mov_b32 m0, s31
	v_lshl_add_u64 v[224:225], s[4:5], 0, v[132:133]
	ds_read_b128 v[182:185], v141 offset:32768
	ds_read_b128 v[186:189], v141 offset:33792
	ds_read_b128 v[190:193], v141 offset:34816
	ds_read_b128 v[194:197], v141 offset:35840
	ds_read_b128 v[198:201], v141 offset:36864
	ds_read_b128 v[202:205], v141 offset:37888
	ds_read_b128 v[206:209], v141 offset:38912
	ds_read_b128 v[210:213], v141 offset:39936
	global_load_lds_dwordx4 v[224:225], off
	v_lshl_add_u64 v[224:225], s[4:5], 0, v[130:131]
	s_mov_b32 m0, s46
	s_nop 0
	global_load_lds_dwordx4 v[224:225], off
	s_waitcnt vmcnt(8)
	s_waitcnt lgkmcnt(0)
	s_barrier
	s_setprio 1
	s_waitcnt lgkmcnt(0)
	v_mfma_f32_16x16x32_bf16 v[124:127], v[142:145], v[182:185], v[124:127]
	v_mfma_f32_16x16x32_bf16 v[120:123], v[150:153], v[182:185], v[120:123]
	v_mfma_f32_16x16x32_bf16 v[104:107], v[150:153], v[190:193], v[104:107]
	v_mfma_f32_16x16x32_bf16 v[108:111], v[142:145], v[190:193], v[108:111]
	v_mfma_f32_16x16x32_bf16 v[92:95], v[142:145], v[198:201], v[92:95]
	v_mfma_f32_16x16x32_bf16 v[88:91], v[150:153], v[198:201], v[88:91]
	v_mfma_f32_16x16x32_bf16 v[72:75], v[150:153], v[206:209], v[72:75]
	v_mfma_f32_16x16x32_bf16 v[76:79], v[142:145], v[206:209], v[76:79]
	v_mfma_f32_16x16x32_bf16 v[124:127], v[146:149], v[186:189], v[124:127]
	v_mfma_f32_16x16x32_bf16 v[120:123], v[154:157], v[186:189], v[120:123]
	v_mfma_f32_16x16x32_bf16 v[104:107], v[154:157], v[194:197], v[104:107]
	v_mfma_f32_16x16x32_bf16 v[108:111], v[146:149], v[194:197], v[108:111]
	v_mfma_f32_16x16x32_bf16 v[92:95], v[146:149], v[202:205], v[92:95]
	v_mfma_f32_16x16x32_bf16 v[88:91], v[154:157], v[202:205], v[88:91]
	v_mfma_f32_16x16x32_bf16 v[72:75], v[154:157], v[210:213], v[72:75]
	v_mfma_f32_16x16x32_bf16 v[76:79], v[146:149], v[210:213], v[76:79]
	s_setprio 0
	s_setprio 1
	v_mfma_f32_16x16x32_bf16 v[116:119], v[158:161], v[182:185], v[116:119]
	v_mfma_f32_16x16x32_bf16 v[112:115], v[166:169], v[182:185], v[112:115]
	v_mfma_f32_16x16x32_bf16 v[96:99], v[166:169], v[190:193], v[96:99]
	v_mfma_f32_16x16x32_bf16 v[100:103], v[158:161], v[190:193], v[100:103]
	v_mfma_f32_16x16x32_bf16 v[84:87], v[158:161], v[198:201], v[84:87]
	v_mfma_f32_16x16x32_bf16 v[80:83], v[166:169], v[198:201], v[80:83]
	v_mfma_f32_16x16x32_bf16 v[64:67], v[166:169], v[206:209], v[64:67]
	v_mfma_f32_16x16x32_bf16 v[68:71], v[158:161], v[206:209], v[68:71]
	v_mfma_f32_16x16x32_bf16 v[116:119], v[162:165], v[186:189], v[116:119]
	v_mfma_f32_16x16x32_bf16 v[112:115], v[170:173], v[186:189], v[112:115]
	v_mfma_f32_16x16x32_bf16 v[96:99], v[170:173], v[194:197], v[96:99]
	v_mfma_f32_16x16x32_bf16 v[100:103], v[162:165], v[194:197], v[100:103]
	v_mfma_f32_16x16x32_bf16 v[84:87], v[162:165], v[202:205], v[84:87]
	v_mfma_f32_16x16x32_bf16 v[80:83], v[170:173], v[202:205], v[80:83]
	v_mfma_f32_16x16x32_bf16 v[64:67], v[170:173], v[210:213], v[64:67]
	v_mfma_f32_16x16x32_bf16 v[68:71], v[162:165], v[210:213], v[68:71]
	s_setprio 0
	s_barrier
; #define PG8_STAGE(bufoff, gbase, voff) do { _Pragma("unroll") for (int _i = 0; _i < 2; ++_i) \
;         __builtin_amdgcn_global_load_lds((const unsigned*)((const char*)(gbase) + (voff)[_i]), (PG8_LAS unsigned*)(lds + (bufoff) + ldsw + _i * 8192), 16, 0, 0); } while (0)
; #define PG8_LDA(dst, b, h) do { _Pragma("unroll") for (int m = 0; m < 4; ++m) _Pragma("unroll") for (int k = 0; k < 2; ++k) dst[m][k] = *(const PG8_LAS bf16x8*)(lds + PG8_SA(b, h) + aoff + m * 2048 + k * 1024); } while (0)
; #define PG8_MMA(ai, bj, At, Bt) do { __builtin_amdgcn_s_setprio(1); _Pragma("unroll") for (int m = 0; m < 4; ++m) _Pragma("unroll") for (int n = 0; n < 2; ++n) _Pragma("unroll") for (int k = 0; k < 2; ++k) \
;         acc[ai][bj][m][n] = __builtin_amdgcn_mfma_f32_16x16x32_bf16(Bt[n][k], At[m][k], acc[ai][bj][m][n], 0, 0, 0); __builtin_amdgcn_s_setprio(0); } while (0)
; #define PG8_WAIT_V(n) asm volatile("s_waitcnt vmcnt(" #n ")" ::: "memory")
; #define PG8_WAIT_L(n) asm volatile("s_waitcnt lgkmcnt(" #n ")" ::: "memory")
; #define PG8_BAR __builtin_amdgcn_s_barrier()
; #define PG8_SCHED __builtin_amdgcn_sched_barrier(0)
; template <class Epi, class Sched, bool ALIGN_EPI = false, bool SP2 = false>
; __device__ __forceinline__ void gemm_phase(PG8_LAS unsigned char* lds, const Gemm g, const Sched& S, const Epi& E) {
;     ...
;         for (int t = 0; t < nt; t += 2) {
;     ...
;             PG8_LDA(At, 1, 1); PG8_STAGE(PG8_SB(1, 0), b3, voffB); PG8_STAGE(PG8_SB(1, 1), b3 + hstep, voffB); PG8_STAGE(PG8_SA(1, 0), a3, voffA);
;             PG8_WAIT_V(8); PG8_WAIT_L(0); PG8_BAR; PG8_MMA(1, 0, At, B0); PG8_MMA(1, 1, At, B1); PG8_BAR; PG8_SCHED;
	s_add_i32 s4, s28, s24
	v_lshl_add_u64 v[174:175], v[174:175], 0, s[44:45]
	s_mov_b32 m0, s4
	ds_read_b128 v[182:185], v141 offset:49152
	ds_read_b128 v[186:189], v141 offset:50176
	ds_read_b128 v[190:193], v141 offset:51200
	ds_read_b128 v[194:197], v141 offset:52224
	ds_read_b128 v[198:201], v141 offset:53248
	ds_read_b128 v[202:205], v141 offset:54272
	ds_read_b128 v[206:209], v141 offset:55296
	ds_read_b128 v[210:213], v141 offset:56320
	global_load_lds_dwordx4 v[174:175], off
	v_lshl_add_u64 v[174:175], v[214:215], 0, s[44:45]
	s_add_i32 m0, s4, 0x2000
	s_add_i32 s4, s38, s24
	global_load_lds_dwordx4 v[174:175], off
	v_lshl_add_u64 v[174:175], v[216:217], 0, s[44:45]
	s_mov_b32 m0, s4
	s_nop 0
	global_load_lds_dwordx4 v[174:175], off
	v_lshl_add_u64 v[174:175], v[218:219], 0, s[44:45]
	s_add_i32 m0, s4, 0x2000
	s_nop 0
	global_load_lds_dwordx4 v[174:175], off
	v_lshl_add_u64 v[174:175], v[220:221], 0, s[44:45]
	s_mov_b32 m0, s69
	s_nop 0
	global_load_lds_dwordx4 v[174:175], off
	v_lshl_add_u64 v[174:175], v[222:223], 0, s[44:45]
	s_mov_b32 m0, s70
	s_nop 0
	global_load_lds_dwordx4 v[174:175], off
	s_waitcnt vmcnt(8)
	s_waitcnt lgkmcnt(0)
	s_barrier
	s_setprio 1
	s_waitcnt lgkmcnt(0)
	v_mfma_f32_16x16x32_bf16 v[60:63], v[142:145], v[182:185], v[60:63]
	v_mfma_f32_16x16x32_bf16 v[56:59], v[150:153], v[182:185], v[56:59]
	v_mfma_f32_16x16x32_bf16 v[40:43], v[150:153], v[190:193], v[40:43]
	v_mfma_f32_16x16x32_bf16 v[44:47], v[142:145], v[190:193], v[44:47]
	v_mfma_f32_16x16x32_bf16 v[28:31], v[142:145], v[198:201], v[28:31]
	v_mfma_f32_16x16x32_bf16 v[24:27], v[150:153], v[198:201], v[24:27]
	v_mfma_f32_16x16x32_bf16 v[8:11], v[150:153], v[206:209], v[8:11]
	v_mfma_f32_16x16x32_bf16 v[12:15], v[142:145], v[206:209], v[12:15]
	v_mfma_f32_16x16x32_bf16 v[60:63], v[146:149], v[186:189], v[60:63]
	v_mfma_f32_16x16x32_bf16 v[56:59], v[154:157], v[186:189], v[56:59]
	v_mfma_f32_16x16x32_bf16 v[40:43], v[154:157], v[194:197], v[40:43]
	v_mfma_f32_16x16x32_bf16 v[44:47], v[146:149], v[194:197], v[44:47]
	v_mfma_f32_16x16x32_bf16 v[28:31], v[146:149], v[202:205], v[28:31]
	v_mfma_f32_16x16x32_bf16 v[24:27], v[154:157], v[202:205], v[24:27]
	v_mfma_f32_16x16x32_bf16 v[8:11], v[154:157], v[210:213], v[8:11]
	v_mfma_f32_16x16x32_bf16 v[12:15], v[146:149], v[210:213], v[12:15]
	s_setprio 0
	s_setprio 1
	v_mfma_f32_16x16x32_bf16 v[52:55], v[158:161], v[182:185], v[52:55]
	v_mfma_f32_16x16x32_bf16 v[48:51], v[166:169], v[182:185], v[48:51]
	v_mfma_f32_16x16x32_bf16 v[36:39], v[158:161], v[190:193], v[36:39]
	v_mfma_f32_16x16x32_bf16 v[32:35], v[166:169], v[190:193], v[32:35]
	v_mfma_f32_16x16x32_bf16 v[20:23], v[158:161], v[198:201], v[20:23]
	v_mfma_f32_16x16x32_bf16 v[16:19], v[166:169], v[198:201], v[16:19]
	v_mfma_f32_16x16x32_bf16 v[4:7], v[158:161], v[206:209], v[4:7]
	v_mfma_f32_16x16x32_bf16 v[0:3], v[166:169], v[206:209], v[0:3]
	v_mfma_f32_16x16x32_bf16 v[52:55], v[162:165], v[186:189], v[52:55]
	v_mfma_f32_16x16x32_bf16 v[48:51], v[170:173], v[186:189], v[48:51]
	s_add_u32 s64, s64, 0x100
	v_mfma_f32_16x16x32_bf16 v[36:39], v[162:165], v[194:197], v[36:39]
	s_addc_u32 s65, s65, 0
	v_mfma_f32_16x16x32_bf16 v[32:35], v[170:173], v[194:197], v[32:35]
	s_add_u32 s66, s66, 0x100
	v_mfma_f32_16x16x32_bf16 v[20:23], v[162:165], v[202:205], v[20:23]
	s_addc_u32 s67, s67, 0
	v_mfma_f32_16x16x32_bf16 v[16:19], v[170:173], v[202:205], v[16:19]
	s_cmp_ge_i32 s83, s63
	v_mfma_f32_16x16x32_bf16 v[4:7], v[162:165], v[210:213], v[4:7]
	s_mov_b32 s4, s83
	v_mfma_f32_16x16x32_bf16 v[0:3], v[170:173], v[210:213], v[0:3]
	s_setprio 0
	s_barrier
	s_cbranch_scc0 .LBB0_812
